# gdn_prep packed forward substitution with two row-pairs interleaved (two independent v_pk_fma_f32 chains instead of one)
# baseline (speedup 1.0000x reference)
.LBB0_514:
	s_or_b64 exec, exec, s[56:57]
	v_cmp_gt_i32_e32 vcc, s75, v102
	v_and_b32_e32 v31, 0x7f, v102
	v_add_u32_e32 v32, 0xf400, v143
	v_cndmask_b32_e32 v30, v163, v168, vcc
	v_lshl_add_u32 v30, v31, 1, v30
	v_cndmask_b32_e32 v31, v167, v164, vcc
	ds_read_u16 v26, v30 offset:0
	ds_read_u16 v27, v30 offset:272
	ds_read_b64 v[28:29], v31 offset:0
	ds_read_u16 v36, v30 offset:544
	ds_read_u16 v37, v30 offset:816
	ds_read_b64 v[38:39], v31 offset:8
	ds_read_b128 v[2:5], v32 offset:0
	ds_read_b128 v[6:9], v32 offset:544
	ds_read_b128 v[10:13], v32 offset:560
	ds_read_u16 v152, v30 offset:1088
	ds_read_u16 v153, v30 offset:1360
	ds_read_b64 v[154:155], v31 offset:16
	ds_read_u16 v156, v30 offset:1632
	ds_read_u16 v157, v30 offset:1904
	ds_read_b64 v[158:159], v31 offset:24
	ds_read_b128 v[120:123], v32 offset:1088
	ds_read_b128 v[124:127], v32 offset:1632
	ds_read_b128 v[128:131], v32 offset:1104
	ds_read_b128 v[132:135], v32 offset:1648
	ds_read_b128 v[144:147], v32 offset:1120
	ds_read_b128 v[148:151], v32 offset:1664
	s_waitcnt lgkmcnt(12)
	v_lshlrev_b32_e32 v26, 16, v26
	v_lshlrev_b32_e32 v27, 16, v27
	v_pk_mul_f32 v[46:47], v[26:27], v[28:29]
	v_lshlrev_b32_e32 v36, 16, v36
	v_lshlrev_b32_e32 v37, 16, v37
	v_pk_mul_f32 v[48:49], v[36:37], v[38:39]
	v_fma_f32 v47, -v3, v46, v47
	v_pk_fma_f32 v[48:49], v[6:7], v[46:47], v[48:49] op_sel_hi:[1,0,1] neg_lo:[1,0,0] neg_hi:[1,0,0]
	v_pk_fma_f32 v[48:49], v[8:9], v[46:47], v[48:49] op_sel:[0,1,0] op_sel_hi:[1,1,1] neg_lo:[1,0,0] neg_hi:[1,0,0]
	v_fma_f32 v49, -v11, v48, v49
	ds_read_b128 v[2:5], v32 offset:1680
	s_waitcnt lgkmcnt(1)
	v_lshlrev_b32_e32 v152, 16, v152
	v_lshlrev_b32_e32 v153, 16, v153
	v_pk_mul_f32 v[50:51], v[152:153], v[154:155]
	v_lshlrev_b32_e32 v156, 16, v156
	v_lshlrev_b32_e32 v157, 16, v157
	v_pk_mul_f32 v[52:53], v[156:157], v[158:159]
	v_pk_fma_f32 v[50:51], v[120:121], v[46:47], v[50:51] op_sel_hi:[1,0,1] neg_lo:[1,0,0] neg_hi:[1,0,0]
	v_pk_fma_f32 v[50:51], v[122:123], v[46:47], v[50:51] op_sel:[0,1,0] op_sel_hi:[1,1,1] neg_lo:[1,0,0] neg_hi:[1,0,0]
	v_pk_fma_f32 v[52:53], v[124:125], v[46:47], v[52:53] op_sel_hi:[1,0,1] neg_lo:[1,0,0] neg_hi:[1,0,0]
	v_pk_fma_f32 v[52:53], v[126:127], v[46:47], v[52:53] op_sel:[0,1,0] op_sel_hi:[1,1,1] neg_lo:[1,0,0] neg_hi:[1,0,0]
	v_pk_fma_f32 v[50:51], v[128:129], v[48:49], v[50:51] op_sel_hi:[1,0,1] neg_lo:[1,0,0] neg_hi:[1,0,0]
	v_pk_fma_f32 v[50:51], v[130:131], v[48:49], v[50:51] op_sel:[0,1,0] op_sel_hi:[1,1,1] neg_lo:[1,0,0] neg_hi:[1,0,0]
	v_pk_fma_f32 v[52:53], v[132:133], v[48:49], v[52:53] op_sel_hi:[1,0,1] neg_lo:[1,0,0] neg_hi:[1,0,0]
	v_pk_fma_f32 v[52:53], v[134:135], v[48:49], v[52:53] op_sel:[0,1,0] op_sel_hi:[1,1,1] neg_lo:[1,0,0] neg_hi:[1,0,0]
	v_fma_f32 v51, -v145, v50, v51
	v_pk_fma_f32 v[52:53], v[148:149], v[50:51], v[52:53] op_sel_hi:[1,0,1] neg_lo:[1,0,0] neg_hi:[1,0,0]
	v_pk_fma_f32 v[52:53], v[150:151], v[50:51], v[52:53] op_sel:[0,1,0] op_sel_hi:[1,1,1] neg_lo:[1,0,0] neg_hi:[1,0,0]
	ds_read_u16 v152, v30 offset:2176
	ds_read_u16 v153, v30 offset:2448
	ds_read_b64 v[154:155], v31 offset:32
	ds_read_u16 v156, v30 offset:2720
	ds_read_u16 v157, v30 offset:2992
	ds_read_b64 v[158:159], v31 offset:40
	ds_read_b128 v[120:123], v32 offset:2176
	ds_read_b128 v[124:127], v32 offset:2720
	ds_read_b128 v[128:131], v32 offset:2192
	ds_read_b128 v[132:135], v32 offset:2736
	ds_read_b128 v[144:147], v32 offset:2208
	ds_read_b128 v[148:151], v32 offset:2752
	s_waitcnt lgkmcnt(12)
	v_fma_f32 v53, -v3, v52, v53
	ds_read_b128 v[2:5], v32 offset:2224
	ds_read_b128 v[6:9], v32 offset:2768
	ds_read_b128 v[10:13], v32 offset:2240
	ds_read_b128 v[14:17], v32 offset:2784
	ds_read_b128 v[18:21], v32 offset:2800
	s_waitcnt lgkmcnt(5)
	v_lshlrev_b32_e32 v152, 16, v152
	v_lshlrev_b32_e32 v153, 16, v153
	v_pk_mul_f32 v[54:55], v[152:153], v[154:155]
	v_lshlrev_b32_e32 v156, 16, v156
	v_lshlrev_b32_e32 v157, 16, v157
	v_pk_mul_f32 v[56:57], v[156:157], v[158:159]
	v_pk_fma_f32 v[54:55], v[120:121], v[46:47], v[54:55] op_sel_hi:[1,0,1] neg_lo:[1,0,0] neg_hi:[1,0,0]
	v_pk_fma_f32 v[54:55], v[122:123], v[46:47], v[54:55] op_sel:[0,1,0] op_sel_hi:[1,1,1] neg_lo:[1,0,0] neg_hi:[1,0,0]
	v_pk_fma_f32 v[56:57], v[124:125], v[46:47], v[56:57] op_sel_hi:[1,0,1] neg_lo:[1,0,0] neg_hi:[1,0,0]
	v_pk_fma_f32 v[56:57], v[126:127], v[46:47], v[56:57] op_sel:[0,1,0] op_sel_hi:[1,1,1] neg_lo:[1,0,0] neg_hi:[1,0,0]
	v_pk_fma_f32 v[54:55], v[128:129], v[48:49], v[54:55] op_sel_hi:[1,0,1] neg_lo:[1,0,0] neg_hi:[1,0,0]
	v_pk_fma_f32 v[54:55], v[130:131], v[48:49], v[54:55] op_sel:[0,1,0] op_sel_hi:[1,1,1] neg_lo:[1,0,0] neg_hi:[1,0,0]
	v_pk_fma_f32 v[56:57], v[132:133], v[48:49], v[56:57] op_sel_hi:[1,0,1] neg_lo:[1,0,0] neg_hi:[1,0,0]
	v_pk_fma_f32 v[56:57], v[134:135], v[48:49], v[56:57] op_sel:[0,1,0] op_sel_hi:[1,1,1] neg_lo:[1,0,0] neg_hi:[1,0,0]
	v_pk_fma_f32 v[54:55], v[144:145], v[50:51], v[54:55] op_sel_hi:[1,0,1] neg_lo:[1,0,0] neg_hi:[1,0,0]
	v_pk_fma_f32 v[54:55], v[146:147], v[50:51], v[54:55] op_sel:[0,1,0] op_sel_hi:[1,1,1] neg_lo:[1,0,0] neg_hi:[1,0,0]
	v_pk_fma_f32 v[56:57], v[148:149], v[50:51], v[56:57] op_sel_hi:[1,0,1] neg_lo:[1,0,0] neg_hi:[1,0,0]
	v_pk_fma_f32 v[56:57], v[150:151], v[50:51], v[56:57] op_sel:[0,1,0] op_sel_hi:[1,1,1] neg_lo:[1,0,0] neg_hi:[1,0,0]
	ds_read_u16 v152, v30 offset:3264
	ds_read_u16 v153, v30 offset:3536
	ds_read_b64 v[154:155], v31 offset:48
	ds_read_u16 v156, v30 offset:3808
	ds_read_u16 v157, v30 offset:4080
	ds_read_b64 v[158:159], v31 offset:56
	ds_read_b128 v[120:123], v32 offset:3264
	ds_read_b128 v[124:127], v32 offset:3808
	ds_read_b128 v[128:131], v32 offset:3280
	ds_read_b128 v[132:135], v32 offset:3824
	ds_read_b128 v[144:147], v32 offset:3296
	ds_read_b128 v[148:151], v32 offset:3840
	s_waitcnt lgkmcnt(12)
	v_pk_fma_f32 v[54:55], v[2:3], v[52:53], v[54:55] op_sel_hi:[1,0,1] neg_lo:[1,0,0] neg_hi:[1,0,0]
	v_pk_fma_f32 v[54:55], v[4:5], v[52:53], v[54:55] op_sel:[0,1,0] op_sel_hi:[1,1,1] neg_lo:[1,0,0] neg_hi:[1,0,0]
	v_pk_fma_f32 v[56:57], v[6:7], v[52:53], v[56:57] op_sel_hi:[1,0,1] neg_lo:[1,0,0] neg_hi:[1,0,0]
	v_pk_fma_f32 v[56:57], v[8:9], v[52:53], v[56:57] op_sel:[0,1,0] op_sel_hi:[1,1,1] neg_lo:[1,0,0] neg_hi:[1,0,0]
	v_fma_f32 v55, -v11, v54, v55
	v_pk_fma_f32 v[56:57], v[14:15], v[54:55], v[56:57] op_sel_hi:[1,0,1] neg_lo:[1,0,0] neg_hi:[1,0,0]
	v_pk_fma_f32 v[56:57], v[16:17], v[54:55], v[56:57] op_sel:[0,1,0] op_sel_hi:[1,1,1] neg_lo:[1,0,0] neg_hi:[1,0,0]
	v_fma_f32 v57, -v19, v56, v57
	ds_read_b128 v[2:5], v32 offset:3312
	ds_read_b128 v[6:9], v32 offset:3856
	ds_read_b128 v[10:13], v32 offset:3328
	ds_read_b128 v[14:17], v32 offset:3872
	ds_read_b128 v[18:21], v32 offset:3344
	ds_read_b128 v[22:25], v32 offset:3888
	s_waitcnt lgkmcnt(6)
	v_lshlrev_b32_e32 v152, 16, v152
	v_lshlrev_b32_e32 v153, 16, v153
	v_pk_mul_f32 v[58:59], v[152:153], v[154:155]
	v_lshlrev_b32_e32 v156, 16, v156
	v_lshlrev_b32_e32 v157, 16, v157
	v_pk_mul_f32 v[60:61], v[156:157], v[158:159]
	v_pk_fma_f32 v[58:59], v[120:121], v[46:47], v[58:59] op_sel_hi:[1,0,1] neg_lo:[1,0,0] neg_hi:[1,0,0]
	v_pk_fma_f32 v[58:59], v[122:123], v[46:47], v[58:59] op_sel:[0,1,0] op_sel_hi:[1,1,1] neg_lo:[1,0,0] neg_hi:[1,0,0]
	v_pk_fma_f32 v[60:61], v[124:125], v[46:47], v[60:61] op_sel_hi:[1,0,1] neg_lo:[1,0,0] neg_hi:[1,0,0]
	v_pk_fma_f32 v[60:61], v[126:127], v[46:47], v[60:61] op_sel:[0,1,0] op_sel_hi:[1,1,1] neg_lo:[1,0,0] neg_hi:[1,0,0]
	v_pk_fma_f32 v[58:59], v[128:129], v[48:49], v[58:59] op_sel_hi:[1,0,1] neg_lo:[1,0,0] neg_hi:[1,0,0]
	v_pk_fma_f32 v[58:59], v[130:131], v[48:49], v[58:59] op_sel:[0,1,0] op_sel_hi:[1,1,1] neg_lo:[1,0,0] neg_hi:[1,0,0]
	v_pk_fma_f32 v[60:61], v[132:133], v[48:49], v[60:61] op_sel_hi:[1,0,1] neg_lo:[1,0,0] neg_hi:[1,0,0]
	v_pk_fma_f32 v[60:61], v[134:135], v[48:49], v[60:61] op_sel:[0,1,0] op_sel_hi:[1,1,1] neg_lo:[1,0,0] neg_hi:[1,0,0]
	v_pk_fma_f32 v[58:59], v[144:145], v[50:51], v[58:59] op_sel_hi:[1,0,1] neg_lo:[1,0,0] neg_hi:[1,0,0]
	v_pk_fma_f32 v[58:59], v[146:147], v[50:51], v[58:59] op_sel:[0,1,0] op_sel_hi:[1,1,1] neg_lo:[1,0,0] neg_hi:[1,0,0]
	v_pk_fma_f32 v[60:61], v[148:149], v[50:51], v[60:61] op_sel_hi:[1,0,1] neg_lo:[1,0,0] neg_hi:[1,0,0]
	v_pk_fma_f32 v[60:61], v[150:151], v[50:51], v[60:61] op_sel:[0,1,0] op_sel_hi:[1,1,1] neg_lo:[1,0,0] neg_hi:[1,0,0]
	ds_read_b128 v[120:123], v32 offset:3360
	ds_read_b128 v[124:127], v32 offset:3904
	ds_read_b128 v[128:131], v32 offset:3920
	s_waitcnt lgkmcnt(3)
	v_pk_fma_f32 v[58:59], v[2:3], v[52:53], v[58:59] op_sel_hi:[1,0,1] neg_lo:[1,0,0] neg_hi:[1,0,0]
	v_pk_fma_f32 v[58:59], v[4:5], v[52:53], v[58:59] op_sel:[0,1,0] op_sel_hi:[1,1,1] neg_lo:[1,0,0] neg_hi:[1,0,0]
	v_pk_fma_f32 v[60:61], v[6:7], v[52:53], v[60:61] op_sel_hi:[1,0,1] neg_lo:[1,0,0] neg_hi:[1,0,0]
	v_pk_fma_f32 v[60:61], v[8:9], v[52:53], v[60:61] op_sel:[0,1,0] op_sel_hi:[1,1,1] neg_lo:[1,0,0] neg_hi:[1,0,0]
	v_pk_fma_f32 v[58:59], v[10:11], v[54:55], v[58:59] op_sel_hi:[1,0,1] neg_lo:[1,0,0] neg_hi:[1,0,0]
	v_pk_fma_f32 v[58:59], v[12:13], v[54:55], v[58:59] op_sel:[0,1,0] op_sel_hi:[1,1,1] neg_lo:[1,0,0] neg_hi:[1,0,0]
	v_pk_fma_f32 v[60:61], v[14:15], v[54:55], v[60:61] op_sel_hi:[1,0,1] neg_lo:[1,0,0] neg_hi:[1,0,0]
	v_pk_fma_f32 v[60:61], v[16:17], v[54:55], v[60:61] op_sel:[0,1,0] op_sel_hi:[1,1,1] neg_lo:[1,0,0] neg_hi:[1,0,0]
	v_pk_fma_f32 v[58:59], v[18:19], v[56:57], v[58:59] op_sel_hi:[1,0,1] neg_lo:[1,0,0] neg_hi:[1,0,0]
	v_pk_fma_f32 v[58:59], v[20:21], v[56:57], v[58:59] op_sel:[0,1,0] op_sel_hi:[1,1,1] neg_lo:[1,0,0] neg_hi:[1,0,0]
	v_pk_fma_f32 v[60:61], v[22:23], v[56:57], v[60:61] op_sel_hi:[1,0,1] neg_lo:[1,0,0] neg_hi:[1,0,0]
	v_pk_fma_f32 v[60:61], v[24:25], v[56:57], v[60:61] op_sel:[0,1,0] op_sel_hi:[1,1,1] neg_lo:[1,0,0] neg_hi:[1,0,0]
	ds_read_u16 v26, v30 offset:4352
	ds_read_u16 v27, v30 offset:4624
	ds_read_b64 v[28:29], v31 offset:64
	ds_read_u16 v36, v30 offset:4896
	ds_read_u16 v37, v30 offset:5168
	ds_read_b64 v[38:39], v31 offset:72
	ds_read_b128 v[2:5], v32 offset:4352
	ds_read_b128 v[6:9], v32 offset:4896
	ds_read_b128 v[10:13], v32 offset:4368
	ds_read_b128 v[14:17], v32 offset:4912
	ds_read_b128 v[18:21], v32 offset:4384
	ds_read_b128 v[22:25], v32 offset:4928
	s_waitcnt lgkmcnt(12)
	v_fma_f32 v59, -v121, v58, v59
	v_pk_fma_f32 v[60:61], v[124:125], v[58:59], v[60:61] op_sel_hi:[1,0,1] neg_lo:[1,0,0] neg_hi:[1,0,0]
	v_pk_fma_f32 v[60:61], v[126:127], v[58:59], v[60:61] op_sel:[0,1,0] op_sel_hi:[1,1,1] neg_lo:[1,0,0] neg_hi:[1,0,0]
	v_fma_f32 v61, -v129, v60, v61
	ds_read_b128 v[120:123], v32 offset:4400
	ds_read_b128 v[124:127], v32 offset:4944
	ds_read_b128 v[128:131], v32 offset:4416
	ds_read_b128 v[132:135], v32 offset:4960
	ds_read_b128 v[144:147], v32 offset:4432
	ds_read_b128 v[148:151], v32 offset:4976
	s_waitcnt lgkmcnt(6)
	v_lshlrev_b32_e32 v26, 16, v26
	v_lshlrev_b32_e32 v27, 16, v27
	v_pk_mul_f32 v[62:63], v[26:27], v[28:29]
	v_lshlrev_b32_e32 v36, 16, v36
	v_lshlrev_b32_e32 v37, 16, v37
	v_pk_mul_f32 v[64:65], v[36:37], v[38:39]
	v_pk_fma_f32 v[62:63], v[2:3], v[46:47], v[62:63] op_sel_hi:[1,0,1] neg_lo:[1,0,0] neg_hi:[1,0,0]
	v_pk_fma_f32 v[62:63], v[4:5], v[46:47], v[62:63] op_sel:[0,1,0] op_sel_hi:[1,1,1] neg_lo:[1,0,0] neg_hi:[1,0,0]
	v_pk_fma_f32 v[64:65], v[6:7], v[46:47], v[64:65] op_sel_hi:[1,0,1] neg_lo:[1,0,0] neg_hi:[1,0,0]
	v_pk_fma_f32 v[64:65], v[8:9], v[46:47], v[64:65] op_sel:[0,1,0] op_sel_hi:[1,1,1] neg_lo:[1,0,0] neg_hi:[1,0,0]
	v_pk_fma_f32 v[62:63], v[10:11], v[48:49], v[62:63] op_sel_hi:[1,0,1] neg_lo:[1,0,0] neg_hi:[1,0,0]
	v_pk_fma_f32 v[62:63], v[12:13], v[48:49], v[62:63] op_sel:[0,1,0] op_sel_hi:[1,1,1] neg_lo:[1,0,0] neg_hi:[1,0,0]
	v_pk_fma_f32 v[64:65], v[14:15], v[48:49], v[64:65] op_sel_hi:[1,0,1] neg_lo:[1,0,0] neg_hi:[1,0,0]
	v_pk_fma_f32 v[64:65], v[16:17], v[48:49], v[64:65] op_sel:[0,1,0] op_sel_hi:[1,1,1] neg_lo:[1,0,0] neg_hi:[1,0,0]
	v_pk_fma_f32 v[62:63], v[18:19], v[50:51], v[62:63] op_sel_hi:[1,0,1] neg_lo:[1,0,0] neg_hi:[1,0,0]
	v_pk_fma_f32 v[62:63], v[20:21], v[50:51], v[62:63] op_sel:[0,1,0] op_sel_hi:[1,1,1] neg_lo:[1,0,0] neg_hi:[1,0,0]
	v_pk_fma_f32 v[64:65], v[22:23], v[50:51], v[64:65] op_sel_hi:[1,0,1] neg_lo:[1,0,0] neg_hi:[1,0,0]
	v_pk_fma_f32 v[64:65], v[24:25], v[50:51], v[64:65] op_sel:[0,1,0] op_sel_hi:[1,1,1] neg_lo:[1,0,0] neg_hi:[1,0,0]
	ds_read_b128 v[2:5], v32 offset:4448
	ds_read_b128 v[6:9], v32 offset:4992
	ds_read_b128 v[10:13], v32 offset:4464
	ds_read_b128 v[14:17], v32 offset:5008
	ds_read_b128 v[18:21], v32 offset:4480
	ds_read_b128 v[22:25], v32 offset:5024
	s_waitcnt lgkmcnt(6)
	v_pk_fma_f32 v[62:63], v[120:121], v[52:53], v[62:63] op_sel_hi:[1,0,1] neg_lo:[1,0,0] neg_hi:[1,0,0]
	v_pk_fma_f32 v[62:63], v[122:123], v[52:53], v[62:63] op_sel:[0,1,0] op_sel_hi:[1,1,1] neg_lo:[1,0,0] neg_hi:[1,0,0]
	v_pk_fma_f32 v[64:65], v[124:125], v[52:53], v[64:65] op_sel_hi:[1,0,1] neg_lo:[1,0,0] neg_hi:[1,0,0]
	v_pk_fma_f32 v[64:65], v[126:127], v[52:53], v[64:65] op_sel:[0,1,0] op_sel_hi:[1,1,1] neg_lo:[1,0,0] neg_hi:[1,0,0]
	v_pk_fma_f32 v[62:63], v[128:129], v[54:55], v[62:63] op_sel_hi:[1,0,1] neg_lo:[1,0,0] neg_hi:[1,0,0]
	v_pk_fma_f32 v[62:63], v[130:131], v[54:55], v[62:63] op_sel:[0,1,0] op_sel_hi:[1,1,1] neg_lo:[1,0,0] neg_hi:[1,0,0]
	v_pk_fma_f32 v[64:65], v[132:133], v[54:55], v[64:65] op_sel_hi:[1,0,1] neg_lo:[1,0,0] neg_hi:[1,0,0]
	v_pk_fma_f32 v[64:65], v[134:135], v[54:55], v[64:65] op_sel:[0,1,0] op_sel_hi:[1,1,1] neg_lo:[1,0,0] neg_hi:[1,0,0]
	v_pk_fma_f32 v[62:63], v[144:145], v[56:57], v[62:63] op_sel_hi:[1,0,1] neg_lo:[1,0,0] neg_hi:[1,0,0]
	v_pk_fma_f32 v[62:63], v[146:147], v[56:57], v[62:63] op_sel:[0,1,0] op_sel_hi:[1,1,1] neg_lo:[1,0,0] neg_hi:[1,0,0]
	v_pk_fma_f32 v[64:65], v[148:149], v[56:57], v[64:65] op_sel_hi:[1,0,1] neg_lo:[1,0,0] neg_hi:[1,0,0]
	v_pk_fma_f32 v[64:65], v[150:151], v[56:57], v[64:65] op_sel:[0,1,0] op_sel_hi:[1,1,1] neg_lo:[1,0,0] neg_hi:[1,0,0]
	ds_read_b128 v[120:123], v32 offset:5040
	s_waitcnt lgkmcnt(1)
	v_pk_fma_f32 v[62:63], v[2:3], v[58:59], v[62:63] op_sel_hi:[1,0,1] neg_lo:[1,0,0] neg_hi:[1,0,0]
	v_pk_fma_f32 v[62:63], v[4:5], v[58:59], v[62:63] op_sel:[0,1,0] op_sel_hi:[1,1,1] neg_lo:[1,0,0] neg_hi:[1,0,0]
	v_pk_fma_f32 v[64:65], v[6:7], v[58:59], v[64:65] op_sel_hi:[1,0,1] neg_lo:[1,0,0] neg_hi:[1,0,0]
	v_pk_fma_f32 v[64:65], v[8:9], v[58:59], v[64:65] op_sel:[0,1,0] op_sel_hi:[1,1,1] neg_lo:[1,0,0] neg_hi:[1,0,0]
	v_pk_fma_f32 v[62:63], v[10:11], v[60:61], v[62:63] op_sel_hi:[1,0,1] neg_lo:[1,0,0] neg_hi:[1,0,0]
	v_pk_fma_f32 v[62:63], v[12:13], v[60:61], v[62:63] op_sel:[0,1,0] op_sel_hi:[1,1,1] neg_lo:[1,0,0] neg_hi:[1,0,0]
	v_pk_fma_f32 v[64:65], v[14:15], v[60:61], v[64:65] op_sel_hi:[1,0,1] neg_lo:[1,0,0] neg_hi:[1,0,0]
	v_pk_fma_f32 v[64:65], v[16:17], v[60:61], v[64:65] op_sel:[0,1,0] op_sel_hi:[1,1,1] neg_lo:[1,0,0] neg_hi:[1,0,0]
	v_fma_f32 v63, -v19, v62, v63
	v_pk_fma_f32 v[64:65], v[22:23], v[62:63], v[64:65] op_sel_hi:[1,0,1] neg_lo:[1,0,0] neg_hi:[1,0,0]
	v_pk_fma_f32 v[64:65], v[24:25], v[62:63], v[64:65] op_sel:[0,1,0] op_sel_hi:[1,1,1] neg_lo:[1,0,0] neg_hi:[1,0,0]
	ds_read_u16 v26, v30 offset:5440
	ds_read_u16 v27, v30 offset:5712
	ds_read_b64 v[28:29], v31 offset:80
	ds_read_u16 v36, v30 offset:5984
	ds_read_u16 v37, v30 offset:6256
	ds_read_b64 v[38:39], v31 offset:88
	ds_read_b128 v[2:5], v32 offset:5440
	ds_read_b128 v[6:9], v32 offset:5984
	ds_read_b128 v[10:13], v32 offset:5456
	ds_read_b128 v[14:17], v32 offset:6000
	ds_read_b128 v[18:21], v32 offset:5472
	ds_read_b128 v[22:25], v32 offset:6016
	s_waitcnt lgkmcnt(12)
	v_fma_f32 v65, -v121, v64, v65
	ds_read_b128 v[120:123], v32 offset:5488
	ds_read_b128 v[124:127], v32 offset:6032
	ds_read_b128 v[128:131], v32 offset:5504
	ds_read_b128 v[132:135], v32 offset:6048
	ds_read_b128 v[144:147], v32 offset:5520
	ds_read_b128 v[148:151], v32 offset:6064
	s_waitcnt lgkmcnt(6)
	v_lshlrev_b32_e32 v26, 16, v26
	v_lshlrev_b32_e32 v27, 16, v27
	v_pk_mul_f32 v[66:67], v[26:27], v[28:29]
	v_lshlrev_b32_e32 v36, 16, v36
	v_lshlrev_b32_e32 v37, 16, v37
	v_pk_mul_f32 v[68:69], v[36:37], v[38:39]
	v_pk_fma_f32 v[66:67], v[2:3], v[46:47], v[66:67] op_sel_hi:[1,0,1] neg_lo:[1,0,0] neg_hi:[1,0,0]
	v_pk_fma_f32 v[66:67], v[4:5], v[46:47], v[66:67] op_sel:[0,1,0] op_sel_hi:[1,1,1] neg_lo:[1,0,0] neg_hi:[1,0,0]
	v_pk_fma_f32 v[68:69], v[6:7], v[46:47], v[68:69] op_sel_hi:[1,0,1] neg_lo:[1,0,0] neg_hi:[1,0,0]
	v_pk_fma_f32 v[68:69], v[8:9], v[46:47], v[68:69] op_sel:[0,1,0] op_sel_hi:[1,1,1] neg_lo:[1,0,0] neg_hi:[1,0,0]
	v_pk_fma_f32 v[66:67], v[10:11], v[48:49], v[66:67] op_sel_hi:[1,0,1] neg_lo:[1,0,0] neg_hi:[1,0,0]
	v_pk_fma_f32 v[66:67], v[12:13], v[48:49], v[66:67] op_sel:[0,1,0] op_sel_hi:[1,1,1] neg_lo:[1,0,0] neg_hi:[1,0,0]
	v_pk_fma_f32 v[68:69], v[14:15], v[48:49], v[68:69] op_sel_hi:[1,0,1] neg_lo:[1,0,0] neg_hi:[1,0,0]
	v_pk_fma_f32 v[68:69], v[16:17], v[48:49], v[68:69] op_sel:[0,1,0] op_sel_hi:[1,1,1] neg_lo:[1,0,0] neg_hi:[1,0,0]
	v_pk_fma_f32 v[66:67], v[18:19], v[50:51], v[66:67] op_sel_hi:[1,0,1] neg_lo:[1,0,0] neg_hi:[1,0,0]
	v_pk_fma_f32 v[66:67], v[20:21], v[50:51], v[66:67] op_sel:[0,1,0] op_sel_hi:[1,1,1] neg_lo:[1,0,0] neg_hi:[1,0,0]
	v_pk_fma_f32 v[68:69], v[22:23], v[50:51], v[68:69] op_sel_hi:[1,0,1] neg_lo:[1,0,0] neg_hi:[1,0,0]
	v_pk_fma_f32 v[68:69], v[24:25], v[50:51], v[68:69] op_sel:[0,1,0] op_sel_hi:[1,1,1] neg_lo:[1,0,0] neg_hi:[1,0,0]
	ds_read_b128 v[2:5], v32 offset:5536
	ds_read_b128 v[6:9], v32 offset:6080
	ds_read_b128 v[10:13], v32 offset:5552
	ds_read_b128 v[14:17], v32 offset:6096
	ds_read_b128 v[18:21], v32 offset:5568
	ds_read_b128 v[22:25], v32 offset:6112
	s_waitcnt lgkmcnt(6)
	v_pk_fma_f32 v[66:67], v[120:121], v[52:53], v[66:67] op_sel_hi:[1,0,1] neg_lo:[1,0,0] neg_hi:[1,0,0]
	v_pk_fma_f32 v[66:67], v[122:123], v[52:53], v[66:67] op_sel:[0,1,0] op_sel_hi:[1,1,1] neg_lo:[1,0,0] neg_hi:[1,0,0]
	v_pk_fma_f32 v[68:69], v[124:125], v[52:53], v[68:69] op_sel_hi:[1,0,1] neg_lo:[1,0,0] neg_hi:[1,0,0]
	v_pk_fma_f32 v[68:69], v[126:127], v[52:53], v[68:69] op_sel:[0,1,0] op_sel_hi:[1,1,1] neg_lo:[1,0,0] neg_hi:[1,0,0]
	v_pk_fma_f32 v[66:67], v[128:129], v[54:55], v[66:67] op_sel_hi:[1,0,1] neg_lo:[1,0,0] neg_hi:[1,0,0]
	v_pk_fma_f32 v[66:67], v[130:131], v[54:55], v[66:67] op_sel:[0,1,0] op_sel_hi:[1,1,1] neg_lo:[1,0,0] neg_hi:[1,0,0]
	v_pk_fma_f32 v[68:69], v[132:133], v[54:55], v[68:69] op_sel_hi:[1,0,1] neg_lo:[1,0,0] neg_hi:[1,0,0]
	v_pk_fma_f32 v[68:69], v[134:135], v[54:55], v[68:69] op_sel:[0,1,0] op_sel_hi:[1,1,1] neg_lo:[1,0,0] neg_hi:[1,0,0]
	v_pk_fma_f32 v[66:67], v[144:145], v[56:57], v[66:67] op_sel_hi:[1,0,1] neg_lo:[1,0,0] neg_hi:[1,0,0]
	v_pk_fma_f32 v[66:67], v[146:147], v[56:57], v[66:67] op_sel:[0,1,0] op_sel_hi:[1,1,1] neg_lo:[1,0,0] neg_hi:[1,0,0]
	v_pk_fma_f32 v[68:69], v[148:149], v[56:57], v[68:69] op_sel_hi:[1,0,1] neg_lo:[1,0,0] neg_hi:[1,0,0]
	v_pk_fma_f32 v[68:69], v[150:151], v[56:57], v[68:69] op_sel:[0,1,0] op_sel_hi:[1,1,1] neg_lo:[1,0,0] neg_hi:[1,0,0]
	ds_read_b128 v[120:123], v32 offset:5584
	ds_read_b128 v[124:127], v32 offset:6128
	ds_read_b128 v[128:131], v32 offset:5600
	ds_read_b128 v[132:135], v32 offset:6144
	ds_read_b128 v[144:147], v32 offset:6160
	s_waitcnt lgkmcnt(5)
	v_pk_fma_f32 v[66:67], v[2:3], v[58:59], v[66:67] op_sel_hi:[1,0,1] neg_lo:[1,0,0] neg_hi:[1,0,0]
	v_pk_fma_f32 v[66:67], v[4:5], v[58:59], v[66:67] op_sel:[0,1,0] op_sel_hi:[1,1,1] neg_lo:[1,0,0] neg_hi:[1,0,0]
	v_pk_fma_f32 v[68:69], v[6:7], v[58:59], v[68:69] op_sel_hi:[1,0,1] neg_lo:[1,0,0] neg_hi:[1,0,0]
	v_pk_fma_f32 v[68:69], v[8:9], v[58:59], v[68:69] op_sel:[0,1,0] op_sel_hi:[1,1,1] neg_lo:[1,0,0] neg_hi:[1,0,0]
	v_pk_fma_f32 v[66:67], v[10:11], v[60:61], v[66:67] op_sel_hi:[1,0,1] neg_lo:[1,0,0] neg_hi:[1,0,0]
	v_pk_fma_f32 v[66:67], v[12:13], v[60:61], v[66:67] op_sel:[0,1,0] op_sel_hi:[1,1,1] neg_lo:[1,0,0] neg_hi:[1,0,0]
	v_pk_fma_f32 v[68:69], v[14:15], v[60:61], v[68:69] op_sel_hi:[1,0,1] neg_lo:[1,0,0] neg_hi:[1,0,0]
	v_pk_fma_f32 v[68:69], v[16:17], v[60:61], v[68:69] op_sel:[0,1,0] op_sel_hi:[1,1,1] neg_lo:[1,0,0] neg_hi:[1,0,0]
	v_pk_fma_f32 v[66:67], v[18:19], v[62:63], v[66:67] op_sel_hi:[1,0,1] neg_lo:[1,0,0] neg_hi:[1,0,0]
	v_pk_fma_f32 v[66:67], v[20:21], v[62:63], v[66:67] op_sel:[0,1,0] op_sel_hi:[1,1,1] neg_lo:[1,0,0] neg_hi:[1,0,0]
	v_pk_fma_f32 v[68:69], v[22:23], v[62:63], v[68:69] op_sel_hi:[1,0,1] neg_lo:[1,0,0] neg_hi:[1,0,0]
	v_pk_fma_f32 v[68:69], v[24:25], v[62:63], v[68:69] op_sel:[0,1,0] op_sel_hi:[1,1,1] neg_lo:[1,0,0] neg_hi:[1,0,0]
	ds_read_u16 v26, v30 offset:6528
	ds_read_u16 v27, v30 offset:6800
	ds_read_b64 v[28:29], v31 offset:96
	ds_read_u16 v36, v30 offset:7072
	ds_read_u16 v37, v30 offset:7344
	ds_read_b64 v[38:39], v31 offset:104
	ds_read_b128 v[2:5], v32 offset:6528
	ds_read_b128 v[6:9], v32 offset:7072
	ds_read_b128 v[10:13], v32 offset:6544
	ds_read_b128 v[14:17], v32 offset:7088
	ds_read_b128 v[18:21], v32 offset:6560
	ds_read_b128 v[22:25], v32 offset:7104
	s_waitcnt lgkmcnt(12)
	v_pk_fma_f32 v[66:67], v[120:121], v[64:65], v[66:67] op_sel_hi:[1,0,1] neg_lo:[1,0,0] neg_hi:[1,0,0]
	v_pk_fma_f32 v[66:67], v[122:123], v[64:65], v[66:67] op_sel:[0,1,0] op_sel_hi:[1,1,1] neg_lo:[1,0,0] neg_hi:[1,0,0]
	v_pk_fma_f32 v[68:69], v[124:125], v[64:65], v[68:69] op_sel_hi:[1,0,1] neg_lo:[1,0,0] neg_hi:[1,0,0]
	v_pk_fma_f32 v[68:69], v[126:127], v[64:65], v[68:69] op_sel:[0,1,0] op_sel_hi:[1,1,1] neg_lo:[1,0,0] neg_hi:[1,0,0]
	v_fma_f32 v67, -v129, v66, v67
	v_pk_fma_f32 v[68:69], v[132:133], v[66:67], v[68:69] op_sel_hi:[1,0,1] neg_lo:[1,0,0] neg_hi:[1,0,0]
	v_pk_fma_f32 v[68:69], v[134:135], v[66:67], v[68:69] op_sel:[0,1,0] op_sel_hi:[1,1,1] neg_lo:[1,0,0] neg_hi:[1,0,0]
	v_fma_f32 v69, -v145, v68, v69
	ds_read_b128 v[120:123], v32 offset:6576
	ds_read_b128 v[124:127], v32 offset:7120
	ds_read_b128 v[128:131], v32 offset:6592
	ds_read_b128 v[132:135], v32 offset:7136
	ds_read_b128 v[144:147], v32 offset:6608
	ds_read_b128 v[148:151], v32 offset:7152
	s_waitcnt lgkmcnt(6)
	v_lshlrev_b32_e32 v26, 16, v26
	v_lshlrev_b32_e32 v27, 16, v27
	v_pk_mul_f32 v[70:71], v[26:27], v[28:29]
	v_lshlrev_b32_e32 v36, 16, v36
	v_lshlrev_b32_e32 v37, 16, v37
	v_pk_mul_f32 v[72:73], v[36:37], v[38:39]
	v_pk_fma_f32 v[70:71], v[2:3], v[46:47], v[70:71] op_sel_hi:[1,0,1] neg_lo:[1,0,0] neg_hi:[1,0,0]
	v_pk_fma_f32 v[70:71], v[4:5], v[46:47], v[70:71] op_sel:[0,1,0] op_sel_hi:[1,1,1] neg_lo:[1,0,0] neg_hi:[1,0,0]
	v_pk_fma_f32 v[72:73], v[6:7], v[46:47], v[72:73] op_sel_hi:[1,0,1] neg_lo:[1,0,0] neg_hi:[1,0,0]
	v_pk_fma_f32 v[72:73], v[8:9], v[46:47], v[72:73] op_sel:[0,1,0] op_sel_hi:[1,1,1] neg_lo:[1,0,0] neg_hi:[1,0,0]
	v_pk_fma_f32 v[70:71], v[10:11], v[48:49], v[70:71] op_sel_hi:[1,0,1] neg_lo:[1,0,0] neg_hi:[1,0,0]
	v_pk_fma_f32 v[70:71], v[12:13], v[48:49], v[70:71] op_sel:[0,1,0] op_sel_hi:[1,1,1] neg_lo:[1,0,0] neg_hi:[1,0,0]
	v_pk_fma_f32 v[72:73], v[14:15], v[48:49], v[72:73] op_sel_hi:[1,0,1] neg_lo:[1,0,0] neg_hi:[1,0,0]
	v_pk_fma_f32 v[72:73], v[16:17], v[48:49], v[72:73] op_sel:[0,1,0] op_sel_hi:[1,1,1] neg_lo:[1,0,0] neg_hi:[1,0,0]
	v_pk_fma_f32 v[70:71], v[18:19], v[50:51], v[70:71] op_sel_hi:[1,0,1] neg_lo:[1,0,0] neg_hi:[1,0,0]
	v_pk_fma_f32 v[70:71], v[20:21], v[50:51], v[70:71] op_sel:[0,1,0] op_sel_hi:[1,1,1] neg_lo:[1,0,0] neg_hi:[1,0,0]
	v_pk_fma_f32 v[72:73], v[22:23], v[50:51], v[72:73] op_sel_hi:[1,0,1] neg_lo:[1,0,0] neg_hi:[1,0,0]
	v_pk_fma_f32 v[72:73], v[24:25], v[50:51], v[72:73] op_sel:[0,1,0] op_sel_hi:[1,1,1] neg_lo:[1,0,0] neg_hi:[1,0,0]
	ds_read_b128 v[2:5], v32 offset:6624
	ds_read_b128 v[6:9], v32 offset:7168
	ds_read_b128 v[10:13], v32 offset:6640
	ds_read_b128 v[14:17], v32 offset:7184
	ds_read_b128 v[18:21], v32 offset:6656
	ds_read_b128 v[22:25], v32 offset:7200
	s_waitcnt lgkmcnt(6)
	v_pk_fma_f32 v[70:71], v[120:121], v[52:53], v[70:71] op_sel_hi:[1,0,1] neg_lo:[1,0,0] neg_hi:[1,0,0]
	v_pk_fma_f32 v[70:71], v[122:123], v[52:53], v[70:71] op_sel:[0,1,0] op_sel_hi:[1,1,1] neg_lo:[1,0,0] neg_hi:[1,0,0]
	v_pk_fma_f32 v[72:73], v[124:125], v[52:53], v[72:73] op_sel_hi:[1,0,1] neg_lo:[1,0,0] neg_hi:[1,0,0]
	v_pk_fma_f32 v[72:73], v[126:127], v[52:53], v[72:73] op_sel:[0,1,0] op_sel_hi:[1,1,1] neg_lo:[1,0,0] neg_hi:[1,0,0]
	v_pk_fma_f32 v[70:71], v[128:129], v[54:55], v[70:71] op_sel_hi:[1,0,1] neg_lo:[1,0,0] neg_hi:[1,0,0]
	v_pk_fma_f32 v[70:71], v[130:131], v[54:55], v[70:71] op_sel:[0,1,0] op_sel_hi:[1,1,1] neg_lo:[1,0,0] neg_hi:[1,0,0]
	v_pk_fma_f32 v[72:73], v[132:133], v[54:55], v[72:73] op_sel_hi:[1,0,1] neg_lo:[1,0,0] neg_hi:[1,0,0]
	v_pk_fma_f32 v[72:73], v[134:135], v[54:55], v[72:73] op_sel:[0,1,0] op_sel_hi:[1,1,1] neg_lo:[1,0,0] neg_hi:[1,0,0]
	v_pk_fma_f32 v[70:71], v[144:145], v[56:57], v[70:71] op_sel_hi:[1,0,1] neg_lo:[1,0,0] neg_hi:[1,0,0]
	v_pk_fma_f32 v[70:71], v[146:147], v[56:57], v[70:71] op_sel:[0,1,0] op_sel_hi:[1,1,1] neg_lo:[1,0,0] neg_hi:[1,0,0]
	v_pk_fma_f32 v[72:73], v[148:149], v[56:57], v[72:73] op_sel_hi:[1,0,1] neg_lo:[1,0,0] neg_hi:[1,0,0]
	v_pk_fma_f32 v[72:73], v[150:151], v[56:57], v[72:73] op_sel:[0,1,0] op_sel_hi:[1,1,1] neg_lo:[1,0,0] neg_hi:[1,0,0]
	ds_read_b128 v[120:123], v32 offset:6672
	ds_read_b128 v[124:127], v32 offset:7216
	ds_read_b128 v[128:131], v32 offset:6688
	ds_read_b128 v[132:135], v32 offset:7232
	ds_read_b128 v[144:147], v32 offset:6704
	ds_read_b128 v[148:151], v32 offset:7248
	s_waitcnt lgkmcnt(6)
	v_pk_fma_f32 v[70:71], v[2:3], v[58:59], v[70:71] op_sel_hi:[1,0,1] neg_lo:[1,0,0] neg_hi:[1,0,0]
	v_pk_fma_f32 v[70:71], v[4:5], v[58:59], v[70:71] op_sel:[0,1,0] op_sel_hi:[1,1,1] neg_lo:[1,0,0] neg_hi:[1,0,0]
	v_pk_fma_f32 v[72:73], v[6:7], v[58:59], v[72:73] op_sel_hi:[1,0,1] neg_lo:[1,0,0] neg_hi:[1,0,0]
	v_pk_fma_f32 v[72:73], v[8:9], v[58:59], v[72:73] op_sel:[0,1,0] op_sel_hi:[1,1,1] neg_lo:[1,0,0] neg_hi:[1,0,0]
	v_pk_fma_f32 v[70:71], v[10:11], v[60:61], v[70:71] op_sel_hi:[1,0,1] neg_lo:[1,0,0] neg_hi:[1,0,0]
	v_pk_fma_f32 v[70:71], v[12:13], v[60:61], v[70:71] op_sel:[0,1,0] op_sel_hi:[1,1,1] neg_lo:[1,0,0] neg_hi:[1,0,0]
	v_pk_fma_f32 v[72:73], v[14:15], v[60:61], v[72:73] op_sel_hi:[1,0,1] neg_lo:[1,0,0] neg_hi:[1,0,0]
	v_pk_fma_f32 v[72:73], v[16:17], v[60:61], v[72:73] op_sel:[0,1,0] op_sel_hi:[1,1,1] neg_lo:[1,0,0] neg_hi:[1,0,0]
	v_pk_fma_f32 v[70:71], v[18:19], v[62:63], v[70:71] op_sel_hi:[1,0,1] neg_lo:[1,0,0] neg_hi:[1,0,0]
	v_pk_fma_f32 v[70:71], v[20:21], v[62:63], v[70:71] op_sel:[0,1,0] op_sel_hi:[1,1,1] neg_lo:[1,0,0] neg_hi:[1,0,0]
	v_pk_fma_f32 v[72:73], v[22:23], v[62:63], v[72:73] op_sel_hi:[1,0,1] neg_lo:[1,0,0] neg_hi:[1,0,0]
	v_pk_fma_f32 v[72:73], v[24:25], v[62:63], v[72:73] op_sel:[0,1,0] op_sel_hi:[1,1,1] neg_lo:[1,0,0] neg_hi:[1,0,0]
	ds_read_b128 v[2:5], v32 offset:6720
	ds_read_b128 v[6:9], v32 offset:7264
	ds_read_b128 v[10:13], v32 offset:7280
	s_waitcnt lgkmcnt(3)
	v_pk_fma_f32 v[70:71], v[120:121], v[64:65], v[70:71] op_sel_hi:[1,0,1] neg_lo:[1,0,0] neg_hi:[1,0,0]
	v_pk_fma_f32 v[70:71], v[122:123], v[64:65], v[70:71] op_sel:[0,1,0] op_sel_hi:[1,1,1] neg_lo:[1,0,0] neg_hi:[1,0,0]
	v_pk_fma_f32 v[72:73], v[124:125], v[64:65], v[72:73] op_sel_hi:[1,0,1] neg_lo:[1,0,0] neg_hi:[1,0,0]
	v_pk_fma_f32 v[72:73], v[126:127], v[64:65], v[72:73] op_sel:[0,1,0] op_sel_hi:[1,1,1] neg_lo:[1,0,0] neg_hi:[1,0,0]
	v_pk_fma_f32 v[70:71], v[128:129], v[66:67], v[70:71] op_sel_hi:[1,0,1] neg_lo:[1,0,0] neg_hi:[1,0,0]
	v_pk_fma_f32 v[70:71], v[130:131], v[66:67], v[70:71] op_sel:[0,1,0] op_sel_hi:[1,1,1] neg_lo:[1,0,0] neg_hi:[1,0,0]
	v_pk_fma_f32 v[72:73], v[132:133], v[66:67], v[72:73] op_sel_hi:[1,0,1] neg_lo:[1,0,0] neg_hi:[1,0,0]
	v_pk_fma_f32 v[72:73], v[134:135], v[66:67], v[72:73] op_sel:[0,1,0] op_sel_hi:[1,1,1] neg_lo:[1,0,0] neg_hi:[1,0,0]
	v_pk_fma_f32 v[70:71], v[144:145], v[68:69], v[70:71] op_sel_hi:[1,0,1] neg_lo:[1,0,0] neg_hi:[1,0,0]
	v_pk_fma_f32 v[70:71], v[146:147], v[68:69], v[70:71] op_sel:[0,1,0] op_sel_hi:[1,1,1] neg_lo:[1,0,0] neg_hi:[1,0,0]
	v_pk_fma_f32 v[72:73], v[148:149], v[68:69], v[72:73] op_sel_hi:[1,0,1] neg_lo:[1,0,0] neg_hi:[1,0,0]
	v_pk_fma_f32 v[72:73], v[150:151], v[68:69], v[72:73] op_sel:[0,1,0] op_sel_hi:[1,1,1] neg_lo:[1,0,0] neg_hi:[1,0,0]
	ds_read_u16 v152, v30 offset:7616
	ds_read_u16 v153, v30 offset:7888
	ds_read_b64 v[154:155], v31 offset:112
	ds_read_u16 v156, v30 offset:8160
	ds_read_u16 v157, v30 offset:8432
	ds_read_b64 v[158:159], v31 offset:120
	ds_read_b128 v[120:123], v32 offset:7616
	ds_read_b128 v[124:127], v32 offset:8160
	ds_read_b128 v[128:131], v32 offset:7632
	ds_read_b128 v[132:135], v32 offset:8176
	ds_read_b128 v[144:147], v32 offset:7648
	ds_read_b128 v[148:151], v32 offset:8192
	s_waitcnt lgkmcnt(12)
	v_fma_f32 v71, -v3, v70, v71
	v_pk_fma_f32 v[72:73], v[6:7], v[70:71], v[72:73] op_sel_hi:[1,0,1] neg_lo:[1,0,0] neg_hi:[1,0,0]
	v_pk_fma_f32 v[72:73], v[8:9], v[70:71], v[72:73] op_sel:[0,1,0] op_sel_hi:[1,1,1] neg_lo:[1,0,0] neg_hi:[1,0,0]
	v_fma_f32 v73, -v11, v72, v73
	ds_read_b128 v[2:5], v32 offset:7664
	ds_read_b128 v[6:9], v32 offset:8208
	ds_read_b128 v[10:13], v32 offset:7680
	ds_read_b128 v[14:17], v32 offset:8224
	ds_read_b128 v[18:21], v32 offset:7696
	ds_read_b128 v[22:25], v32 offset:8240
	s_waitcnt lgkmcnt(6)
	v_lshlrev_b32_e32 v152, 16, v152
	v_lshlrev_b32_e32 v153, 16, v153
	v_pk_mul_f32 v[74:75], v[152:153], v[154:155]
	v_lshlrev_b32_e32 v156, 16, v156
	v_lshlrev_b32_e32 v157, 16, v157
	v_pk_mul_f32 v[76:77], v[156:157], v[158:159]
	v_pk_fma_f32 v[74:75], v[120:121], v[46:47], v[74:75] op_sel_hi:[1,0,1] neg_lo:[1,0,0] neg_hi:[1,0,0]
	v_pk_fma_f32 v[74:75], v[122:123], v[46:47], v[74:75] op_sel:[0,1,0] op_sel_hi:[1,1,1] neg_lo:[1,0,0] neg_hi:[1,0,0]
	v_pk_fma_f32 v[76:77], v[124:125], v[46:47], v[76:77] op_sel_hi:[1,0,1] neg_lo:[1,0,0] neg_hi:[1,0,0]
	v_pk_fma_f32 v[76:77], v[126:127], v[46:47], v[76:77] op_sel:[0,1,0] op_sel_hi:[1,1,1] neg_lo:[1,0,0] neg_hi:[1,0,0]
	v_pk_fma_f32 v[74:75], v[128:129], v[48:49], v[74:75] op_sel_hi:[1,0,1] neg_lo:[1,0,0] neg_hi:[1,0,0]
	v_pk_fma_f32 v[74:75], v[130:131], v[48:49], v[74:75] op_sel:[0,1,0] op_sel_hi:[1,1,1] neg_lo:[1,0,0] neg_hi:[1,0,0]
	v_pk_fma_f32 v[76:77], v[132:133], v[48:49], v[76:77] op_sel_hi:[1,0,1] neg_lo:[1,0,0] neg_hi:[1,0,0]
	v_pk_fma_f32 v[76:77], v[134:135], v[48:49], v[76:77] op_sel:[0,1,0] op_sel_hi:[1,1,1] neg_lo:[1,0,0] neg_hi:[1,0,0]
	v_pk_fma_f32 v[74:75], v[144:145], v[50:51], v[74:75] op_sel_hi:[1,0,1] neg_lo:[1,0,0] neg_hi:[1,0,0]
	v_pk_fma_f32 v[74:75], v[146:147], v[50:51], v[74:75] op_sel:[0,1,0] op_sel_hi:[1,1,1] neg_lo:[1,0,0] neg_hi:[1,0,0]
	v_pk_fma_f32 v[76:77], v[148:149], v[50:51], v[76:77] op_sel_hi:[1,0,1] neg_lo:[1,0,0] neg_hi:[1,0,0]
	v_pk_fma_f32 v[76:77], v[150:151], v[50:51], v[76:77] op_sel:[0,1,0] op_sel_hi:[1,1,1] neg_lo:[1,0,0] neg_hi:[1,0,0]
	ds_read_b128 v[120:123], v32 offset:7712
	ds_read_b128 v[124:127], v32 offset:8256
	ds_read_b128 v[128:131], v32 offset:7728
	ds_read_b128 v[132:135], v32 offset:8272
	ds_read_b128 v[144:147], v32 offset:7744
	ds_read_b128 v[148:151], v32 offset:8288
	s_waitcnt lgkmcnt(6)
	v_pk_fma_f32 v[74:75], v[2:3], v[52:53], v[74:75] op_sel_hi:[1,0,1] neg_lo:[1,0,0] neg_hi:[1,0,0]
	v_pk_fma_f32 v[74:75], v[4:5], v[52:53], v[74:75] op_sel:[0,1,0] op_sel_hi:[1,1,1] neg_lo:[1,0,0] neg_hi:[1,0,0]
	v_pk_fma_f32 v[76:77], v[6:7], v[52:53], v[76:77] op_sel_hi:[1,0,1] neg_lo:[1,0,0] neg_hi:[1,0,0]
	v_pk_fma_f32 v[76:77], v[8:9], v[52:53], v[76:77] op_sel:[0,1,0] op_sel_hi:[1,1,1] neg_lo:[1,0,0] neg_hi:[1,0,0]
	v_pk_fma_f32 v[74:75], v[10:11], v[54:55], v[74:75] op_sel_hi:[1,0,1] neg_lo:[1,0,0] neg_hi:[1,0,0]
	v_pk_fma_f32 v[74:75], v[12:13], v[54:55], v[74:75] op_sel:[0,1,0] op_sel_hi:[1,1,1] neg_lo:[1,0,0] neg_hi:[1,0,0]
	v_pk_fma_f32 v[76:77], v[14:15], v[54:55], v[76:77] op_sel_hi:[1,0,1] neg_lo:[1,0,0] neg_hi:[1,0,0]
	v_pk_fma_f32 v[76:77], v[16:17], v[54:55], v[76:77] op_sel:[0,1,0] op_sel_hi:[1,1,1] neg_lo:[1,0,0] neg_hi:[1,0,0]
	v_pk_fma_f32 v[74:75], v[18:19], v[56:57], v[74:75] op_sel_hi:[1,0,1] neg_lo:[1,0,0] neg_hi:[1,0,0]
	v_pk_fma_f32 v[74:75], v[20:21], v[56:57], v[74:75] op_sel:[0,1,0] op_sel_hi:[1,1,1] neg_lo:[1,0,0] neg_hi:[1,0,0]
	v_pk_fma_f32 v[76:77], v[22:23], v[56:57], v[76:77] op_sel_hi:[1,0,1] neg_lo:[1,0,0] neg_hi:[1,0,0]
	v_pk_fma_f32 v[76:77], v[24:25], v[56:57], v[76:77] op_sel:[0,1,0] op_sel_hi:[1,1,1] neg_lo:[1,0,0] neg_hi:[1,0,0]
	ds_read_b128 v[2:5], v32 offset:7760
	ds_read_b128 v[6:9], v32 offset:8304
	ds_read_b128 v[10:13], v32 offset:7776
	ds_read_b128 v[14:17], v32 offset:8320
	ds_read_b128 v[18:21], v32 offset:7792
	ds_read_b128 v[22:25], v32 offset:8336
	s_waitcnt lgkmcnt(6)
	v_pk_fma_f32 v[74:75], v[120:121], v[58:59], v[74:75] op_sel_hi:[1,0,1] neg_lo:[1,0,0] neg_hi:[1,0,0]
	v_pk_fma_f32 v[74:75], v[122:123], v[58:59], v[74:75] op_sel:[0,1,0] op_sel_hi:[1,1,1] neg_lo:[1,0,0] neg_hi:[1,0,0]
	v_pk_fma_f32 v[76:77], v[124:125], v[58:59], v[76:77] op_sel_hi:[1,0,1] neg_lo:[1,0,0] neg_hi:[1,0,0]
	v_pk_fma_f32 v[76:77], v[126:127], v[58:59], v[76:77] op_sel:[0,1,0] op_sel_hi:[1,1,1] neg_lo:[1,0,0] neg_hi:[1,0,0]
	v_pk_fma_f32 v[74:75], v[128:129], v[60:61], v[74:75] op_sel_hi:[1,0,1] neg_lo:[1,0,0] neg_hi:[1,0,0]
	v_pk_fma_f32 v[74:75], v[130:131], v[60:61], v[74:75] op_sel:[0,1,0] op_sel_hi:[1,1,1] neg_lo:[1,0,0] neg_hi:[1,0,0]
	v_pk_fma_f32 v[76:77], v[132:133], v[60:61], v[76:77] op_sel_hi:[1,0,1] neg_lo:[1,0,0] neg_hi:[1,0,0]
	v_pk_fma_f32 v[76:77], v[134:135], v[60:61], v[76:77] op_sel:[0,1,0] op_sel_hi:[1,1,1] neg_lo:[1,0,0] neg_hi:[1,0,0]
	v_pk_fma_f32 v[74:75], v[144:145], v[62:63], v[74:75] op_sel_hi:[1,0,1] neg_lo:[1,0,0] neg_hi:[1,0,0]
	v_pk_fma_f32 v[74:75], v[146:147], v[62:63], v[74:75] op_sel:[0,1,0] op_sel_hi:[1,1,1] neg_lo:[1,0,0] neg_hi:[1,0,0]
	v_pk_fma_f32 v[76:77], v[148:149], v[62:63], v[76:77] op_sel_hi:[1,0,1] neg_lo:[1,0,0] neg_hi:[1,0,0]
	v_pk_fma_f32 v[76:77], v[150:151], v[62:63], v[76:77] op_sel:[0,1,0] op_sel_hi:[1,1,1] neg_lo:[1,0,0] neg_hi:[1,0,0]
	ds_read_b128 v[120:123], v32 offset:7808
	ds_read_b128 v[124:127], v32 offset:8352
	ds_read_b128 v[128:131], v32 offset:7824
	ds_read_b128 v[132:135], v32 offset:8368
	ds_read_b128 v[144:147], v32 offset:7840
	ds_read_b128 v[148:151], v32 offset:8384
	s_waitcnt lgkmcnt(6)
	v_pk_fma_f32 v[74:75], v[2:3], v[64:65], v[74:75] op_sel_hi:[1,0,1] neg_lo:[1,0,0] neg_hi:[1,0,0]
	v_pk_fma_f32 v[74:75], v[4:5], v[64:65], v[74:75] op_sel:[0,1,0] op_sel_hi:[1,1,1] neg_lo:[1,0,0] neg_hi:[1,0,0]
	v_pk_fma_f32 v[76:77], v[6:7], v[64:65], v[76:77] op_sel_hi:[1,0,1] neg_lo:[1,0,0] neg_hi:[1,0,0]
	v_pk_fma_f32 v[76:77], v[8:9], v[64:65], v[76:77] op_sel:[0,1,0] op_sel_hi:[1,1,1] neg_lo:[1,0,0] neg_hi:[1,0,0]
	v_pk_fma_f32 v[74:75], v[10:11], v[66:67], v[74:75] op_sel_hi:[1,0,1] neg_lo:[1,0,0] neg_hi:[1,0,0]
	v_pk_fma_f32 v[74:75], v[12:13], v[66:67], v[74:75] op_sel:[0,1,0] op_sel_hi:[1,1,1] neg_lo:[1,0,0] neg_hi:[1,0,0]
	v_pk_fma_f32 v[76:77], v[14:15], v[66:67], v[76:77] op_sel_hi:[1,0,1] neg_lo:[1,0,0] neg_hi:[1,0,0]
	v_pk_fma_f32 v[76:77], v[16:17], v[66:67], v[76:77] op_sel:[0,1,0] op_sel_hi:[1,1,1] neg_lo:[1,0,0] neg_hi:[1,0,0]
	v_pk_fma_f32 v[74:75], v[18:19], v[68:69], v[74:75] op_sel_hi:[1,0,1] neg_lo:[1,0,0] neg_hi:[1,0,0]
	v_pk_fma_f32 v[74:75], v[20:21], v[68:69], v[74:75] op_sel:[0,1,0] op_sel_hi:[1,1,1] neg_lo:[1,0,0] neg_hi:[1,0,0]
	v_pk_fma_f32 v[76:77], v[22:23], v[68:69], v[76:77] op_sel_hi:[1,0,1] neg_lo:[1,0,0] neg_hi:[1,0,0]
	v_pk_fma_f32 v[76:77], v[24:25], v[68:69], v[76:77] op_sel:[0,1,0] op_sel_hi:[1,1,1] neg_lo:[1,0,0] neg_hi:[1,0,0]
	ds_read_b128 v[2:5], v32 offset:8400
	s_waitcnt lgkmcnt(1)
	v_pk_fma_f32 v[74:75], v[120:121], v[70:71], v[74:75] op_sel_hi:[1,0,1] neg_lo:[1,0,0] neg_hi:[1,0,0]
	v_pk_fma_f32 v[74:75], v[122:123], v[70:71], v[74:75] op_sel:[0,1,0] op_sel_hi:[1,1,1] neg_lo:[1,0,0] neg_hi:[1,0,0]
	v_pk_fma_f32 v[76:77], v[124:125], v[70:71], v[76:77] op_sel_hi:[1,0,1] neg_lo:[1,0,0] neg_hi:[1,0,0]
	v_pk_fma_f32 v[76:77], v[126:127], v[70:71], v[76:77] op_sel:[0,1,0] op_sel_hi:[1,1,1] neg_lo:[1,0,0] neg_hi:[1,0,0]
	v_pk_fma_f32 v[74:75], v[128:129], v[72:73], v[74:75] op_sel_hi:[1,0,1] neg_lo:[1,0,0] neg_hi:[1,0,0]
	v_pk_fma_f32 v[74:75], v[130:131], v[72:73], v[74:75] op_sel:[0,1,0] op_sel_hi:[1,1,1] neg_lo:[1,0,0] neg_hi:[1,0,0]
	v_pk_fma_f32 v[76:77], v[132:133], v[72:73], v[76:77] op_sel_hi:[1,0,1] neg_lo:[1,0,0] neg_hi:[1,0,0]
	v_pk_fma_f32 v[76:77], v[134:135], v[72:73], v[76:77] op_sel:[0,1,0] op_sel_hi:[1,1,1] neg_lo:[1,0,0] neg_hi:[1,0,0]
	v_fma_f32 v75, -v145, v74, v75
	v_pk_fma_f32 v[76:77], v[148:149], v[74:75], v[76:77] op_sel_hi:[1,0,1] neg_lo:[1,0,0] neg_hi:[1,0,0]
	v_pk_fma_f32 v[76:77], v[150:151], v[74:75], v[76:77] op_sel:[0,1,0] op_sel_hi:[1,1,1] neg_lo:[1,0,0] neg_hi:[1,0,0]
	ds_read_u16 v152, v30 offset:8704
	ds_read_u16 v153, v30 offset:8976
	ds_read_b64 v[154:155], v31 offset:128
	ds_read_u16 v156, v30 offset:9248
	ds_read_u16 v157, v30 offset:9520
	ds_read_b64 v[158:159], v31 offset:136
	ds_read_b128 v[120:123], v32 offset:8704
	ds_read_b128 v[124:127], v32 offset:9248
	ds_read_b128 v[128:131], v32 offset:8720
	ds_read_b128 v[132:135], v32 offset:9264
	ds_read_b128 v[144:147], v32 offset:8736
	ds_read_b128 v[148:151], v32 offset:9280
	s_waitcnt lgkmcnt(12)
	v_fma_f32 v77, -v3, v76, v77
	ds_read_b128 v[2:5], v32 offset:8752
	ds_read_b128 v[6:9], v32 offset:9296
	ds_read_b128 v[10:13], v32 offset:8768
	ds_read_b128 v[14:17], v32 offset:9312
	ds_read_b128 v[18:21], v32 offset:8784
	ds_read_b128 v[22:25], v32 offset:9328
	s_waitcnt lgkmcnt(6)
	v_lshlrev_b32_e32 v152, 16, v152
	v_lshlrev_b32_e32 v153, 16, v153
	v_pk_mul_f32 v[78:79], v[152:153], v[154:155]
	v_lshlrev_b32_e32 v156, 16, v156
	v_lshlrev_b32_e32 v157, 16, v157
	v_pk_mul_f32 v[80:81], v[156:157], v[158:159]
	v_pk_fma_f32 v[78:79], v[120:121], v[46:47], v[78:79] op_sel_hi:[1,0,1] neg_lo:[1,0,0] neg_hi:[1,0,0]
	v_pk_fma_f32 v[78:79], v[122:123], v[46:47], v[78:79] op_sel:[0,1,0] op_sel_hi:[1,1,1] neg_lo:[1,0,0] neg_hi:[1,0,0]
	v_pk_fma_f32 v[80:81], v[124:125], v[46:47], v[80:81] op_sel_hi:[1,0,1] neg_lo:[1,0,0] neg_hi:[1,0,0]
	v_pk_fma_f32 v[80:81], v[126:127], v[46:47], v[80:81] op_sel:[0,1,0] op_sel_hi:[1,1,1] neg_lo:[1,0,0] neg_hi:[1,0,0]
	v_pk_fma_f32 v[78:79], v[128:129], v[48:49], v[78:79] op_sel_hi:[1,0,1] neg_lo:[1,0,0] neg_hi:[1,0,0]
	v_pk_fma_f32 v[78:79], v[130:131], v[48:49], v[78:79] op_sel:[0,1,0] op_sel_hi:[1,1,1] neg_lo:[1,0,0] neg_hi:[1,0,0]
	v_pk_fma_f32 v[80:81], v[132:133], v[48:49], v[80:81] op_sel_hi:[1,0,1] neg_lo:[1,0,0] neg_hi:[1,0,0]
	v_pk_fma_f32 v[80:81], v[134:135], v[48:49], v[80:81] op_sel:[0,1,0] op_sel_hi:[1,1,1] neg_lo:[1,0,0] neg_hi:[1,0,0]
	v_pk_fma_f32 v[78:79], v[144:145], v[50:51], v[78:79] op_sel_hi:[1,0,1] neg_lo:[1,0,0] neg_hi:[1,0,0]
	v_pk_fma_f32 v[78:79], v[146:147], v[50:51], v[78:79] op_sel:[0,1,0] op_sel_hi:[1,1,1] neg_lo:[1,0,0] neg_hi:[1,0,0]
	v_pk_fma_f32 v[80:81], v[148:149], v[50:51], v[80:81] op_sel_hi:[1,0,1] neg_lo:[1,0,0] neg_hi:[1,0,0]
	v_pk_fma_f32 v[80:81], v[150:151], v[50:51], v[80:81] op_sel:[0,1,0] op_sel_hi:[1,1,1] neg_lo:[1,0,0] neg_hi:[1,0,0]
	ds_read_b128 v[120:123], v32 offset:8800
	ds_read_b128 v[124:127], v32 offset:9344
	ds_read_b128 v[128:131], v32 offset:8816
	ds_read_b128 v[132:135], v32 offset:9360
	ds_read_b128 v[144:147], v32 offset:8832
	ds_read_b128 v[148:151], v32 offset:9376
	s_waitcnt lgkmcnt(6)
	v_pk_fma_f32 v[78:79], v[2:3], v[52:53], v[78:79] op_sel_hi:[1,0,1] neg_lo:[1,0,0] neg_hi:[1,0,0]
	v_pk_fma_f32 v[78:79], v[4:5], v[52:53], v[78:79] op_sel:[0,1,0] op_sel_hi:[1,1,1] neg_lo:[1,0,0] neg_hi:[1,0,0]
	v_pk_fma_f32 v[80:81], v[6:7], v[52:53], v[80:81] op_sel_hi:[1,0,1] neg_lo:[1,0,0] neg_hi:[1,0,0]
	v_pk_fma_f32 v[80:81], v[8:9], v[52:53], v[80:81] op_sel:[0,1,0] op_sel_hi:[1,1,1] neg_lo:[1,0,0] neg_hi:[1,0,0]
	v_pk_fma_f32 v[78:79], v[10:11], v[54:55], v[78:79] op_sel_hi:[1,0,1] neg_lo:[1,0,0] neg_hi:[1,0,0]
	v_pk_fma_f32 v[78:79], v[12:13], v[54:55], v[78:79] op_sel:[0,1,0] op_sel_hi:[1,1,1] neg_lo:[1,0,0] neg_hi:[1,0,0]
	v_pk_fma_f32 v[80:81], v[14:15], v[54:55], v[80:81] op_sel_hi:[1,0,1] neg_lo:[1,0,0] neg_hi:[1,0,0]
	v_pk_fma_f32 v[80:81], v[16:17], v[54:55], v[80:81] op_sel:[0,1,0] op_sel_hi:[1,1,1] neg_lo:[1,0,0] neg_hi:[1,0,0]
	v_pk_fma_f32 v[78:79], v[18:19], v[56:57], v[78:79] op_sel_hi:[1,0,1] neg_lo:[1,0,0] neg_hi:[1,0,0]
	v_pk_fma_f32 v[78:79], v[20:21], v[56:57], v[78:79] op_sel:[0,1,0] op_sel_hi:[1,1,1] neg_lo:[1,0,0] neg_hi:[1,0,0]
	v_pk_fma_f32 v[80:81], v[22:23], v[56:57], v[80:81] op_sel_hi:[1,0,1] neg_lo:[1,0,0] neg_hi:[1,0,0]
	v_pk_fma_f32 v[80:81], v[24:25], v[56:57], v[80:81] op_sel:[0,1,0] op_sel_hi:[1,1,1] neg_lo:[1,0,0] neg_hi:[1,0,0]
	ds_read_b128 v[2:5], v32 offset:8848
	ds_read_b128 v[6:9], v32 offset:9392
	ds_read_b128 v[10:13], v32 offset:8864
	ds_read_b128 v[14:17], v32 offset:9408
	ds_read_b128 v[18:21], v32 offset:8880
	ds_read_b128 v[22:25], v32 offset:9424
	s_waitcnt lgkmcnt(6)
	v_pk_fma_f32 v[78:79], v[120:121], v[58:59], v[78:79] op_sel_hi:[1,0,1] neg_lo:[1,0,0] neg_hi:[1,0,0]
	v_pk_fma_f32 v[78:79], v[122:123], v[58:59], v[78:79] op_sel:[0,1,0] op_sel_hi:[1,1,1] neg_lo:[1,0,0] neg_hi:[1,0,0]
	v_pk_fma_f32 v[80:81], v[124:125], v[58:59], v[80:81] op_sel_hi:[1,0,1] neg_lo:[1,0,0] neg_hi:[1,0,0]
	v_pk_fma_f32 v[80:81], v[126:127], v[58:59], v[80:81] op_sel:[0,1,0] op_sel_hi:[1,1,1] neg_lo:[1,0,0] neg_hi:[1,0,0]
	v_pk_fma_f32 v[78:79], v[128:129], v[60:61], v[78:79] op_sel_hi:[1,0,1] neg_lo:[1,0,0] neg_hi:[1,0,0]
	v_pk_fma_f32 v[78:79], v[130:131], v[60:61], v[78:79] op_sel:[0,1,0] op_sel_hi:[1,1,1] neg_lo:[1,0,0] neg_hi:[1,0,0]
	v_pk_fma_f32 v[80:81], v[132:133], v[60:61], v[80:81] op_sel_hi:[1,0,1] neg_lo:[1,0,0] neg_hi:[1,0,0]
	v_pk_fma_f32 v[80:81], v[134:135], v[60:61], v[80:81] op_sel:[0,1,0] op_sel_hi:[1,1,1] neg_lo:[1,0,0] neg_hi:[1,0,0]
	v_pk_fma_f32 v[78:79], v[144:145], v[62:63], v[78:79] op_sel_hi:[1,0,1] neg_lo:[1,0,0] neg_hi:[1,0,0]
	v_pk_fma_f32 v[78:79], v[146:147], v[62:63], v[78:79] op_sel:[0,1,0] op_sel_hi:[1,1,1] neg_lo:[1,0,0] neg_hi:[1,0,0]
	v_pk_fma_f32 v[80:81], v[148:149], v[62:63], v[80:81] op_sel_hi:[1,0,1] neg_lo:[1,0,0] neg_hi:[1,0,0]
	v_pk_fma_f32 v[80:81], v[150:151], v[62:63], v[80:81] op_sel:[0,1,0] op_sel_hi:[1,1,1] neg_lo:[1,0,0] neg_hi:[1,0,0]
	ds_read_b128 v[120:123], v32 offset:8896
	ds_read_b128 v[124:127], v32 offset:9440
	ds_read_b128 v[128:131], v32 offset:8912
	ds_read_b128 v[132:135], v32 offset:9456
	ds_read_b128 v[144:147], v32 offset:8928
	ds_read_b128 v[148:151], v32 offset:9472
	s_waitcnt lgkmcnt(6)
	v_pk_fma_f32 v[78:79], v[2:3], v[64:65], v[78:79] op_sel_hi:[1,0,1] neg_lo:[1,0,0] neg_hi:[1,0,0]
	v_pk_fma_f32 v[78:79], v[4:5], v[64:65], v[78:79] op_sel:[0,1,0] op_sel_hi:[1,1,1] neg_lo:[1,0,0] neg_hi:[1,0,0]
	v_pk_fma_f32 v[80:81], v[6:7], v[64:65], v[80:81] op_sel_hi:[1,0,1] neg_lo:[1,0,0] neg_hi:[1,0,0]
	v_pk_fma_f32 v[80:81], v[8:9], v[64:65], v[80:81] op_sel:[0,1,0] op_sel_hi:[1,1,1] neg_lo:[1,0,0] neg_hi:[1,0,0]
	v_pk_fma_f32 v[78:79], v[10:11], v[66:67], v[78:79] op_sel_hi:[1,0,1] neg_lo:[1,0,0] neg_hi:[1,0,0]
	v_pk_fma_f32 v[78:79], v[12:13], v[66:67], v[78:79] op_sel:[0,1,0] op_sel_hi:[1,1,1] neg_lo:[1,0,0] neg_hi:[1,0,0]
	v_pk_fma_f32 v[80:81], v[14:15], v[66:67], v[80:81] op_sel_hi:[1,0,1] neg_lo:[1,0,0] neg_hi:[1,0,0]
	v_pk_fma_f32 v[80:81], v[16:17], v[66:67], v[80:81] op_sel:[0,1,0] op_sel_hi:[1,1,1] neg_lo:[1,0,0] neg_hi:[1,0,0]
	v_pk_fma_f32 v[78:79], v[18:19], v[68:69], v[78:79] op_sel_hi:[1,0,1] neg_lo:[1,0,0] neg_hi:[1,0,0]
	v_pk_fma_f32 v[78:79], v[20:21], v[68:69], v[78:79] op_sel:[0,1,0] op_sel_hi:[1,1,1] neg_lo:[1,0,0] neg_hi:[1,0,0]
	v_pk_fma_f32 v[80:81], v[22:23], v[68:69], v[80:81] op_sel_hi:[1,0,1] neg_lo:[1,0,0] neg_hi:[1,0,0]
	v_pk_fma_f32 v[80:81], v[24:25], v[68:69], v[80:81] op_sel:[0,1,0] op_sel_hi:[1,1,1] neg_lo:[1,0,0] neg_hi:[1,0,0]
	ds_read_b128 v[2:5], v32 offset:8944
	ds_read_b128 v[6:9], v32 offset:9488
	ds_read_b128 v[10:13], v32 offset:8960
	ds_read_b128 v[14:17], v32 offset:9504
	ds_read_b128 v[18:21], v32 offset:9520
	s_waitcnt lgkmcnt(5)
	v_pk_fma_f32 v[78:79], v[120:121], v[70:71], v[78:79] op_sel_hi:[1,0,1] neg_lo:[1,0,0] neg_hi:[1,0,0]
	v_pk_fma_f32 v[78:79], v[122:123], v[70:71], v[78:79] op_sel:[0,1,0] op_sel_hi:[1,1,1] neg_lo:[1,0,0] neg_hi:[1,0,0]
	v_pk_fma_f32 v[80:81], v[124:125], v[70:71], v[80:81] op_sel_hi:[1,0,1] neg_lo:[1,0,0] neg_hi:[1,0,0]
	v_pk_fma_f32 v[80:81], v[126:127], v[70:71], v[80:81] op_sel:[0,1,0] op_sel_hi:[1,1,1] neg_lo:[1,0,0] neg_hi:[1,0,0]
	v_pk_fma_f32 v[78:79], v[128:129], v[72:73], v[78:79] op_sel_hi:[1,0,1] neg_lo:[1,0,0] neg_hi:[1,0,0]
	v_pk_fma_f32 v[78:79], v[130:131], v[72:73], v[78:79] op_sel:[0,1,0] op_sel_hi:[1,1,1] neg_lo:[1,0,0] neg_hi:[1,0,0]
	v_pk_fma_f32 v[80:81], v[132:133], v[72:73], v[80:81] op_sel_hi:[1,0,1] neg_lo:[1,0,0] neg_hi:[1,0,0]
	v_pk_fma_f32 v[80:81], v[134:135], v[72:73], v[80:81] op_sel:[0,1,0] op_sel_hi:[1,1,1] neg_lo:[1,0,0] neg_hi:[1,0,0]
	v_pk_fma_f32 v[78:79], v[144:145], v[74:75], v[78:79] op_sel_hi:[1,0,1] neg_lo:[1,0,0] neg_hi:[1,0,0]
	v_pk_fma_f32 v[78:79], v[146:147], v[74:75], v[78:79] op_sel:[0,1,0] op_sel_hi:[1,1,1] neg_lo:[1,0,0] neg_hi:[1,0,0]
	v_pk_fma_f32 v[80:81], v[148:149], v[74:75], v[80:81] op_sel_hi:[1,0,1] neg_lo:[1,0,0] neg_hi:[1,0,0]
	v_pk_fma_f32 v[80:81], v[150:151], v[74:75], v[80:81] op_sel:[0,1,0] op_sel_hi:[1,1,1] neg_lo:[1,0,0] neg_hi:[1,0,0]
	ds_read_u16 v152, v30 offset:9792
	ds_read_u16 v153, v30 offset:10064
	ds_read_b64 v[154:155], v31 offset:144
	ds_read_u16 v156, v30 offset:10336
	ds_read_u16 v157, v30 offset:10608
	ds_read_b64 v[158:159], v31 offset:152
	ds_read_b128 v[120:123], v32 offset:9792
	ds_read_b128 v[124:127], v32 offset:10336
	ds_read_b128 v[128:131], v32 offset:9808
	ds_read_b128 v[132:135], v32 offset:10352
	ds_read_b128 v[144:147], v32 offset:9824
	ds_read_b128 v[148:151], v32 offset:10368
	s_waitcnt lgkmcnt(12)
	v_pk_fma_f32 v[78:79], v[2:3], v[76:77], v[78:79] op_sel_hi:[1,0,1] neg_lo:[1,0,0] neg_hi:[1,0,0]
	v_pk_fma_f32 v[78:79], v[4:5], v[76:77], v[78:79] op_sel:[0,1,0] op_sel_hi:[1,1,1] neg_lo:[1,0,0] neg_hi:[1,0,0]
	v_pk_fma_f32 v[80:81], v[6:7], v[76:77], v[80:81] op_sel_hi:[1,0,1] neg_lo:[1,0,0] neg_hi:[1,0,0]
	v_pk_fma_f32 v[80:81], v[8:9], v[76:77], v[80:81] op_sel:[0,1,0] op_sel_hi:[1,1,1] neg_lo:[1,0,0] neg_hi:[1,0,0]
	v_fma_f32 v79, -v11, v78, v79
	v_pk_fma_f32 v[80:81], v[14:15], v[78:79], v[80:81] op_sel_hi:[1,0,1] neg_lo:[1,0,0] neg_hi:[1,0,0]
	v_pk_fma_f32 v[80:81], v[16:17], v[78:79], v[80:81] op_sel:[0,1,0] op_sel_hi:[1,1,1] neg_lo:[1,0,0] neg_hi:[1,0,0]
	v_fma_f32 v81, -v19, v80, v81
	ds_read_b128 v[2:5], v32 offset:9840
	ds_read_b128 v[6:9], v32 offset:10384
	ds_read_b128 v[10:13], v32 offset:9856
	ds_read_b128 v[14:17], v32 offset:10400
	ds_read_b128 v[18:21], v32 offset:9872
	ds_read_b128 v[22:25], v32 offset:10416
	s_waitcnt lgkmcnt(6)
	v_lshlrev_b32_e32 v152, 16, v152
	v_lshlrev_b32_e32 v153, 16, v153
	v_pk_mul_f32 v[82:83], v[152:153], v[154:155]
	v_lshlrev_b32_e32 v156, 16, v156
	v_lshlrev_b32_e32 v157, 16, v157
	v_pk_mul_f32 v[84:85], v[156:157], v[158:159]
	v_pk_fma_f32 v[82:83], v[120:121], v[46:47], v[82:83] op_sel_hi:[1,0,1] neg_lo:[1,0,0] neg_hi:[1,0,0]
	v_pk_fma_f32 v[82:83], v[122:123], v[46:47], v[82:83] op_sel:[0,1,0] op_sel_hi:[1,1,1] neg_lo:[1,0,0] neg_hi:[1,0,0]
	v_pk_fma_f32 v[84:85], v[124:125], v[46:47], v[84:85] op_sel_hi:[1,0,1] neg_lo:[1,0,0] neg_hi:[1,0,0]
	v_pk_fma_f32 v[84:85], v[126:127], v[46:47], v[84:85] op_sel:[0,1,0] op_sel_hi:[1,1,1] neg_lo:[1,0,0] neg_hi:[1,0,0]
	v_pk_fma_f32 v[82:83], v[128:129], v[48:49], v[82:83] op_sel_hi:[1,0,1] neg_lo:[1,0,0] neg_hi:[1,0,0]
	v_pk_fma_f32 v[82:83], v[130:131], v[48:49], v[82:83] op_sel:[0,1,0] op_sel_hi:[1,1,1] neg_lo:[1,0,0] neg_hi:[1,0,0]
	v_pk_fma_f32 v[84:85], v[132:133], v[48:49], v[84:85] op_sel_hi:[1,0,1] neg_lo:[1,0,0] neg_hi:[1,0,0]
	v_pk_fma_f32 v[84:85], v[134:135], v[48:49], v[84:85] op_sel:[0,1,0] op_sel_hi:[1,1,1] neg_lo:[1,0,0] neg_hi:[1,0,0]
	v_pk_fma_f32 v[82:83], v[144:145], v[50:51], v[82:83] op_sel_hi:[1,0,1] neg_lo:[1,0,0] neg_hi:[1,0,0]
	v_pk_fma_f32 v[82:83], v[146:147], v[50:51], v[82:83] op_sel:[0,1,0] op_sel_hi:[1,1,1] neg_lo:[1,0,0] neg_hi:[1,0,0]
	v_pk_fma_f32 v[84:85], v[148:149], v[50:51], v[84:85] op_sel_hi:[1,0,1] neg_lo:[1,0,0] neg_hi:[1,0,0]
	v_pk_fma_f32 v[84:85], v[150:151], v[50:51], v[84:85] op_sel:[0,1,0] op_sel_hi:[1,1,1] neg_lo:[1,0,0] neg_hi:[1,0,0]
	ds_read_b128 v[120:123], v32 offset:9888
	ds_read_b128 v[124:127], v32 offset:10432
	ds_read_b128 v[128:131], v32 offset:9904
	ds_read_b128 v[132:135], v32 offset:10448
	ds_read_b128 v[144:147], v32 offset:9920
	ds_read_b128 v[148:151], v32 offset:10464
	s_waitcnt lgkmcnt(6)
	v_pk_fma_f32 v[82:83], v[2:3], v[52:53], v[82:83] op_sel_hi:[1,0,1] neg_lo:[1,0,0] neg_hi:[1,0,0]
	v_pk_fma_f32 v[82:83], v[4:5], v[52:53], v[82:83] op_sel:[0,1,0] op_sel_hi:[1,1,1] neg_lo:[1,0,0] neg_hi:[1,0,0]
	v_pk_fma_f32 v[84:85], v[6:7], v[52:53], v[84:85] op_sel_hi:[1,0,1] neg_lo:[1,0,0] neg_hi:[1,0,0]
	v_pk_fma_f32 v[84:85], v[8:9], v[52:53], v[84:85] op_sel:[0,1,0] op_sel_hi:[1,1,1] neg_lo:[1,0,0] neg_hi:[1,0,0]
	v_pk_fma_f32 v[82:83], v[10:11], v[54:55], v[82:83] op_sel_hi:[1,0,1] neg_lo:[1,0,0] neg_hi:[1,0,0]
	v_pk_fma_f32 v[82:83], v[12:13], v[54:55], v[82:83] op_sel:[0,1,0] op_sel_hi:[1,1,1] neg_lo:[1,0,0] neg_hi:[1,0,0]
	v_pk_fma_f32 v[84:85], v[14:15], v[54:55], v[84:85] op_sel_hi:[1,0,1] neg_lo:[1,0,0] neg_hi:[1,0,0]
	v_pk_fma_f32 v[84:85], v[16:17], v[54:55], v[84:85] op_sel:[0,1,0] op_sel_hi:[1,1,1] neg_lo:[1,0,0] neg_hi:[1,0,0]
	v_pk_fma_f32 v[82:83], v[18:19], v[56:57], v[82:83] op_sel_hi:[1,0,1] neg_lo:[1,0,0] neg_hi:[1,0,0]
	v_pk_fma_f32 v[82:83], v[20:21], v[56:57], v[82:83] op_sel:[0,1,0] op_sel_hi:[1,1,1] neg_lo:[1,0,0] neg_hi:[1,0,0]
	v_pk_fma_f32 v[84:85], v[22:23], v[56:57], v[84:85] op_sel_hi:[1,0,1] neg_lo:[1,0,0] neg_hi:[1,0,0]
	v_pk_fma_f32 v[84:85], v[24:25], v[56:57], v[84:85] op_sel:[0,1,0] op_sel_hi:[1,1,1] neg_lo:[1,0,0] neg_hi:[1,0,0]
	ds_read_b128 v[2:5], v32 offset:9936
	ds_read_b128 v[6:9], v32 offset:10480
	ds_read_b128 v[10:13], v32 offset:9952
	ds_read_b128 v[14:17], v32 offset:10496
	ds_read_b128 v[18:21], v32 offset:9968
	ds_read_b128 v[22:25], v32 offset:10512
	s_waitcnt lgkmcnt(6)
	v_pk_fma_f32 v[82:83], v[120:121], v[58:59], v[82:83] op_sel_hi:[1,0,1] neg_lo:[1,0,0] neg_hi:[1,0,0]
	v_pk_fma_f32 v[82:83], v[122:123], v[58:59], v[82:83] op_sel:[0,1,0] op_sel_hi:[1,1,1] neg_lo:[1,0,0] neg_hi:[1,0,0]
	v_pk_fma_f32 v[84:85], v[124:125], v[58:59], v[84:85] op_sel_hi:[1,0,1] neg_lo:[1,0,0] neg_hi:[1,0,0]
	v_pk_fma_f32 v[84:85], v[126:127], v[58:59], v[84:85] op_sel:[0,1,0] op_sel_hi:[1,1,1] neg_lo:[1,0,0] neg_hi:[1,0,0]
	v_pk_fma_f32 v[82:83], v[128:129], v[60:61], v[82:83] op_sel_hi:[1,0,1] neg_lo:[1,0,0] neg_hi:[1,0,0]
	v_pk_fma_f32 v[82:83], v[130:131], v[60:61], v[82:83] op_sel:[0,1,0] op_sel_hi:[1,1,1] neg_lo:[1,0,0] neg_hi:[1,0,0]
	v_pk_fma_f32 v[84:85], v[132:133], v[60:61], v[84:85] op_sel_hi:[1,0,1] neg_lo:[1,0,0] neg_hi:[1,0,0]
	v_pk_fma_f32 v[84:85], v[134:135], v[60:61], v[84:85] op_sel:[0,1,0] op_sel_hi:[1,1,1] neg_lo:[1,0,0] neg_hi:[1,0,0]
	v_pk_fma_f32 v[82:83], v[144:145], v[62:63], v[82:83] op_sel_hi:[1,0,1] neg_lo:[1,0,0] neg_hi:[1,0,0]
	v_pk_fma_f32 v[82:83], v[146:147], v[62:63], v[82:83] op_sel:[0,1,0] op_sel_hi:[1,1,1] neg_lo:[1,0,0] neg_hi:[1,0,0]
	v_pk_fma_f32 v[84:85], v[148:149], v[62:63], v[84:85] op_sel_hi:[1,0,1] neg_lo:[1,0,0] neg_hi:[1,0,0]
	v_pk_fma_f32 v[84:85], v[150:151], v[62:63], v[84:85] op_sel:[0,1,0] op_sel_hi:[1,1,1] neg_lo:[1,0,0] neg_hi:[1,0,0]
	ds_read_b128 v[120:123], v32 offset:9984
	ds_read_b128 v[124:127], v32 offset:10528
	ds_read_b128 v[128:131], v32 offset:10000
	ds_read_b128 v[132:135], v32 offset:10544
	ds_read_b128 v[144:147], v32 offset:10016
	ds_read_b128 v[148:151], v32 offset:10560
	s_waitcnt lgkmcnt(6)
	v_pk_fma_f32 v[82:83], v[2:3], v[64:65], v[82:83] op_sel_hi:[1,0,1] neg_lo:[1,0,0] neg_hi:[1,0,0]
	v_pk_fma_f32 v[82:83], v[4:5], v[64:65], v[82:83] op_sel:[0,1,0] op_sel_hi:[1,1,1] neg_lo:[1,0,0] neg_hi:[1,0,0]
	v_pk_fma_f32 v[84:85], v[6:7], v[64:65], v[84:85] op_sel_hi:[1,0,1] neg_lo:[1,0,0] neg_hi:[1,0,0]
	v_pk_fma_f32 v[84:85], v[8:9], v[64:65], v[84:85] op_sel:[0,1,0] op_sel_hi:[1,1,1] neg_lo:[1,0,0] neg_hi:[1,0,0]
	v_pk_fma_f32 v[82:83], v[10:11], v[66:67], v[82:83] op_sel_hi:[1,0,1] neg_lo:[1,0,0] neg_hi:[1,0,0]
	v_pk_fma_f32 v[82:83], v[12:13], v[66:67], v[82:83] op_sel:[0,1,0] op_sel_hi:[1,1,1] neg_lo:[1,0,0] neg_hi:[1,0,0]
	v_pk_fma_f32 v[84:85], v[14:15], v[66:67], v[84:85] op_sel_hi:[1,0,1] neg_lo:[1,0,0] neg_hi:[1,0,0]
	v_pk_fma_f32 v[84:85], v[16:17], v[66:67], v[84:85] op_sel:[0,1,0] op_sel_hi:[1,1,1] neg_lo:[1,0,0] neg_hi:[1,0,0]
	v_pk_fma_f32 v[82:83], v[18:19], v[68:69], v[82:83] op_sel_hi:[1,0,1] neg_lo:[1,0,0] neg_hi:[1,0,0]
	v_pk_fma_f32 v[82:83], v[20:21], v[68:69], v[82:83] op_sel:[0,1,0] op_sel_hi:[1,1,1] neg_lo:[1,0,0] neg_hi:[1,0,0]
	v_pk_fma_f32 v[84:85], v[22:23], v[68:69], v[84:85] op_sel_hi:[1,0,1] neg_lo:[1,0,0] neg_hi:[1,0,0]
	v_pk_fma_f32 v[84:85], v[24:25], v[68:69], v[84:85] op_sel:[0,1,0] op_sel_hi:[1,1,1] neg_lo:[1,0,0] neg_hi:[1,0,0]
	ds_read_b128 v[2:5], v32 offset:10032
	ds_read_b128 v[6:9], v32 offset:10576
	ds_read_b128 v[10:13], v32 offset:10048
	ds_read_b128 v[14:17], v32 offset:10592
	ds_read_b128 v[18:21], v32 offset:10064
	ds_read_b128 v[22:25], v32 offset:10608
	s_waitcnt lgkmcnt(6)
	v_pk_fma_f32 v[82:83], v[120:121], v[70:71], v[82:83] op_sel_hi:[1,0,1] neg_lo:[1,0,0] neg_hi:[1,0,0]
	v_pk_fma_f32 v[82:83], v[122:123], v[70:71], v[82:83] op_sel:[0,1,0] op_sel_hi:[1,1,1] neg_lo:[1,0,0] neg_hi:[1,0,0]
	v_pk_fma_f32 v[84:85], v[124:125], v[70:71], v[84:85] op_sel_hi:[1,0,1] neg_lo:[1,0,0] neg_hi:[1,0,0]
	v_pk_fma_f32 v[84:85], v[126:127], v[70:71], v[84:85] op_sel:[0,1,0] op_sel_hi:[1,1,1] neg_lo:[1,0,0] neg_hi:[1,0,0]
	v_pk_fma_f32 v[82:83], v[128:129], v[72:73], v[82:83] op_sel_hi:[1,0,1] neg_lo:[1,0,0] neg_hi:[1,0,0]
	v_pk_fma_f32 v[82:83], v[130:131], v[72:73], v[82:83] op_sel:[0,1,0] op_sel_hi:[1,1,1] neg_lo:[1,0,0] neg_hi:[1,0,0]
	v_pk_fma_f32 v[84:85], v[132:133], v[72:73], v[84:85] op_sel_hi:[1,0,1] neg_lo:[1,0,0] neg_hi:[1,0,0]
	v_pk_fma_f32 v[84:85], v[134:135], v[72:73], v[84:85] op_sel:[0,1,0] op_sel_hi:[1,1,1] neg_lo:[1,0,0] neg_hi:[1,0,0]
	v_pk_fma_f32 v[82:83], v[144:145], v[74:75], v[82:83] op_sel_hi:[1,0,1] neg_lo:[1,0,0] neg_hi:[1,0,0]
	v_pk_fma_f32 v[82:83], v[146:147], v[74:75], v[82:83] op_sel:[0,1,0] op_sel_hi:[1,1,1] neg_lo:[1,0,0] neg_hi:[1,0,0]
	v_pk_fma_f32 v[84:85], v[148:149], v[74:75], v[84:85] op_sel_hi:[1,0,1] neg_lo:[1,0,0] neg_hi:[1,0,0]
	v_pk_fma_f32 v[84:85], v[150:151], v[74:75], v[84:85] op_sel:[0,1,0] op_sel_hi:[1,1,1] neg_lo:[1,0,0] neg_hi:[1,0,0]
	ds_read_b128 v[120:123], v32 offset:10080
	ds_read_b128 v[124:127], v32 offset:10624
	ds_read_b128 v[128:131], v32 offset:10640
	s_waitcnt lgkmcnt(3)
	v_pk_fma_f32 v[82:83], v[2:3], v[76:77], v[82:83] op_sel_hi:[1,0,1] neg_lo:[1,0,0] neg_hi:[1,0,0]
	v_pk_fma_f32 v[82:83], v[4:5], v[76:77], v[82:83] op_sel:[0,1,0] op_sel_hi:[1,1,1] neg_lo:[1,0,0] neg_hi:[1,0,0]
	v_pk_fma_f32 v[84:85], v[6:7], v[76:77], v[84:85] op_sel_hi:[1,0,1] neg_lo:[1,0,0] neg_hi:[1,0,0]
	v_pk_fma_f32 v[84:85], v[8:9], v[76:77], v[84:85] op_sel:[0,1,0] op_sel_hi:[1,1,1] neg_lo:[1,0,0] neg_hi:[1,0,0]
	v_pk_fma_f32 v[82:83], v[10:11], v[78:79], v[82:83] op_sel_hi:[1,0,1] neg_lo:[1,0,0] neg_hi:[1,0,0]
	v_pk_fma_f32 v[82:83], v[12:13], v[78:79], v[82:83] op_sel:[0,1,0] op_sel_hi:[1,1,1] neg_lo:[1,0,0] neg_hi:[1,0,0]
	v_pk_fma_f32 v[84:85], v[14:15], v[78:79], v[84:85] op_sel_hi:[1,0,1] neg_lo:[1,0,0] neg_hi:[1,0,0]
	v_pk_fma_f32 v[84:85], v[16:17], v[78:79], v[84:85] op_sel:[0,1,0] op_sel_hi:[1,1,1] neg_lo:[1,0,0] neg_hi:[1,0,0]
	v_pk_fma_f32 v[82:83], v[18:19], v[80:81], v[82:83] op_sel_hi:[1,0,1] neg_lo:[1,0,0] neg_hi:[1,0,0]
	v_pk_fma_f32 v[82:83], v[20:21], v[80:81], v[82:83] op_sel:[0,1,0] op_sel_hi:[1,1,1] neg_lo:[1,0,0] neg_hi:[1,0,0]
	v_pk_fma_f32 v[84:85], v[22:23], v[80:81], v[84:85] op_sel_hi:[1,0,1] neg_lo:[1,0,0] neg_hi:[1,0,0]
	v_pk_fma_f32 v[84:85], v[24:25], v[80:81], v[84:85] op_sel:[0,1,0] op_sel_hi:[1,1,1] neg_lo:[1,0,0] neg_hi:[1,0,0]
	ds_read_u16 v26, v30 offset:10880
	ds_read_u16 v27, v30 offset:11152
	ds_read_b64 v[28:29], v31 offset:160
	ds_read_u16 v36, v30 offset:11424
	ds_read_u16 v37, v30 offset:11696
	ds_read_b64 v[38:39], v31 offset:168
	ds_read_b128 v[2:5], v32 offset:10880
	ds_read_b128 v[6:9], v32 offset:11424
	ds_read_b128 v[10:13], v32 offset:10896
	ds_read_b128 v[14:17], v32 offset:11440
	ds_read_b128 v[18:21], v32 offset:10912
	ds_read_b128 v[22:25], v32 offset:11456
	s_waitcnt lgkmcnt(12)
	v_fma_f32 v83, -v121, v82, v83
	v_pk_fma_f32 v[84:85], v[124:125], v[82:83], v[84:85] op_sel_hi:[1,0,1] neg_lo:[1,0,0] neg_hi:[1,0,0]
	v_pk_fma_f32 v[84:85], v[126:127], v[82:83], v[84:85] op_sel:[0,1,0] op_sel_hi:[1,1,1] neg_lo:[1,0,0] neg_hi:[1,0,0]
	v_fma_f32 v85, -v129, v84, v85
	ds_read_b128 v[120:123], v32 offset:10928
	ds_read_b128 v[124:127], v32 offset:11472
	ds_read_b128 v[128:131], v32 offset:10944
	ds_read_b128 v[132:135], v32 offset:11488
	ds_read_b128 v[144:147], v32 offset:10960
	ds_read_b128 v[148:151], v32 offset:11504
	s_waitcnt lgkmcnt(6)
	v_lshlrev_b32_e32 v26, 16, v26
	v_lshlrev_b32_e32 v27, 16, v27
	v_pk_mul_f32 v[86:87], v[26:27], v[28:29]
	v_lshlrev_b32_e32 v36, 16, v36
	v_lshlrev_b32_e32 v37, 16, v37
	v_pk_mul_f32 v[88:89], v[36:37], v[38:39]
	v_pk_fma_f32 v[86:87], v[2:3], v[46:47], v[86:87] op_sel_hi:[1,0,1] neg_lo:[1,0,0] neg_hi:[1,0,0]
	v_pk_fma_f32 v[86:87], v[4:5], v[46:47], v[86:87] op_sel:[0,1,0] op_sel_hi:[1,1,1] neg_lo:[1,0,0] neg_hi:[1,0,0]
	v_pk_fma_f32 v[88:89], v[6:7], v[46:47], v[88:89] op_sel_hi:[1,0,1] neg_lo:[1,0,0] neg_hi:[1,0,0]
	v_pk_fma_f32 v[88:89], v[8:9], v[46:47], v[88:89] op_sel:[0,1,0] op_sel_hi:[1,1,1] neg_lo:[1,0,0] neg_hi:[1,0,0]
	v_pk_fma_f32 v[86:87], v[10:11], v[48:49], v[86:87] op_sel_hi:[1,0,1] neg_lo:[1,0,0] neg_hi:[1,0,0]
	v_pk_fma_f32 v[86:87], v[12:13], v[48:49], v[86:87] op_sel:[0,1,0] op_sel_hi:[1,1,1] neg_lo:[1,0,0] neg_hi:[1,0,0]
	v_pk_fma_f32 v[88:89], v[14:15], v[48:49], v[88:89] op_sel_hi:[1,0,1] neg_lo:[1,0,0] neg_hi:[1,0,0]
	v_pk_fma_f32 v[88:89], v[16:17], v[48:49], v[88:89] op_sel:[0,1,0] op_sel_hi:[1,1,1] neg_lo:[1,0,0] neg_hi:[1,0,0]
	v_pk_fma_f32 v[86:87], v[18:19], v[50:51], v[86:87] op_sel_hi:[1,0,1] neg_lo:[1,0,0] neg_hi:[1,0,0]
	v_pk_fma_f32 v[86:87], v[20:21], v[50:51], v[86:87] op_sel:[0,1,0] op_sel_hi:[1,1,1] neg_lo:[1,0,0] neg_hi:[1,0,0]
	v_pk_fma_f32 v[88:89], v[22:23], v[50:51], v[88:89] op_sel_hi:[1,0,1] neg_lo:[1,0,0] neg_hi:[1,0,0]
	v_pk_fma_f32 v[88:89], v[24:25], v[50:51], v[88:89] op_sel:[0,1,0] op_sel_hi:[1,1,1] neg_lo:[1,0,0] neg_hi:[1,0,0]
	ds_read_b128 v[2:5], v32 offset:10976
	ds_read_b128 v[6:9], v32 offset:11520
	ds_read_b128 v[10:13], v32 offset:10992
	ds_read_b128 v[14:17], v32 offset:11536
	ds_read_b128 v[18:21], v32 offset:11008
	ds_read_b128 v[22:25], v32 offset:11552
	s_waitcnt lgkmcnt(6)
	v_pk_fma_f32 v[86:87], v[120:121], v[52:53], v[86:87] op_sel_hi:[1,0,1] neg_lo:[1,0,0] neg_hi:[1,0,0]
	v_pk_fma_f32 v[86:87], v[122:123], v[52:53], v[86:87] op_sel:[0,1,0] op_sel_hi:[1,1,1] neg_lo:[1,0,0] neg_hi:[1,0,0]
	v_pk_fma_f32 v[88:89], v[124:125], v[52:53], v[88:89] op_sel_hi:[1,0,1] neg_lo:[1,0,0] neg_hi:[1,0,0]
	v_pk_fma_f32 v[88:89], v[126:127], v[52:53], v[88:89] op_sel:[0,1,0] op_sel_hi:[1,1,1] neg_lo:[1,0,0] neg_hi:[1,0,0]
	v_pk_fma_f32 v[86:87], v[128:129], v[54:55], v[86:87] op_sel_hi:[1,0,1] neg_lo:[1,0,0] neg_hi:[1,0,0]
	v_pk_fma_f32 v[86:87], v[130:131], v[54:55], v[86:87] op_sel:[0,1,0] op_sel_hi:[1,1,1] neg_lo:[1,0,0] neg_hi:[1,0,0]
	v_pk_fma_f32 v[88:89], v[132:133], v[54:55], v[88:89] op_sel_hi:[1,0,1] neg_lo:[1,0,0] neg_hi:[1,0,0]
	v_pk_fma_f32 v[88:89], v[134:135], v[54:55], v[88:89] op_sel:[0,1,0] op_sel_hi:[1,1,1] neg_lo:[1,0,0] neg_hi:[1,0,0]
	v_pk_fma_f32 v[86:87], v[144:145], v[56:57], v[86:87] op_sel_hi:[1,0,1] neg_lo:[1,0,0] neg_hi:[1,0,0]
	v_pk_fma_f32 v[86:87], v[146:147], v[56:57], v[86:87] op_sel:[0,1,0] op_sel_hi:[1,1,1] neg_lo:[1,0,0] neg_hi:[1,0,0]
	v_pk_fma_f32 v[88:89], v[148:149], v[56:57], v[88:89] op_sel_hi:[1,0,1] neg_lo:[1,0,0] neg_hi:[1,0,0]
	v_pk_fma_f32 v[88:89], v[150:151], v[56:57], v[88:89] op_sel:[0,1,0] op_sel_hi:[1,1,1] neg_lo:[1,0,0] neg_hi:[1,0,0]
	ds_read_b128 v[120:123], v32 offset:11024
	ds_read_b128 v[124:127], v32 offset:11568
	ds_read_b128 v[128:131], v32 offset:11040
	ds_read_b128 v[132:135], v32 offset:11584
	ds_read_b128 v[144:147], v32 offset:11056
	ds_read_b128 v[148:151], v32 offset:11600
	s_waitcnt lgkmcnt(6)
	v_pk_fma_f32 v[86:87], v[2:3], v[58:59], v[86:87] op_sel_hi:[1,0,1] neg_lo:[1,0,0] neg_hi:[1,0,0]
	v_pk_fma_f32 v[86:87], v[4:5], v[58:59], v[86:87] op_sel:[0,1,0] op_sel_hi:[1,1,1] neg_lo:[1,0,0] neg_hi:[1,0,0]
	v_pk_fma_f32 v[88:89], v[6:7], v[58:59], v[88:89] op_sel_hi:[1,0,1] neg_lo:[1,0,0] neg_hi:[1,0,0]
	v_pk_fma_f32 v[88:89], v[8:9], v[58:59], v[88:89] op_sel:[0,1,0] op_sel_hi:[1,1,1] neg_lo:[1,0,0] neg_hi:[1,0,0]
	v_pk_fma_f32 v[86:87], v[10:11], v[60:61], v[86:87] op_sel_hi:[1,0,1] neg_lo:[1,0,0] neg_hi:[1,0,0]
	v_pk_fma_f32 v[86:87], v[12:13], v[60:61], v[86:87] op_sel:[0,1,0] op_sel_hi:[1,1,1] neg_lo:[1,0,0] neg_hi:[1,0,0]
	v_pk_fma_f32 v[88:89], v[14:15], v[60:61], v[88:89] op_sel_hi:[1,0,1] neg_lo:[1,0,0] neg_hi:[1,0,0]
	v_pk_fma_f32 v[88:89], v[16:17], v[60:61], v[88:89] op_sel:[0,1,0] op_sel_hi:[1,1,1] neg_lo:[1,0,0] neg_hi:[1,0,0]
	v_pk_fma_f32 v[86:87], v[18:19], v[62:63], v[86:87] op_sel_hi:[1,0,1] neg_lo:[1,0,0] neg_hi:[1,0,0]
	v_pk_fma_f32 v[86:87], v[20:21], v[62:63], v[86:87] op_sel:[0,1,0] op_sel_hi:[1,1,1] neg_lo:[1,0,0] neg_hi:[1,0,0]
	v_pk_fma_f32 v[88:89], v[22:23], v[62:63], v[88:89] op_sel_hi:[1,0,1] neg_lo:[1,0,0] neg_hi:[1,0,0]
	v_pk_fma_f32 v[88:89], v[24:25], v[62:63], v[88:89] op_sel:[0,1,0] op_sel_hi:[1,1,1] neg_lo:[1,0,0] neg_hi:[1,0,0]
	ds_read_b128 v[2:5], v32 offset:11072
	ds_read_b128 v[6:9], v32 offset:11616
	ds_read_b128 v[10:13], v32 offset:11088
	ds_read_b128 v[14:17], v32 offset:11632
	ds_read_b128 v[18:21], v32 offset:11104
	ds_read_b128 v[22:25], v32 offset:11648
	s_waitcnt lgkmcnt(6)
	v_pk_fma_f32 v[86:87], v[120:121], v[64:65], v[86:87] op_sel_hi:[1,0,1] neg_lo:[1,0,0] neg_hi:[1,0,0]
	v_pk_fma_f32 v[86:87], v[122:123], v[64:65], v[86:87] op_sel:[0,1,0] op_sel_hi:[1,1,1] neg_lo:[1,0,0] neg_hi:[1,0,0]
	v_pk_fma_f32 v[88:89], v[124:125], v[64:65], v[88:89] op_sel_hi:[1,0,1] neg_lo:[1,0,0] neg_hi:[1,0,0]
	v_pk_fma_f32 v[88:89], v[126:127], v[64:65], v[88:89] op_sel:[0,1,0] op_sel_hi:[1,1,1] neg_lo:[1,0,0] neg_hi:[1,0,0]
	v_pk_fma_f32 v[86:87], v[128:129], v[66:67], v[86:87] op_sel_hi:[1,0,1] neg_lo:[1,0,0] neg_hi:[1,0,0]
	v_pk_fma_f32 v[86:87], v[130:131], v[66:67], v[86:87] op_sel:[0,1,0] op_sel_hi:[1,1,1] neg_lo:[1,0,0] neg_hi:[1,0,0]
	v_pk_fma_f32 v[88:89], v[132:133], v[66:67], v[88:89] op_sel_hi:[1,0,1] neg_lo:[1,0,0] neg_hi:[1,0,0]
	v_pk_fma_f32 v[88:89], v[134:135], v[66:67], v[88:89] op_sel:[0,1,0] op_sel_hi:[1,1,1] neg_lo:[1,0,0] neg_hi:[1,0,0]
	v_pk_fma_f32 v[86:87], v[144:145], v[68:69], v[86:87] op_sel_hi:[1,0,1] neg_lo:[1,0,0] neg_hi:[1,0,0]
	v_pk_fma_f32 v[86:87], v[146:147], v[68:69], v[86:87] op_sel:[0,1,0] op_sel_hi:[1,1,1] neg_lo:[1,0,0] neg_hi:[1,0,0]
	v_pk_fma_f32 v[88:89], v[148:149], v[68:69], v[88:89] op_sel_hi:[1,0,1] neg_lo:[1,0,0] neg_hi:[1,0,0]
	v_pk_fma_f32 v[88:89], v[150:151], v[68:69], v[88:89] op_sel:[0,1,0] op_sel_hi:[1,1,1] neg_lo:[1,0,0] neg_hi:[1,0,0]
	ds_read_b128 v[120:123], v32 offset:11120
	ds_read_b128 v[124:127], v32 offset:11664
	ds_read_b128 v[128:131], v32 offset:11136
	ds_read_b128 v[132:135], v32 offset:11680
	ds_read_b128 v[144:147], v32 offset:11152
	ds_read_b128 v[148:151], v32 offset:11696
	s_waitcnt lgkmcnt(6)
	v_pk_fma_f32 v[86:87], v[2:3], v[70:71], v[86:87] op_sel_hi:[1,0,1] neg_lo:[1,0,0] neg_hi:[1,0,0]
	v_pk_fma_f32 v[86:87], v[4:5], v[70:71], v[86:87] op_sel:[0,1,0] op_sel_hi:[1,1,1] neg_lo:[1,0,0] neg_hi:[1,0,0]
	v_pk_fma_f32 v[88:89], v[6:7], v[70:71], v[88:89] op_sel_hi:[1,0,1] neg_lo:[1,0,0] neg_hi:[1,0,0]
	v_pk_fma_f32 v[88:89], v[8:9], v[70:71], v[88:89] op_sel:[0,1,0] op_sel_hi:[1,1,1] neg_lo:[1,0,0] neg_hi:[1,0,0]
	v_pk_fma_f32 v[86:87], v[10:11], v[72:73], v[86:87] op_sel_hi:[1,0,1] neg_lo:[1,0,0] neg_hi:[1,0,0]
	v_pk_fma_f32 v[86:87], v[12:13], v[72:73], v[86:87] op_sel:[0,1,0] op_sel_hi:[1,1,1] neg_lo:[1,0,0] neg_hi:[1,0,0]
	v_pk_fma_f32 v[88:89], v[14:15], v[72:73], v[88:89] op_sel_hi:[1,0,1] neg_lo:[1,0,0] neg_hi:[1,0,0]
	v_pk_fma_f32 v[88:89], v[16:17], v[72:73], v[88:89] op_sel:[0,1,0] op_sel_hi:[1,1,1] neg_lo:[1,0,0] neg_hi:[1,0,0]
	v_pk_fma_f32 v[86:87], v[18:19], v[74:75], v[86:87] op_sel_hi:[1,0,1] neg_lo:[1,0,0] neg_hi:[1,0,0]
	v_pk_fma_f32 v[86:87], v[20:21], v[74:75], v[86:87] op_sel:[0,1,0] op_sel_hi:[1,1,1] neg_lo:[1,0,0] neg_hi:[1,0,0]
	v_pk_fma_f32 v[88:89], v[22:23], v[74:75], v[88:89] op_sel_hi:[1,0,1] neg_lo:[1,0,0] neg_hi:[1,0,0]
	v_pk_fma_f32 v[88:89], v[24:25], v[74:75], v[88:89] op_sel:[0,1,0] op_sel_hi:[1,1,1] neg_lo:[1,0,0] neg_hi:[1,0,0]
	ds_read_b128 v[2:5], v32 offset:11168
	ds_read_b128 v[6:9], v32 offset:11712
	ds_read_b128 v[10:13], v32 offset:11184
	ds_read_b128 v[14:17], v32 offset:11728
	ds_read_b128 v[18:21], v32 offset:11200
	ds_read_b128 v[22:25], v32 offset:11744
	s_waitcnt lgkmcnt(6)
	v_pk_fma_f32 v[86:87], v[120:121], v[76:77], v[86:87] op_sel_hi:[1,0,1] neg_lo:[1,0,0] neg_hi:[1,0,0]
	v_pk_fma_f32 v[86:87], v[122:123], v[76:77], v[86:87] op_sel:[0,1,0] op_sel_hi:[1,1,1] neg_lo:[1,0,0] neg_hi:[1,0,0]
	v_pk_fma_f32 v[88:89], v[124:125], v[76:77], v[88:89] op_sel_hi:[1,0,1] neg_lo:[1,0,0] neg_hi:[1,0,0]
	v_pk_fma_f32 v[88:89], v[126:127], v[76:77], v[88:89] op_sel:[0,1,0] op_sel_hi:[1,1,1] neg_lo:[1,0,0] neg_hi:[1,0,0]
	v_pk_fma_f32 v[86:87], v[128:129], v[78:79], v[86:87] op_sel_hi:[1,0,1] neg_lo:[1,0,0] neg_hi:[1,0,0]
	v_pk_fma_f32 v[86:87], v[130:131], v[78:79], v[86:87] op_sel:[0,1,0] op_sel_hi:[1,1,1] neg_lo:[1,0,0] neg_hi:[1,0,0]
	v_pk_fma_f32 v[88:89], v[132:133], v[78:79], v[88:89] op_sel_hi:[1,0,1] neg_lo:[1,0,0] neg_hi:[1,0,0]
	v_pk_fma_f32 v[88:89], v[134:135], v[78:79], v[88:89] op_sel:[0,1,0] op_sel_hi:[1,1,1] neg_lo:[1,0,0] neg_hi:[1,0,0]
	v_pk_fma_f32 v[86:87], v[144:145], v[80:81], v[86:87] op_sel_hi:[1,0,1] neg_lo:[1,0,0] neg_hi:[1,0,0]
	v_pk_fma_f32 v[86:87], v[146:147], v[80:81], v[86:87] op_sel:[0,1,0] op_sel_hi:[1,1,1] neg_lo:[1,0,0] neg_hi:[1,0,0]
	v_pk_fma_f32 v[88:89], v[148:149], v[80:81], v[88:89] op_sel_hi:[1,0,1] neg_lo:[1,0,0] neg_hi:[1,0,0]
	v_pk_fma_f32 v[88:89], v[150:151], v[80:81], v[88:89] op_sel:[0,1,0] op_sel_hi:[1,1,1] neg_lo:[1,0,0] neg_hi:[1,0,0]
	ds_read_b128 v[120:123], v32 offset:11760
	s_waitcnt lgkmcnt(1)
	v_pk_fma_f32 v[86:87], v[2:3], v[82:83], v[86:87] op_sel_hi:[1,0,1] neg_lo:[1,0,0] neg_hi:[1,0,0]
	v_pk_fma_f32 v[86:87], v[4:5], v[82:83], v[86:87] op_sel:[0,1,0] op_sel_hi:[1,1,1] neg_lo:[1,0,0] neg_hi:[1,0,0]
	v_pk_fma_f32 v[88:89], v[6:7], v[82:83], v[88:89] op_sel_hi:[1,0,1] neg_lo:[1,0,0] neg_hi:[1,0,0]
	v_pk_fma_f32 v[88:89], v[8:9], v[82:83], v[88:89] op_sel:[0,1,0] op_sel_hi:[1,1,1] neg_lo:[1,0,0] neg_hi:[1,0,0]
	v_pk_fma_f32 v[86:87], v[10:11], v[84:85], v[86:87] op_sel_hi:[1,0,1] neg_lo:[1,0,0] neg_hi:[1,0,0]
	v_pk_fma_f32 v[86:87], v[12:13], v[84:85], v[86:87] op_sel:[0,1,0] op_sel_hi:[1,1,1] neg_lo:[1,0,0] neg_hi:[1,0,0]
	v_pk_fma_f32 v[88:89], v[14:15], v[84:85], v[88:89] op_sel_hi:[1,0,1] neg_lo:[1,0,0] neg_hi:[1,0,0]
	v_pk_fma_f32 v[88:89], v[16:17], v[84:85], v[88:89] op_sel:[0,1,0] op_sel_hi:[1,1,1] neg_lo:[1,0,0] neg_hi:[1,0,0]
	v_fma_f32 v87, -v19, v86, v87
	v_pk_fma_f32 v[88:89], v[22:23], v[86:87], v[88:89] op_sel_hi:[1,0,1] neg_lo:[1,0,0] neg_hi:[1,0,0]
	v_pk_fma_f32 v[88:89], v[24:25], v[86:87], v[88:89] op_sel:[0,1,0] op_sel_hi:[1,1,1] neg_lo:[1,0,0] neg_hi:[1,0,0]
	ds_read_u16 v26, v30 offset:11968
	ds_read_u16 v27, v30 offset:12240
	ds_read_b64 v[28:29], v31 offset:176
	ds_read_u16 v36, v30 offset:12512
	ds_read_u16 v37, v30 offset:12784
	ds_read_b64 v[38:39], v31 offset:184
	ds_read_b128 v[2:5], v32 offset:11968
	ds_read_b128 v[6:9], v32 offset:12512
	ds_read_b128 v[10:13], v32 offset:11984
	ds_read_b128 v[14:17], v32 offset:12528
	ds_read_b128 v[18:21], v32 offset:12000
	ds_read_b128 v[22:25], v32 offset:12544
	s_waitcnt lgkmcnt(12)
	v_fma_f32 v89, -v121, v88, v89
	ds_read_b128 v[120:123], v32 offset:12016
	ds_read_b128 v[124:127], v32 offset:12560
	ds_read_b128 v[128:131], v32 offset:12032
	ds_read_b128 v[132:135], v32 offset:12576
	ds_read_b128 v[144:147], v32 offset:12048
	ds_read_b128 v[148:151], v32 offset:12592
	s_waitcnt lgkmcnt(6)
	v_lshlrev_b32_e32 v26, 16, v26
	v_lshlrev_b32_e32 v27, 16, v27
	v_pk_mul_f32 v[90:91], v[26:27], v[28:29]
	v_lshlrev_b32_e32 v36, 16, v36
	v_lshlrev_b32_e32 v37, 16, v37
	v_pk_mul_f32 v[92:93], v[36:37], v[38:39]
	v_pk_fma_f32 v[90:91], v[2:3], v[46:47], v[90:91] op_sel_hi:[1,0,1] neg_lo:[1,0,0] neg_hi:[1,0,0]
	v_pk_fma_f32 v[90:91], v[4:5], v[46:47], v[90:91] op_sel:[0,1,0] op_sel_hi:[1,1,1] neg_lo:[1,0,0] neg_hi:[1,0,0]
	v_pk_fma_f32 v[92:93], v[6:7], v[46:47], v[92:93] op_sel_hi:[1,0,1] neg_lo:[1,0,0] neg_hi:[1,0,0]
	v_pk_fma_f32 v[92:93], v[8:9], v[46:47], v[92:93] op_sel:[0,1,0] op_sel_hi:[1,1,1] neg_lo:[1,0,0] neg_hi:[1,0,0]
	v_pk_fma_f32 v[90:91], v[10:11], v[48:49], v[90:91] op_sel_hi:[1,0,1] neg_lo:[1,0,0] neg_hi:[1,0,0]
	v_pk_fma_f32 v[90:91], v[12:13], v[48:49], v[90:91] op_sel:[0,1,0] op_sel_hi:[1,1,1] neg_lo:[1,0,0] neg_hi:[1,0,0]
	v_pk_fma_f32 v[92:93], v[14:15], v[48:49], v[92:93] op_sel_hi:[1,0,1] neg_lo:[1,0,0] neg_hi:[1,0,0]
	v_pk_fma_f32 v[92:93], v[16:17], v[48:49], v[92:93] op_sel:[0,1,0] op_sel_hi:[1,1,1] neg_lo:[1,0,0] neg_hi:[1,0,0]
	v_pk_fma_f32 v[90:91], v[18:19], v[50:51], v[90:91] op_sel_hi:[1,0,1] neg_lo:[1,0,0] neg_hi:[1,0,0]
	v_pk_fma_f32 v[90:91], v[20:21], v[50:51], v[90:91] op_sel:[0,1,0] op_sel_hi:[1,1,1] neg_lo:[1,0,0] neg_hi:[1,0,0]
	v_pk_fma_f32 v[92:93], v[22:23], v[50:51], v[92:93] op_sel_hi:[1,0,1] neg_lo:[1,0,0] neg_hi:[1,0,0]
	v_pk_fma_f32 v[92:93], v[24:25], v[50:51], v[92:93] op_sel:[0,1,0] op_sel_hi:[1,1,1] neg_lo:[1,0,0] neg_hi:[1,0,0]
	ds_read_b128 v[2:5], v32 offset:12064
	ds_read_b128 v[6:9], v32 offset:12608
	ds_read_b128 v[10:13], v32 offset:12080
	ds_read_b128 v[14:17], v32 offset:12624
	ds_read_b128 v[18:21], v32 offset:12096
	ds_read_b128 v[22:25], v32 offset:12640
	s_waitcnt lgkmcnt(6)
	v_pk_fma_f32 v[90:91], v[120:121], v[52:53], v[90:91] op_sel_hi:[1,0,1] neg_lo:[1,0,0] neg_hi:[1,0,0]
	v_pk_fma_f32 v[90:91], v[122:123], v[52:53], v[90:91] op_sel:[0,1,0] op_sel_hi:[1,1,1] neg_lo:[1,0,0] neg_hi:[1,0,0]
	v_pk_fma_f32 v[92:93], v[124:125], v[52:53], v[92:93] op_sel_hi:[1,0,1] neg_lo:[1,0,0] neg_hi:[1,0,0]
	v_pk_fma_f32 v[92:93], v[126:127], v[52:53], v[92:93] op_sel:[0,1,0] op_sel_hi:[1,1,1] neg_lo:[1,0,0] neg_hi:[1,0,0]
	v_pk_fma_f32 v[90:91], v[128:129], v[54:55], v[90:91] op_sel_hi:[1,0,1] neg_lo:[1,0,0] neg_hi:[1,0,0]
	v_pk_fma_f32 v[90:91], v[130:131], v[54:55], v[90:91] op_sel:[0,1,0] op_sel_hi:[1,1,1] neg_lo:[1,0,0] neg_hi:[1,0,0]
	v_pk_fma_f32 v[92:93], v[132:133], v[54:55], v[92:93] op_sel_hi:[1,0,1] neg_lo:[1,0,0] neg_hi:[1,0,0]
	v_pk_fma_f32 v[92:93], v[134:135], v[54:55], v[92:93] op_sel:[0,1,0] op_sel_hi:[1,1,1] neg_lo:[1,0,0] neg_hi:[1,0,0]
	v_pk_fma_f32 v[90:91], v[144:145], v[56:57], v[90:91] op_sel_hi:[1,0,1] neg_lo:[1,0,0] neg_hi:[1,0,0]
	v_pk_fma_f32 v[90:91], v[146:147], v[56:57], v[90:91] op_sel:[0,1,0] op_sel_hi:[1,1,1] neg_lo:[1,0,0] neg_hi:[1,0,0]
	v_pk_fma_f32 v[92:93], v[148:149], v[56:57], v[92:93] op_sel_hi:[1,0,1] neg_lo:[1,0,0] neg_hi:[1,0,0]
	v_pk_fma_f32 v[92:93], v[150:151], v[56:57], v[92:93] op_sel:[0,1,0] op_sel_hi:[1,1,1] neg_lo:[1,0,0] neg_hi:[1,0,0]
	ds_read_b128 v[120:123], v32 offset:12112
	ds_read_b128 v[124:127], v32 offset:12656
	ds_read_b128 v[128:131], v32 offset:12128
	ds_read_b128 v[132:135], v32 offset:12672
	ds_read_b128 v[144:147], v32 offset:12144
	ds_read_b128 v[148:151], v32 offset:12688
	s_waitcnt lgkmcnt(6)
	v_pk_fma_f32 v[90:91], v[2:3], v[58:59], v[90:91] op_sel_hi:[1,0,1] neg_lo:[1,0,0] neg_hi:[1,0,0]
	v_pk_fma_f32 v[90:91], v[4:5], v[58:59], v[90:91] op_sel:[0,1,0] op_sel_hi:[1,1,1] neg_lo:[1,0,0] neg_hi:[1,0,0]
	v_pk_fma_f32 v[92:93], v[6:7], v[58:59], v[92:93] op_sel_hi:[1,0,1] neg_lo:[1,0,0] neg_hi:[1,0,0]
	v_pk_fma_f32 v[92:93], v[8:9], v[58:59], v[92:93] op_sel:[0,1,0] op_sel_hi:[1,1,1] neg_lo:[1,0,0] neg_hi:[1,0,0]
	v_pk_fma_f32 v[90:91], v[10:11], v[60:61], v[90:91] op_sel_hi:[1,0,1] neg_lo:[1,0,0] neg_hi:[1,0,0]
	v_pk_fma_f32 v[90:91], v[12:13], v[60:61], v[90:91] op_sel:[0,1,0] op_sel_hi:[1,1,1] neg_lo:[1,0,0] neg_hi:[1,0,0]
	v_pk_fma_f32 v[92:93], v[14:15], v[60:61], v[92:93] op_sel_hi:[1,0,1] neg_lo:[1,0,0] neg_hi:[1,0,0]
	v_pk_fma_f32 v[92:93], v[16:17], v[60:61], v[92:93] op_sel:[0,1,0] op_sel_hi:[1,1,1] neg_lo:[1,0,0] neg_hi:[1,0,0]
	v_pk_fma_f32 v[90:91], v[18:19], v[62:63], v[90:91] op_sel_hi:[1,0,1] neg_lo:[1,0,0] neg_hi:[1,0,0]
	v_pk_fma_f32 v[90:91], v[20:21], v[62:63], v[90:91] op_sel:[0,1,0] op_sel_hi:[1,1,1] neg_lo:[1,0,0] neg_hi:[1,0,0]
	v_pk_fma_f32 v[92:93], v[22:23], v[62:63], v[92:93] op_sel_hi:[1,0,1] neg_lo:[1,0,0] neg_hi:[1,0,0]
	v_pk_fma_f32 v[92:93], v[24:25], v[62:63], v[92:93] op_sel:[0,1,0] op_sel_hi:[1,1,1] neg_lo:[1,0,0] neg_hi:[1,0,0]
	ds_read_b128 v[2:5], v32 offset:12160
	ds_read_b128 v[6:9], v32 offset:12704
	ds_read_b128 v[10:13], v32 offset:12176
	ds_read_b128 v[14:17], v32 offset:12720
	ds_read_b128 v[18:21], v32 offset:12192
	ds_read_b128 v[22:25], v32 offset:12736
	s_waitcnt lgkmcnt(6)
	v_pk_fma_f32 v[90:91], v[120:121], v[64:65], v[90:91] op_sel_hi:[1,0,1] neg_lo:[1,0,0] neg_hi:[1,0,0]
	v_pk_fma_f32 v[90:91], v[122:123], v[64:65], v[90:91] op_sel:[0,1,0] op_sel_hi:[1,1,1] neg_lo:[1,0,0] neg_hi:[1,0,0]
	v_pk_fma_f32 v[92:93], v[124:125], v[64:65], v[92:93] op_sel_hi:[1,0,1] neg_lo:[1,0,0] neg_hi:[1,0,0]
	v_pk_fma_f32 v[92:93], v[126:127], v[64:65], v[92:93] op_sel:[0,1,0] op_sel_hi:[1,1,1] neg_lo:[1,0,0] neg_hi:[1,0,0]
	v_pk_fma_f32 v[90:91], v[128:129], v[66:67], v[90:91] op_sel_hi:[1,0,1] neg_lo:[1,0,0] neg_hi:[1,0,0]
	v_pk_fma_f32 v[90:91], v[130:131], v[66:67], v[90:91] op_sel:[0,1,0] op_sel_hi:[1,1,1] neg_lo:[1,0,0] neg_hi:[1,0,0]
	v_pk_fma_f32 v[92:93], v[132:133], v[66:67], v[92:93] op_sel_hi:[1,0,1] neg_lo:[1,0,0] neg_hi:[1,0,0]
	v_pk_fma_f32 v[92:93], v[134:135], v[66:67], v[92:93] op_sel:[0,1,0] op_sel_hi:[1,1,1] neg_lo:[1,0,0] neg_hi:[1,0,0]
	v_pk_fma_f32 v[90:91], v[144:145], v[68:69], v[90:91] op_sel_hi:[1,0,1] neg_lo:[1,0,0] neg_hi:[1,0,0]
	v_pk_fma_f32 v[90:91], v[146:147], v[68:69], v[90:91] op_sel:[0,1,0] op_sel_hi:[1,1,1] neg_lo:[1,0,0] neg_hi:[1,0,0]
	v_pk_fma_f32 v[92:93], v[148:149], v[68:69], v[92:93] op_sel_hi:[1,0,1] neg_lo:[1,0,0] neg_hi:[1,0,0]
	v_pk_fma_f32 v[92:93], v[150:151], v[68:69], v[92:93] op_sel:[0,1,0] op_sel_hi:[1,1,1] neg_lo:[1,0,0] neg_hi:[1,0,0]
	ds_read_b128 v[120:123], v32 offset:12208
	ds_read_b128 v[124:127], v32 offset:12752
	ds_read_b128 v[128:131], v32 offset:12224
	ds_read_b128 v[132:135], v32 offset:12768
	ds_read_b128 v[144:147], v32 offset:12240
	ds_read_b128 v[148:151], v32 offset:12784
	s_waitcnt lgkmcnt(6)
	v_pk_fma_f32 v[90:91], v[2:3], v[70:71], v[90:91] op_sel_hi:[1,0,1] neg_lo:[1,0,0] neg_hi:[1,0,0]
	v_pk_fma_f32 v[90:91], v[4:5], v[70:71], v[90:91] op_sel:[0,1,0] op_sel_hi:[1,1,1] neg_lo:[1,0,0] neg_hi:[1,0,0]
	v_pk_fma_f32 v[92:93], v[6:7], v[70:71], v[92:93] op_sel_hi:[1,0,1] neg_lo:[1,0,0] neg_hi:[1,0,0]
	v_pk_fma_f32 v[92:93], v[8:9], v[70:71], v[92:93] op_sel:[0,1,0] op_sel_hi:[1,1,1] neg_lo:[1,0,0] neg_hi:[1,0,0]
	v_pk_fma_f32 v[90:91], v[10:11], v[72:73], v[90:91] op_sel_hi:[1,0,1] neg_lo:[1,0,0] neg_hi:[1,0,0]
	v_pk_fma_f32 v[90:91], v[12:13], v[72:73], v[90:91] op_sel:[0,1,0] op_sel_hi:[1,1,1] neg_lo:[1,0,0] neg_hi:[1,0,0]
	v_pk_fma_f32 v[92:93], v[14:15], v[72:73], v[92:93] op_sel_hi:[1,0,1] neg_lo:[1,0,0] neg_hi:[1,0,0]
	v_pk_fma_f32 v[92:93], v[16:17], v[72:73], v[92:93] op_sel:[0,1,0] op_sel_hi:[1,1,1] neg_lo:[1,0,0] neg_hi:[1,0,0]
	v_pk_fma_f32 v[90:91], v[18:19], v[74:75], v[90:91] op_sel_hi:[1,0,1] neg_lo:[1,0,0] neg_hi:[1,0,0]
	v_pk_fma_f32 v[90:91], v[20:21], v[74:75], v[90:91] op_sel:[0,1,0] op_sel_hi:[1,1,1] neg_lo:[1,0,0] neg_hi:[1,0,0]
	v_pk_fma_f32 v[92:93], v[22:23], v[74:75], v[92:93] op_sel_hi:[1,0,1] neg_lo:[1,0,0] neg_hi:[1,0,0]
	v_pk_fma_f32 v[92:93], v[24:25], v[74:75], v[92:93] op_sel:[0,1,0] op_sel_hi:[1,1,1] neg_lo:[1,0,0] neg_hi:[1,0,0]
	ds_read_b128 v[2:5], v32 offset:12256
	ds_read_b128 v[6:9], v32 offset:12800
	ds_read_b128 v[10:13], v32 offset:12272
	ds_read_b128 v[14:17], v32 offset:12816
	ds_read_b128 v[18:21], v32 offset:12288
	ds_read_b128 v[22:25], v32 offset:12832
	s_waitcnt lgkmcnt(6)
	v_pk_fma_f32 v[90:91], v[120:121], v[76:77], v[90:91] op_sel_hi:[1,0,1] neg_lo:[1,0,0] neg_hi:[1,0,0]
	v_pk_fma_f32 v[90:91], v[122:123], v[76:77], v[90:91] op_sel:[0,1,0] op_sel_hi:[1,1,1] neg_lo:[1,0,0] neg_hi:[1,0,0]
	v_pk_fma_f32 v[92:93], v[124:125], v[76:77], v[92:93] op_sel_hi:[1,0,1] neg_lo:[1,0,0] neg_hi:[1,0,0]
	v_pk_fma_f32 v[92:93], v[126:127], v[76:77], v[92:93] op_sel:[0,1,0] op_sel_hi:[1,1,1] neg_lo:[1,0,0] neg_hi:[1,0,0]
	v_pk_fma_f32 v[90:91], v[128:129], v[78:79], v[90:91] op_sel_hi:[1,0,1] neg_lo:[1,0,0] neg_hi:[1,0,0]
	v_pk_fma_f32 v[90:91], v[130:131], v[78:79], v[90:91] op_sel:[0,1,0] op_sel_hi:[1,1,1] neg_lo:[1,0,0] neg_hi:[1,0,0]
	v_pk_fma_f32 v[92:93], v[132:133], v[78:79], v[92:93] op_sel_hi:[1,0,1] neg_lo:[1,0,0] neg_hi:[1,0,0]
	v_pk_fma_f32 v[92:93], v[134:135], v[78:79], v[92:93] op_sel:[0,1,0] op_sel_hi:[1,1,1] neg_lo:[1,0,0] neg_hi:[1,0,0]
	v_pk_fma_f32 v[90:91], v[144:145], v[80:81], v[90:91] op_sel_hi:[1,0,1] neg_lo:[1,0,0] neg_hi:[1,0,0]
	v_pk_fma_f32 v[90:91], v[146:147], v[80:81], v[90:91] op_sel:[0,1,0] op_sel_hi:[1,1,1] neg_lo:[1,0,0] neg_hi:[1,0,0]
	v_pk_fma_f32 v[92:93], v[148:149], v[80:81], v[92:93] op_sel_hi:[1,0,1] neg_lo:[1,0,0] neg_hi:[1,0,0]
	v_pk_fma_f32 v[92:93], v[150:151], v[80:81], v[92:93] op_sel:[0,1,0] op_sel_hi:[1,1,1] neg_lo:[1,0,0] neg_hi:[1,0,0]
	ds_read_b128 v[120:123], v32 offset:12304
	ds_read_b128 v[124:127], v32 offset:12848
	ds_read_b128 v[128:131], v32 offset:12320
	ds_read_b128 v[132:135], v32 offset:12864
	ds_read_b128 v[144:147], v32 offset:12880
	s_waitcnt lgkmcnt(5)
	v_pk_fma_f32 v[90:91], v[2:3], v[82:83], v[90:91] op_sel_hi:[1,0,1] neg_lo:[1,0,0] neg_hi:[1,0,0]
	v_pk_fma_f32 v[90:91], v[4:5], v[82:83], v[90:91] op_sel:[0,1,0] op_sel_hi:[1,1,1] neg_lo:[1,0,0] neg_hi:[1,0,0]
	v_pk_fma_f32 v[92:93], v[6:7], v[82:83], v[92:93] op_sel_hi:[1,0,1] neg_lo:[1,0,0] neg_hi:[1,0,0]
	v_pk_fma_f32 v[92:93], v[8:9], v[82:83], v[92:93] op_sel:[0,1,0] op_sel_hi:[1,1,1] neg_lo:[1,0,0] neg_hi:[1,0,0]
	v_pk_fma_f32 v[90:91], v[10:11], v[84:85], v[90:91] op_sel_hi:[1,0,1] neg_lo:[1,0,0] neg_hi:[1,0,0]
	v_pk_fma_f32 v[90:91], v[12:13], v[84:85], v[90:91] op_sel:[0,1,0] op_sel_hi:[1,1,1] neg_lo:[1,0,0] neg_hi:[1,0,0]
	v_pk_fma_f32 v[92:93], v[14:15], v[84:85], v[92:93] op_sel_hi:[1,0,1] neg_lo:[1,0,0] neg_hi:[1,0,0]
	v_pk_fma_f32 v[92:93], v[16:17], v[84:85], v[92:93] op_sel:[0,1,0] op_sel_hi:[1,1,1] neg_lo:[1,0,0] neg_hi:[1,0,0]
	v_pk_fma_f32 v[90:91], v[18:19], v[86:87], v[90:91] op_sel_hi:[1,0,1] neg_lo:[1,0,0] neg_hi:[1,0,0]
	v_pk_fma_f32 v[90:91], v[20:21], v[86:87], v[90:91] op_sel:[0,1,0] op_sel_hi:[1,1,1] neg_lo:[1,0,0] neg_hi:[1,0,0]
	v_pk_fma_f32 v[92:93], v[22:23], v[86:87], v[92:93] op_sel_hi:[1,0,1] neg_lo:[1,0,0] neg_hi:[1,0,0]
	v_pk_fma_f32 v[92:93], v[24:25], v[86:87], v[92:93] op_sel:[0,1,0] op_sel_hi:[1,1,1] neg_lo:[1,0,0] neg_hi:[1,0,0]
	ds_read_u16 v26, v30 offset:13056
	ds_read_u16 v27, v30 offset:13328
	ds_read_b64 v[28:29], v31 offset:192
	ds_read_u16 v36, v30 offset:13600
	ds_read_u16 v37, v30 offset:13872
	ds_read_b64 v[38:39], v31 offset:200
	ds_read_b128 v[2:5], v32 offset:13056
	ds_read_b128 v[6:9], v32 offset:13600
	ds_read_b128 v[10:13], v32 offset:13072
	ds_read_b128 v[14:17], v32 offset:13616
	ds_read_b128 v[18:21], v32 offset:13088
	ds_read_b128 v[22:25], v32 offset:13632
	s_waitcnt lgkmcnt(12)
	v_pk_fma_f32 v[90:91], v[120:121], v[88:89], v[90:91] op_sel_hi:[1,0,1] neg_lo:[1,0,0] neg_hi:[1,0,0]
	v_pk_fma_f32 v[90:91], v[122:123], v[88:89], v[90:91] op_sel:[0,1,0] op_sel_hi:[1,1,1] neg_lo:[1,0,0] neg_hi:[1,0,0]
	v_pk_fma_f32 v[92:93], v[124:125], v[88:89], v[92:93] op_sel_hi:[1,0,1] neg_lo:[1,0,0] neg_hi:[1,0,0]
	v_pk_fma_f32 v[92:93], v[126:127], v[88:89], v[92:93] op_sel:[0,1,0] op_sel_hi:[1,1,1] neg_lo:[1,0,0] neg_hi:[1,0,0]
	v_fma_f32 v91, -v129, v90, v91
	v_pk_fma_f32 v[92:93], v[132:133], v[90:91], v[92:93] op_sel_hi:[1,0,1] neg_lo:[1,0,0] neg_hi:[1,0,0]
	v_pk_fma_f32 v[92:93], v[134:135], v[90:91], v[92:93] op_sel:[0,1,0] op_sel_hi:[1,1,1] neg_lo:[1,0,0] neg_hi:[1,0,0]
	v_fma_f32 v93, -v145, v92, v93
	ds_read_b128 v[120:123], v32 offset:13104
	ds_read_b128 v[124:127], v32 offset:13648
	ds_read_b128 v[128:131], v32 offset:13120
	ds_read_b128 v[132:135], v32 offset:13664
	ds_read_b128 v[144:147], v32 offset:13136
	ds_read_b128 v[148:151], v32 offset:13680
	s_waitcnt lgkmcnt(6)
	v_lshlrev_b32_e32 v26, 16, v26
	v_lshlrev_b32_e32 v27, 16, v27
	v_pk_mul_f32 v[94:95], v[26:27], v[28:29]
	v_lshlrev_b32_e32 v36, 16, v36
	v_lshlrev_b32_e32 v37, 16, v37
	v_pk_mul_f32 v[96:97], v[36:37], v[38:39]
	v_pk_fma_f32 v[94:95], v[2:3], v[46:47], v[94:95] op_sel_hi:[1,0,1] neg_lo:[1,0,0] neg_hi:[1,0,0]
	v_pk_fma_f32 v[94:95], v[4:5], v[46:47], v[94:95] op_sel:[0,1,0] op_sel_hi:[1,1,1] neg_lo:[1,0,0] neg_hi:[1,0,0]
	v_pk_fma_f32 v[96:97], v[6:7], v[46:47], v[96:97] op_sel_hi:[1,0,1] neg_lo:[1,0,0] neg_hi:[1,0,0]
	v_pk_fma_f32 v[96:97], v[8:9], v[46:47], v[96:97] op_sel:[0,1,0] op_sel_hi:[1,1,1] neg_lo:[1,0,0] neg_hi:[1,0,0]
	v_pk_fma_f32 v[94:95], v[10:11], v[48:49], v[94:95] op_sel_hi:[1,0,1] neg_lo:[1,0,0] neg_hi:[1,0,0]
	v_pk_fma_f32 v[94:95], v[12:13], v[48:49], v[94:95] op_sel:[0,1,0] op_sel_hi:[1,1,1] neg_lo:[1,0,0] neg_hi:[1,0,0]
	v_pk_fma_f32 v[96:97], v[14:15], v[48:49], v[96:97] op_sel_hi:[1,0,1] neg_lo:[1,0,0] neg_hi:[1,0,0]
	v_pk_fma_f32 v[96:97], v[16:17], v[48:49], v[96:97] op_sel:[0,1,0] op_sel_hi:[1,1,1] neg_lo:[1,0,0] neg_hi:[1,0,0]
	v_pk_fma_f32 v[94:95], v[18:19], v[50:51], v[94:95] op_sel_hi:[1,0,1] neg_lo:[1,0,0] neg_hi:[1,0,0]
	v_pk_fma_f32 v[94:95], v[20:21], v[50:51], v[94:95] op_sel:[0,1,0] op_sel_hi:[1,1,1] neg_lo:[1,0,0] neg_hi:[1,0,0]
	v_pk_fma_f32 v[96:97], v[22:23], v[50:51], v[96:97] op_sel_hi:[1,0,1] neg_lo:[1,0,0] neg_hi:[1,0,0]
	v_pk_fma_f32 v[96:97], v[24:25], v[50:51], v[96:97] op_sel:[0,1,0] op_sel_hi:[1,1,1] neg_lo:[1,0,0] neg_hi:[1,0,0]
	ds_read_b128 v[2:5], v32 offset:13152
	ds_read_b128 v[6:9], v32 offset:13696
	ds_read_b128 v[10:13], v32 offset:13168
	ds_read_b128 v[14:17], v32 offset:13712
	ds_read_b128 v[18:21], v32 offset:13184
	ds_read_b128 v[22:25], v32 offset:13728
	s_waitcnt lgkmcnt(6)
	v_pk_fma_f32 v[94:95], v[120:121], v[52:53], v[94:95] op_sel_hi:[1,0,1] neg_lo:[1,0,0] neg_hi:[1,0,0]
	v_pk_fma_f32 v[94:95], v[122:123], v[52:53], v[94:95] op_sel:[0,1,0] op_sel_hi:[1,1,1] neg_lo:[1,0,0] neg_hi:[1,0,0]
	v_pk_fma_f32 v[96:97], v[124:125], v[52:53], v[96:97] op_sel_hi:[1,0,1] neg_lo:[1,0,0] neg_hi:[1,0,0]
	v_pk_fma_f32 v[96:97], v[126:127], v[52:53], v[96:97] op_sel:[0,1,0] op_sel_hi:[1,1,1] neg_lo:[1,0,0] neg_hi:[1,0,0]
	v_pk_fma_f32 v[94:95], v[128:129], v[54:55], v[94:95] op_sel_hi:[1,0,1] neg_lo:[1,0,0] neg_hi:[1,0,0]
	v_pk_fma_f32 v[94:95], v[130:131], v[54:55], v[94:95] op_sel:[0,1,0] op_sel_hi:[1,1,1] neg_lo:[1,0,0] neg_hi:[1,0,0]
	v_pk_fma_f32 v[96:97], v[132:133], v[54:55], v[96:97] op_sel_hi:[1,0,1] neg_lo:[1,0,0] neg_hi:[1,0,0]
	v_pk_fma_f32 v[96:97], v[134:135], v[54:55], v[96:97] op_sel:[0,1,0] op_sel_hi:[1,1,1] neg_lo:[1,0,0] neg_hi:[1,0,0]
	v_pk_fma_f32 v[94:95], v[144:145], v[56:57], v[94:95] op_sel_hi:[1,0,1] neg_lo:[1,0,0] neg_hi:[1,0,0]
	v_pk_fma_f32 v[94:95], v[146:147], v[56:57], v[94:95] op_sel:[0,1,0] op_sel_hi:[1,1,1] neg_lo:[1,0,0] neg_hi:[1,0,0]
	v_pk_fma_f32 v[96:97], v[148:149], v[56:57], v[96:97] op_sel_hi:[1,0,1] neg_lo:[1,0,0] neg_hi:[1,0,0]
	v_pk_fma_f32 v[96:97], v[150:151], v[56:57], v[96:97] op_sel:[0,1,0] op_sel_hi:[1,1,1] neg_lo:[1,0,0] neg_hi:[1,0,0]
	ds_read_b128 v[120:123], v32 offset:13200
	ds_read_b128 v[124:127], v32 offset:13744
	ds_read_b128 v[128:131], v32 offset:13216
	ds_read_b128 v[132:135], v32 offset:13760
	ds_read_b128 v[144:147], v32 offset:13232
	ds_read_b128 v[148:151], v32 offset:13776
	s_waitcnt lgkmcnt(6)
	v_pk_fma_f32 v[94:95], v[2:3], v[58:59], v[94:95] op_sel_hi:[1,0,1] neg_lo:[1,0,0] neg_hi:[1,0,0]
	v_pk_fma_f32 v[94:95], v[4:5], v[58:59], v[94:95] op_sel:[0,1,0] op_sel_hi:[1,1,1] neg_lo:[1,0,0] neg_hi:[1,0,0]
	v_pk_fma_f32 v[96:97], v[6:7], v[58:59], v[96:97] op_sel_hi:[1,0,1] neg_lo:[1,0,0] neg_hi:[1,0,0]
	v_pk_fma_f32 v[96:97], v[8:9], v[58:59], v[96:97] op_sel:[0,1,0] op_sel_hi:[1,1,1] neg_lo:[1,0,0] neg_hi:[1,0,0]
	v_pk_fma_f32 v[94:95], v[10:11], v[60:61], v[94:95] op_sel_hi:[1,0,1] neg_lo:[1,0,0] neg_hi:[1,0,0]
	v_pk_fma_f32 v[94:95], v[12:13], v[60:61], v[94:95] op_sel:[0,1,0] op_sel_hi:[1,1,1] neg_lo:[1,0,0] neg_hi:[1,0,0]
	v_pk_fma_f32 v[96:97], v[14:15], v[60:61], v[96:97] op_sel_hi:[1,0,1] neg_lo:[1,0,0] neg_hi:[1,0,0]
	v_pk_fma_f32 v[96:97], v[16:17], v[60:61], v[96:97] op_sel:[0,1,0] op_sel_hi:[1,1,1] neg_lo:[1,0,0] neg_hi:[1,0,0]
	v_pk_fma_f32 v[94:95], v[18:19], v[62:63], v[94:95] op_sel_hi:[1,0,1] neg_lo:[1,0,0] neg_hi:[1,0,0]
	v_pk_fma_f32 v[94:95], v[20:21], v[62:63], v[94:95] op_sel:[0,1,0] op_sel_hi:[1,1,1] neg_lo:[1,0,0] neg_hi:[1,0,0]
	v_pk_fma_f32 v[96:97], v[22:23], v[62:63], v[96:97] op_sel_hi:[1,0,1] neg_lo:[1,0,0] neg_hi:[1,0,0]
	v_pk_fma_f32 v[96:97], v[24:25], v[62:63], v[96:97] op_sel:[0,1,0] op_sel_hi:[1,1,1] neg_lo:[1,0,0] neg_hi:[1,0,0]
	ds_read_b128 v[2:5], v32 offset:13248
	ds_read_b128 v[6:9], v32 offset:13792
	ds_read_b128 v[10:13], v32 offset:13264
	ds_read_b128 v[14:17], v32 offset:13808
	ds_read_b128 v[18:21], v32 offset:13280
	ds_read_b128 v[22:25], v32 offset:13824
	s_waitcnt lgkmcnt(6)
	v_pk_fma_f32 v[94:95], v[120:121], v[64:65], v[94:95] op_sel_hi:[1,0,1] neg_lo:[1,0,0] neg_hi:[1,0,0]
	v_pk_fma_f32 v[94:95], v[122:123], v[64:65], v[94:95] op_sel:[0,1,0] op_sel_hi:[1,1,1] neg_lo:[1,0,0] neg_hi:[1,0,0]
	v_pk_fma_f32 v[96:97], v[124:125], v[64:65], v[96:97] op_sel_hi:[1,0,1] neg_lo:[1,0,0] neg_hi:[1,0,0]
	v_pk_fma_f32 v[96:97], v[126:127], v[64:65], v[96:97] op_sel:[0,1,0] op_sel_hi:[1,1,1] neg_lo:[1,0,0] neg_hi:[1,0,0]
	v_pk_fma_f32 v[94:95], v[128:129], v[66:67], v[94:95] op_sel_hi:[1,0,1] neg_lo:[1,0,0] neg_hi:[1,0,0]
	v_pk_fma_f32 v[94:95], v[130:131], v[66:67], v[94:95] op_sel:[0,1,0] op_sel_hi:[1,1,1] neg_lo:[1,0,0] neg_hi:[1,0,0]
	v_pk_fma_f32 v[96:97], v[132:133], v[66:67], v[96:97] op_sel_hi:[1,0,1] neg_lo:[1,0,0] neg_hi:[1,0,0]
	v_pk_fma_f32 v[96:97], v[134:135], v[66:67], v[96:97] op_sel:[0,1,0] op_sel_hi:[1,1,1] neg_lo:[1,0,0] neg_hi:[1,0,0]
	v_pk_fma_f32 v[94:95], v[144:145], v[68:69], v[94:95] op_sel_hi:[1,0,1] neg_lo:[1,0,0] neg_hi:[1,0,0]
	v_pk_fma_f32 v[94:95], v[146:147], v[68:69], v[94:95] op_sel:[0,1,0] op_sel_hi:[1,1,1] neg_lo:[1,0,0] neg_hi:[1,0,0]
	v_pk_fma_f32 v[96:97], v[148:149], v[68:69], v[96:97] op_sel_hi:[1,0,1] neg_lo:[1,0,0] neg_hi:[1,0,0]
	v_pk_fma_f32 v[96:97], v[150:151], v[68:69], v[96:97] op_sel:[0,1,0] op_sel_hi:[1,1,1] neg_lo:[1,0,0] neg_hi:[1,0,0]
	ds_read_b128 v[120:123], v32 offset:13296
	ds_read_b128 v[124:127], v32 offset:13840
	ds_read_b128 v[128:131], v32 offset:13312
	ds_read_b128 v[132:135], v32 offset:13856
	ds_read_b128 v[144:147], v32 offset:13328
	ds_read_b128 v[148:151], v32 offset:13872
	s_waitcnt lgkmcnt(6)
	v_pk_fma_f32 v[94:95], v[2:3], v[70:71], v[94:95] op_sel_hi:[1,0,1] neg_lo:[1,0,0] neg_hi:[1,0,0]
	v_pk_fma_f32 v[94:95], v[4:5], v[70:71], v[94:95] op_sel:[0,1,0] op_sel_hi:[1,1,1] neg_lo:[1,0,0] neg_hi:[1,0,0]
	v_pk_fma_f32 v[96:97], v[6:7], v[70:71], v[96:97] op_sel_hi:[1,0,1] neg_lo:[1,0,0] neg_hi:[1,0,0]
	v_pk_fma_f32 v[96:97], v[8:9], v[70:71], v[96:97] op_sel:[0,1,0] op_sel_hi:[1,1,1] neg_lo:[1,0,0] neg_hi:[1,0,0]
	v_pk_fma_f32 v[94:95], v[10:11], v[72:73], v[94:95] op_sel_hi:[1,0,1] neg_lo:[1,0,0] neg_hi:[1,0,0]
	v_pk_fma_f32 v[94:95], v[12:13], v[72:73], v[94:95] op_sel:[0,1,0] op_sel_hi:[1,1,1] neg_lo:[1,0,0] neg_hi:[1,0,0]
	v_pk_fma_f32 v[96:97], v[14:15], v[72:73], v[96:97] op_sel_hi:[1,0,1] neg_lo:[1,0,0] neg_hi:[1,0,0]
	v_pk_fma_f32 v[96:97], v[16:17], v[72:73], v[96:97] op_sel:[0,1,0] op_sel_hi:[1,1,1] neg_lo:[1,0,0] neg_hi:[1,0,0]
	v_pk_fma_f32 v[94:95], v[18:19], v[74:75], v[94:95] op_sel_hi:[1,0,1] neg_lo:[1,0,0] neg_hi:[1,0,0]
	v_pk_fma_f32 v[94:95], v[20:21], v[74:75], v[94:95] op_sel:[0,1,0] op_sel_hi:[1,1,1] neg_lo:[1,0,0] neg_hi:[1,0,0]
	v_pk_fma_f32 v[96:97], v[22:23], v[74:75], v[96:97] op_sel_hi:[1,0,1] neg_lo:[1,0,0] neg_hi:[1,0,0]
	v_pk_fma_f32 v[96:97], v[24:25], v[74:75], v[96:97] op_sel:[0,1,0] op_sel_hi:[1,1,1] neg_lo:[1,0,0] neg_hi:[1,0,0]
	ds_read_b128 v[2:5], v32 offset:13344
	ds_read_b128 v[6:9], v32 offset:13888
	ds_read_b128 v[10:13], v32 offset:13360
	ds_read_b128 v[14:17], v32 offset:13904
	ds_read_b128 v[18:21], v32 offset:13376
	ds_read_b128 v[22:25], v32 offset:13920
	s_waitcnt lgkmcnt(6)
	v_pk_fma_f32 v[94:95], v[120:121], v[76:77], v[94:95] op_sel_hi:[1,0,1] neg_lo:[1,0,0] neg_hi:[1,0,0]
	v_pk_fma_f32 v[94:95], v[122:123], v[76:77], v[94:95] op_sel:[0,1,0] op_sel_hi:[1,1,1] neg_lo:[1,0,0] neg_hi:[1,0,0]
	v_pk_fma_f32 v[96:97], v[124:125], v[76:77], v[96:97] op_sel_hi:[1,0,1] neg_lo:[1,0,0] neg_hi:[1,0,0]
	v_pk_fma_f32 v[96:97], v[126:127], v[76:77], v[96:97] op_sel:[0,1,0] op_sel_hi:[1,1,1] neg_lo:[1,0,0] neg_hi:[1,0,0]
	v_pk_fma_f32 v[94:95], v[128:129], v[78:79], v[94:95] op_sel_hi:[1,0,1] neg_lo:[1,0,0] neg_hi:[1,0,0]
	v_pk_fma_f32 v[94:95], v[130:131], v[78:79], v[94:95] op_sel:[0,1,0] op_sel_hi:[1,1,1] neg_lo:[1,0,0] neg_hi:[1,0,0]
	v_pk_fma_f32 v[96:97], v[132:133], v[78:79], v[96:97] op_sel_hi:[1,0,1] neg_lo:[1,0,0] neg_hi:[1,0,0]
	v_pk_fma_f32 v[96:97], v[134:135], v[78:79], v[96:97] op_sel:[0,1,0] op_sel_hi:[1,1,1] neg_lo:[1,0,0] neg_hi:[1,0,0]
	v_pk_fma_f32 v[94:95], v[144:145], v[80:81], v[94:95] op_sel_hi:[1,0,1] neg_lo:[1,0,0] neg_hi:[1,0,0]
	v_pk_fma_f32 v[94:95], v[146:147], v[80:81], v[94:95] op_sel:[0,1,0] op_sel_hi:[1,1,1] neg_lo:[1,0,0] neg_hi:[1,0,0]
	v_pk_fma_f32 v[96:97], v[148:149], v[80:81], v[96:97] op_sel_hi:[1,0,1] neg_lo:[1,0,0] neg_hi:[1,0,0]
	v_pk_fma_f32 v[96:97], v[150:151], v[80:81], v[96:97] op_sel:[0,1,0] op_sel_hi:[1,1,1] neg_lo:[1,0,0] neg_hi:[1,0,0]
	ds_read_b128 v[120:123], v32 offset:13392
	ds_read_b128 v[124:127], v32 offset:13936
	ds_read_b128 v[128:131], v32 offset:13408
	ds_read_b128 v[132:135], v32 offset:13952
	ds_read_b128 v[144:147], v32 offset:13424
	ds_read_b128 v[148:151], v32 offset:13968
	s_waitcnt lgkmcnt(6)
	v_pk_fma_f32 v[94:95], v[2:3], v[82:83], v[94:95] op_sel_hi:[1,0,1] neg_lo:[1,0,0] neg_hi:[1,0,0]
	v_pk_fma_f32 v[94:95], v[4:5], v[82:83], v[94:95] op_sel:[0,1,0] op_sel_hi:[1,1,1] neg_lo:[1,0,0] neg_hi:[1,0,0]
	v_pk_fma_f32 v[96:97], v[6:7], v[82:83], v[96:97] op_sel_hi:[1,0,1] neg_lo:[1,0,0] neg_hi:[1,0,0]
	v_pk_fma_f32 v[96:97], v[8:9], v[82:83], v[96:97] op_sel:[0,1,0] op_sel_hi:[1,1,1] neg_lo:[1,0,0] neg_hi:[1,0,0]
	v_pk_fma_f32 v[94:95], v[10:11], v[84:85], v[94:95] op_sel_hi:[1,0,1] neg_lo:[1,0,0] neg_hi:[1,0,0]
	v_pk_fma_f32 v[94:95], v[12:13], v[84:85], v[94:95] op_sel:[0,1,0] op_sel_hi:[1,1,1] neg_lo:[1,0,0] neg_hi:[1,0,0]
	v_pk_fma_f32 v[96:97], v[14:15], v[84:85], v[96:97] op_sel_hi:[1,0,1] neg_lo:[1,0,0] neg_hi:[1,0,0]
	v_pk_fma_f32 v[96:97], v[16:17], v[84:85], v[96:97] op_sel:[0,1,0] op_sel_hi:[1,1,1] neg_lo:[1,0,0] neg_hi:[1,0,0]
	v_pk_fma_f32 v[94:95], v[18:19], v[86:87], v[94:95] op_sel_hi:[1,0,1] neg_lo:[1,0,0] neg_hi:[1,0,0]
	v_pk_fma_f32 v[94:95], v[20:21], v[86:87], v[94:95] op_sel:[0,1,0] op_sel_hi:[1,1,1] neg_lo:[1,0,0] neg_hi:[1,0,0]
	v_pk_fma_f32 v[96:97], v[22:23], v[86:87], v[96:97] op_sel_hi:[1,0,1] neg_lo:[1,0,0] neg_hi:[1,0,0]
	v_pk_fma_f32 v[96:97], v[24:25], v[86:87], v[96:97] op_sel:[0,1,0] op_sel_hi:[1,1,1] neg_lo:[1,0,0] neg_hi:[1,0,0]
	ds_read_b128 v[2:5], v32 offset:13440
	ds_read_b128 v[6:9], v32 offset:13984
	ds_read_b128 v[10:13], v32 offset:14000
	s_waitcnt lgkmcnt(3)
	v_pk_fma_f32 v[94:95], v[120:121], v[88:89], v[94:95] op_sel_hi:[1,0,1] neg_lo:[1,0,0] neg_hi:[1,0,0]
	v_pk_fma_f32 v[94:95], v[122:123], v[88:89], v[94:95] op_sel:[0,1,0] op_sel_hi:[1,1,1] neg_lo:[1,0,0] neg_hi:[1,0,0]
	v_pk_fma_f32 v[96:97], v[124:125], v[88:89], v[96:97] op_sel_hi:[1,0,1] neg_lo:[1,0,0] neg_hi:[1,0,0]
	v_pk_fma_f32 v[96:97], v[126:127], v[88:89], v[96:97] op_sel:[0,1,0] op_sel_hi:[1,1,1] neg_lo:[1,0,0] neg_hi:[1,0,0]
	v_pk_fma_f32 v[94:95], v[128:129], v[90:91], v[94:95] op_sel_hi:[1,0,1] neg_lo:[1,0,0] neg_hi:[1,0,0]
	v_pk_fma_f32 v[94:95], v[130:131], v[90:91], v[94:95] op_sel:[0,1,0] op_sel_hi:[1,1,1] neg_lo:[1,0,0] neg_hi:[1,0,0]
	v_pk_fma_f32 v[96:97], v[132:133], v[90:91], v[96:97] op_sel_hi:[1,0,1] neg_lo:[1,0,0] neg_hi:[1,0,0]
	v_pk_fma_f32 v[96:97], v[134:135], v[90:91], v[96:97] op_sel:[0,1,0] op_sel_hi:[1,1,1] neg_lo:[1,0,0] neg_hi:[1,0,0]
	v_pk_fma_f32 v[94:95], v[144:145], v[92:93], v[94:95] op_sel_hi:[1,0,1] neg_lo:[1,0,0] neg_hi:[1,0,0]
	v_pk_fma_f32 v[94:95], v[146:147], v[92:93], v[94:95] op_sel:[0,1,0] op_sel_hi:[1,1,1] neg_lo:[1,0,0] neg_hi:[1,0,0]
	v_pk_fma_f32 v[96:97], v[148:149], v[92:93], v[96:97] op_sel_hi:[1,0,1] neg_lo:[1,0,0] neg_hi:[1,0,0]
	v_pk_fma_f32 v[96:97], v[150:151], v[92:93], v[96:97] op_sel:[0,1,0] op_sel_hi:[1,1,1] neg_lo:[1,0,0] neg_hi:[1,0,0]
	ds_read_u16 v152, v30 offset:14144
	ds_read_u16 v153, v30 offset:14416
	ds_read_b64 v[154:155], v31 offset:208
	ds_read_u16 v156, v30 offset:14688
	ds_read_u16 v157, v30 offset:14960
	ds_read_b64 v[158:159], v31 offset:216
	ds_read_b128 v[120:123], v32 offset:14144
	ds_read_b128 v[124:127], v32 offset:14688
	ds_read_b128 v[128:131], v32 offset:14160
	ds_read_b128 v[132:135], v32 offset:14704
	ds_read_b128 v[144:147], v32 offset:14176
	ds_read_b128 v[148:151], v32 offset:14720
	s_waitcnt lgkmcnt(12)
	v_fma_f32 v95, -v3, v94, v95
	v_pk_fma_f32 v[96:97], v[6:7], v[94:95], v[96:97] op_sel_hi:[1,0,1] neg_lo:[1,0,0] neg_hi:[1,0,0]
	v_pk_fma_f32 v[96:97], v[8:9], v[94:95], v[96:97] op_sel:[0,1,0] op_sel_hi:[1,1,1] neg_lo:[1,0,0] neg_hi:[1,0,0]
	v_fma_f32 v97, -v11, v96, v97
	ds_read_b128 v[2:5], v32 offset:14192
	ds_read_b128 v[6:9], v32 offset:14736
	ds_read_b128 v[10:13], v32 offset:14208
	ds_read_b128 v[14:17], v32 offset:14752
	ds_read_b128 v[18:21], v32 offset:14224
	ds_read_b128 v[22:25], v32 offset:14768
	s_waitcnt lgkmcnt(6)
	v_lshlrev_b32_e32 v152, 16, v152
	v_lshlrev_b32_e32 v153, 16, v153
	v_pk_mul_f32 v[106:107], v[152:153], v[154:155]
	v_lshlrev_b32_e32 v156, 16, v156
	v_lshlrev_b32_e32 v157, 16, v157
	v_pk_mul_f32 v[108:109], v[156:157], v[158:159]
	v_pk_fma_f32 v[106:107], v[120:121], v[46:47], v[106:107] op_sel_hi:[1,0,1] neg_lo:[1,0,0] neg_hi:[1,0,0]
	v_pk_fma_f32 v[106:107], v[122:123], v[46:47], v[106:107] op_sel:[0,1,0] op_sel_hi:[1,1,1] neg_lo:[1,0,0] neg_hi:[1,0,0]
	v_pk_fma_f32 v[108:109], v[124:125], v[46:47], v[108:109] op_sel_hi:[1,0,1] neg_lo:[1,0,0] neg_hi:[1,0,0]
	v_pk_fma_f32 v[108:109], v[126:127], v[46:47], v[108:109] op_sel:[0,1,0] op_sel_hi:[1,1,1] neg_lo:[1,0,0] neg_hi:[1,0,0]
	v_pk_fma_f32 v[106:107], v[128:129], v[48:49], v[106:107] op_sel_hi:[1,0,1] neg_lo:[1,0,0] neg_hi:[1,0,0]
	v_pk_fma_f32 v[106:107], v[130:131], v[48:49], v[106:107] op_sel:[0,1,0] op_sel_hi:[1,1,1] neg_lo:[1,0,0] neg_hi:[1,0,0]
	v_pk_fma_f32 v[108:109], v[132:133], v[48:49], v[108:109] op_sel_hi:[1,0,1] neg_lo:[1,0,0] neg_hi:[1,0,0]
	v_pk_fma_f32 v[108:109], v[134:135], v[48:49], v[108:109] op_sel:[0,1,0] op_sel_hi:[1,1,1] neg_lo:[1,0,0] neg_hi:[1,0,0]
	v_pk_fma_f32 v[106:107], v[144:145], v[50:51], v[106:107] op_sel_hi:[1,0,1] neg_lo:[1,0,0] neg_hi:[1,0,0]
	v_pk_fma_f32 v[106:107], v[146:147], v[50:51], v[106:107] op_sel:[0,1,0] op_sel_hi:[1,1,1] neg_lo:[1,0,0] neg_hi:[1,0,0]
	v_pk_fma_f32 v[108:109], v[148:149], v[50:51], v[108:109] op_sel_hi:[1,0,1] neg_lo:[1,0,0] neg_hi:[1,0,0]
	v_pk_fma_f32 v[108:109], v[150:151], v[50:51], v[108:109] op_sel:[0,1,0] op_sel_hi:[1,1,1] neg_lo:[1,0,0] neg_hi:[1,0,0]
	ds_read_b128 v[120:123], v32 offset:14240
	ds_read_b128 v[124:127], v32 offset:14784
	ds_read_b128 v[128:131], v32 offset:14256
	ds_read_b128 v[132:135], v32 offset:14800
	ds_read_b128 v[144:147], v32 offset:14272
	ds_read_b128 v[148:151], v32 offset:14816
	s_waitcnt lgkmcnt(6)
	v_pk_fma_f32 v[106:107], v[2:3], v[52:53], v[106:107] op_sel_hi:[1,0,1] neg_lo:[1,0,0] neg_hi:[1,0,0]
	v_pk_fma_f32 v[106:107], v[4:5], v[52:53], v[106:107] op_sel:[0,1,0] op_sel_hi:[1,1,1] neg_lo:[1,0,0] neg_hi:[1,0,0]
	v_pk_fma_f32 v[108:109], v[6:7], v[52:53], v[108:109] op_sel_hi:[1,0,1] neg_lo:[1,0,0] neg_hi:[1,0,0]
	v_pk_fma_f32 v[108:109], v[8:9], v[52:53], v[108:109] op_sel:[0,1,0] op_sel_hi:[1,1,1] neg_lo:[1,0,0] neg_hi:[1,0,0]
	v_pk_fma_f32 v[106:107], v[10:11], v[54:55], v[106:107] op_sel_hi:[1,0,1] neg_lo:[1,0,0] neg_hi:[1,0,0]
	v_pk_fma_f32 v[106:107], v[12:13], v[54:55], v[106:107] op_sel:[0,1,0] op_sel_hi:[1,1,1] neg_lo:[1,0,0] neg_hi:[1,0,0]
	v_pk_fma_f32 v[108:109], v[14:15], v[54:55], v[108:109] op_sel_hi:[1,0,1] neg_lo:[1,0,0] neg_hi:[1,0,0]
	v_pk_fma_f32 v[108:109], v[16:17], v[54:55], v[108:109] op_sel:[0,1,0] op_sel_hi:[1,1,1] neg_lo:[1,0,0] neg_hi:[1,0,0]
	v_pk_fma_f32 v[106:107], v[18:19], v[56:57], v[106:107] op_sel_hi:[1,0,1] neg_lo:[1,0,0] neg_hi:[1,0,0]
	v_pk_fma_f32 v[106:107], v[20:21], v[56:57], v[106:107] op_sel:[0,1,0] op_sel_hi:[1,1,1] neg_lo:[1,0,0] neg_hi:[1,0,0]
	v_pk_fma_f32 v[108:109], v[22:23], v[56:57], v[108:109] op_sel_hi:[1,0,1] neg_lo:[1,0,0] neg_hi:[1,0,0]
	v_pk_fma_f32 v[108:109], v[24:25], v[56:57], v[108:109] op_sel:[0,1,0] op_sel_hi:[1,1,1] neg_lo:[1,0,0] neg_hi:[1,0,0]
	ds_read_b128 v[2:5], v32 offset:14288
	ds_read_b128 v[6:9], v32 offset:14832
	ds_read_b128 v[10:13], v32 offset:14304
	ds_read_b128 v[14:17], v32 offset:14848
	ds_read_b128 v[18:21], v32 offset:14320
	ds_read_b128 v[22:25], v32 offset:14864
	s_waitcnt lgkmcnt(6)
	v_pk_fma_f32 v[106:107], v[120:121], v[58:59], v[106:107] op_sel_hi:[1,0,1] neg_lo:[1,0,0] neg_hi:[1,0,0]
	v_pk_fma_f32 v[106:107], v[122:123], v[58:59], v[106:107] op_sel:[0,1,0] op_sel_hi:[1,1,1] neg_lo:[1,0,0] neg_hi:[1,0,0]
	v_pk_fma_f32 v[108:109], v[124:125], v[58:59], v[108:109] op_sel_hi:[1,0,1] neg_lo:[1,0,0] neg_hi:[1,0,0]
	v_pk_fma_f32 v[108:109], v[126:127], v[58:59], v[108:109] op_sel:[0,1,0] op_sel_hi:[1,1,1] neg_lo:[1,0,0] neg_hi:[1,0,0]
	v_pk_fma_f32 v[106:107], v[128:129], v[60:61], v[106:107] op_sel_hi:[1,0,1] neg_lo:[1,0,0] neg_hi:[1,0,0]
	v_pk_fma_f32 v[106:107], v[130:131], v[60:61], v[106:107] op_sel:[0,1,0] op_sel_hi:[1,1,1] neg_lo:[1,0,0] neg_hi:[1,0,0]
	v_pk_fma_f32 v[108:109], v[132:133], v[60:61], v[108:109] op_sel_hi:[1,0,1] neg_lo:[1,0,0] neg_hi:[1,0,0]
	v_pk_fma_f32 v[108:109], v[134:135], v[60:61], v[108:109] op_sel:[0,1,0] op_sel_hi:[1,1,1] neg_lo:[1,0,0] neg_hi:[1,0,0]
	v_pk_fma_f32 v[106:107], v[144:145], v[62:63], v[106:107] op_sel_hi:[1,0,1] neg_lo:[1,0,0] neg_hi:[1,0,0]
	v_pk_fma_f32 v[106:107], v[146:147], v[62:63], v[106:107] op_sel:[0,1,0] op_sel_hi:[1,1,1] neg_lo:[1,0,0] neg_hi:[1,0,0]
	v_pk_fma_f32 v[108:109], v[148:149], v[62:63], v[108:109] op_sel_hi:[1,0,1] neg_lo:[1,0,0] neg_hi:[1,0,0]
	v_pk_fma_f32 v[108:109], v[150:151], v[62:63], v[108:109] op_sel:[0,1,0] op_sel_hi:[1,1,1] neg_lo:[1,0,0] neg_hi:[1,0,0]
	ds_read_b128 v[120:123], v32 offset:14336
	ds_read_b128 v[124:127], v32 offset:14880
	ds_read_b128 v[128:131], v32 offset:14352
	ds_read_b128 v[132:135], v32 offset:14896
	ds_read_b128 v[144:147], v32 offset:14368
	ds_read_b128 v[148:151], v32 offset:14912
	s_waitcnt lgkmcnt(6)
	v_pk_fma_f32 v[106:107], v[2:3], v[64:65], v[106:107] op_sel_hi:[1,0,1] neg_lo:[1,0,0] neg_hi:[1,0,0]
	v_pk_fma_f32 v[106:107], v[4:5], v[64:65], v[106:107] op_sel:[0,1,0] op_sel_hi:[1,1,1] neg_lo:[1,0,0] neg_hi:[1,0,0]
	v_pk_fma_f32 v[108:109], v[6:7], v[64:65], v[108:109] op_sel_hi:[1,0,1] neg_lo:[1,0,0] neg_hi:[1,0,0]
	v_pk_fma_f32 v[108:109], v[8:9], v[64:65], v[108:109] op_sel:[0,1,0] op_sel_hi:[1,1,1] neg_lo:[1,0,0] neg_hi:[1,0,0]
	v_pk_fma_f32 v[106:107], v[10:11], v[66:67], v[106:107] op_sel_hi:[1,0,1] neg_lo:[1,0,0] neg_hi:[1,0,0]
	v_pk_fma_f32 v[106:107], v[12:13], v[66:67], v[106:107] op_sel:[0,1,0] op_sel_hi:[1,1,1] neg_lo:[1,0,0] neg_hi:[1,0,0]
	v_pk_fma_f32 v[108:109], v[14:15], v[66:67], v[108:109] op_sel_hi:[1,0,1] neg_lo:[1,0,0] neg_hi:[1,0,0]
	v_pk_fma_f32 v[108:109], v[16:17], v[66:67], v[108:109] op_sel:[0,1,0] op_sel_hi:[1,1,1] neg_lo:[1,0,0] neg_hi:[1,0,0]
	v_pk_fma_f32 v[106:107], v[18:19], v[68:69], v[106:107] op_sel_hi:[1,0,1] neg_lo:[1,0,0] neg_hi:[1,0,0]
	v_pk_fma_f32 v[106:107], v[20:21], v[68:69], v[106:107] op_sel:[0,1,0] op_sel_hi:[1,1,1] neg_lo:[1,0,0] neg_hi:[1,0,0]
	v_pk_fma_f32 v[108:109], v[22:23], v[68:69], v[108:109] op_sel_hi:[1,0,1] neg_lo:[1,0,0] neg_hi:[1,0,0]
	v_pk_fma_f32 v[108:109], v[24:25], v[68:69], v[108:109] op_sel:[0,1,0] op_sel_hi:[1,1,1] neg_lo:[1,0,0] neg_hi:[1,0,0]
	ds_read_b128 v[2:5], v32 offset:14384
	ds_read_b128 v[6:9], v32 offset:14928
	ds_read_b128 v[10:13], v32 offset:14400
	ds_read_b128 v[14:17], v32 offset:14944
	ds_read_b128 v[18:21], v32 offset:14416
	ds_read_b128 v[22:25], v32 offset:14960
	s_waitcnt lgkmcnt(6)
	v_pk_fma_f32 v[106:107], v[120:121], v[70:71], v[106:107] op_sel_hi:[1,0,1] neg_lo:[1,0,0] neg_hi:[1,0,0]
	v_pk_fma_f32 v[106:107], v[122:123], v[70:71], v[106:107] op_sel:[0,1,0] op_sel_hi:[1,1,1] neg_lo:[1,0,0] neg_hi:[1,0,0]
	v_pk_fma_f32 v[108:109], v[124:125], v[70:71], v[108:109] op_sel_hi:[1,0,1] neg_lo:[1,0,0] neg_hi:[1,0,0]
	v_pk_fma_f32 v[108:109], v[126:127], v[70:71], v[108:109] op_sel:[0,1,0] op_sel_hi:[1,1,1] neg_lo:[1,0,0] neg_hi:[1,0,0]
	v_pk_fma_f32 v[106:107], v[128:129], v[72:73], v[106:107] op_sel_hi:[1,0,1] neg_lo:[1,0,0] neg_hi:[1,0,0]
	v_pk_fma_f32 v[106:107], v[130:131], v[72:73], v[106:107] op_sel:[0,1,0] op_sel_hi:[1,1,1] neg_lo:[1,0,0] neg_hi:[1,0,0]
	v_pk_fma_f32 v[108:109], v[132:133], v[72:73], v[108:109] op_sel_hi:[1,0,1] neg_lo:[1,0,0] neg_hi:[1,0,0]
	v_pk_fma_f32 v[108:109], v[134:135], v[72:73], v[108:109] op_sel:[0,1,0] op_sel_hi:[1,1,1] neg_lo:[1,0,0] neg_hi:[1,0,0]
	v_pk_fma_f32 v[106:107], v[144:145], v[74:75], v[106:107] op_sel_hi:[1,0,1] neg_lo:[1,0,0] neg_hi:[1,0,0]
	v_pk_fma_f32 v[106:107], v[146:147], v[74:75], v[106:107] op_sel:[0,1,0] op_sel_hi:[1,1,1] neg_lo:[1,0,0] neg_hi:[1,0,0]
	v_pk_fma_f32 v[108:109], v[148:149], v[74:75], v[108:109] op_sel_hi:[1,0,1] neg_lo:[1,0,0] neg_hi:[1,0,0]
	v_pk_fma_f32 v[108:109], v[150:151], v[74:75], v[108:109] op_sel:[0,1,0] op_sel_hi:[1,1,1] neg_lo:[1,0,0] neg_hi:[1,0,0]
	ds_read_b128 v[120:123], v32 offset:14432
	ds_read_b128 v[124:127], v32 offset:14976
	ds_read_b128 v[128:131], v32 offset:14448
	ds_read_b128 v[132:135], v32 offset:14992
	ds_read_b128 v[144:147], v32 offset:14464
	ds_read_b128 v[148:151], v32 offset:15008
	s_waitcnt lgkmcnt(6)
	v_pk_fma_f32 v[106:107], v[2:3], v[76:77], v[106:107] op_sel_hi:[1,0,1] neg_lo:[1,0,0] neg_hi:[1,0,0]
	v_pk_fma_f32 v[106:107], v[4:5], v[76:77], v[106:107] op_sel:[0,1,0] op_sel_hi:[1,1,1] neg_lo:[1,0,0] neg_hi:[1,0,0]
	v_pk_fma_f32 v[108:109], v[6:7], v[76:77], v[108:109] op_sel_hi:[1,0,1] neg_lo:[1,0,0] neg_hi:[1,0,0]
	v_pk_fma_f32 v[108:109], v[8:9], v[76:77], v[108:109] op_sel:[0,1,0] op_sel_hi:[1,1,1] neg_lo:[1,0,0] neg_hi:[1,0,0]
	v_pk_fma_f32 v[106:107], v[10:11], v[78:79], v[106:107] op_sel_hi:[1,0,1] neg_lo:[1,0,0] neg_hi:[1,0,0]
	v_pk_fma_f32 v[106:107], v[12:13], v[78:79], v[106:107] op_sel:[0,1,0] op_sel_hi:[1,1,1] neg_lo:[1,0,0] neg_hi:[1,0,0]
	v_pk_fma_f32 v[108:109], v[14:15], v[78:79], v[108:109] op_sel_hi:[1,0,1] neg_lo:[1,0,0] neg_hi:[1,0,0]
	v_pk_fma_f32 v[108:109], v[16:17], v[78:79], v[108:109] op_sel:[0,1,0] op_sel_hi:[1,1,1] neg_lo:[1,0,0] neg_hi:[1,0,0]
	v_pk_fma_f32 v[106:107], v[18:19], v[80:81], v[106:107] op_sel_hi:[1,0,1] neg_lo:[1,0,0] neg_hi:[1,0,0]
	v_pk_fma_f32 v[106:107], v[20:21], v[80:81], v[106:107] op_sel:[0,1,0] op_sel_hi:[1,1,1] neg_lo:[1,0,0] neg_hi:[1,0,0]
	v_pk_fma_f32 v[108:109], v[22:23], v[80:81], v[108:109] op_sel_hi:[1,0,1] neg_lo:[1,0,0] neg_hi:[1,0,0]
	v_pk_fma_f32 v[108:109], v[24:25], v[80:81], v[108:109] op_sel:[0,1,0] op_sel_hi:[1,1,1] neg_lo:[1,0,0] neg_hi:[1,0,0]
	ds_read_b128 v[2:5], v32 offset:14480
	ds_read_b128 v[6:9], v32 offset:15024
	ds_read_b128 v[10:13], v32 offset:14496
	ds_read_b128 v[14:17], v32 offset:15040
	ds_read_b128 v[18:21], v32 offset:14512
	ds_read_b128 v[22:25], v32 offset:15056
	s_waitcnt lgkmcnt(6)
	v_pk_fma_f32 v[106:107], v[120:121], v[82:83], v[106:107] op_sel_hi:[1,0,1] neg_lo:[1,0,0] neg_hi:[1,0,0]
	v_pk_fma_f32 v[106:107], v[122:123], v[82:83], v[106:107] op_sel:[0,1,0] op_sel_hi:[1,1,1] neg_lo:[1,0,0] neg_hi:[1,0,0]
	v_pk_fma_f32 v[108:109], v[124:125], v[82:83], v[108:109] op_sel_hi:[1,0,1] neg_lo:[1,0,0] neg_hi:[1,0,0]
	v_pk_fma_f32 v[108:109], v[126:127], v[82:83], v[108:109] op_sel:[0,1,0] op_sel_hi:[1,1,1] neg_lo:[1,0,0] neg_hi:[1,0,0]
	v_pk_fma_f32 v[106:107], v[128:129], v[84:85], v[106:107] op_sel_hi:[1,0,1] neg_lo:[1,0,0] neg_hi:[1,0,0]
	v_pk_fma_f32 v[106:107], v[130:131], v[84:85], v[106:107] op_sel:[0,1,0] op_sel_hi:[1,1,1] neg_lo:[1,0,0] neg_hi:[1,0,0]
	v_pk_fma_f32 v[108:109], v[132:133], v[84:85], v[108:109] op_sel_hi:[1,0,1] neg_lo:[1,0,0] neg_hi:[1,0,0]
	v_pk_fma_f32 v[108:109], v[134:135], v[84:85], v[108:109] op_sel:[0,1,0] op_sel_hi:[1,1,1] neg_lo:[1,0,0] neg_hi:[1,0,0]
	v_pk_fma_f32 v[106:107], v[144:145], v[86:87], v[106:107] op_sel_hi:[1,0,1] neg_lo:[1,0,0] neg_hi:[1,0,0]
	v_pk_fma_f32 v[106:107], v[146:147], v[86:87], v[106:107] op_sel:[0,1,0] op_sel_hi:[1,1,1] neg_lo:[1,0,0] neg_hi:[1,0,0]
	v_pk_fma_f32 v[108:109], v[148:149], v[86:87], v[108:109] op_sel_hi:[1,0,1] neg_lo:[1,0,0] neg_hi:[1,0,0]
	v_pk_fma_f32 v[108:109], v[150:151], v[86:87], v[108:109] op_sel:[0,1,0] op_sel_hi:[1,1,1] neg_lo:[1,0,0] neg_hi:[1,0,0]
	ds_read_b128 v[120:123], v32 offset:14528
	ds_read_b128 v[124:127], v32 offset:15072
	ds_read_b128 v[128:131], v32 offset:14544
	ds_read_b128 v[132:135], v32 offset:15088
	ds_read_b128 v[144:147], v32 offset:14560
	ds_read_b128 v[148:151], v32 offset:15104
	s_waitcnt lgkmcnt(6)
	v_pk_fma_f32 v[106:107], v[2:3], v[88:89], v[106:107] op_sel_hi:[1,0,1] neg_lo:[1,0,0] neg_hi:[1,0,0]
	v_pk_fma_f32 v[106:107], v[4:5], v[88:89], v[106:107] op_sel:[0,1,0] op_sel_hi:[1,1,1] neg_lo:[1,0,0] neg_hi:[1,0,0]
	v_pk_fma_f32 v[108:109], v[6:7], v[88:89], v[108:109] op_sel_hi:[1,0,1] neg_lo:[1,0,0] neg_hi:[1,0,0]
	v_pk_fma_f32 v[108:109], v[8:9], v[88:89], v[108:109] op_sel:[0,1,0] op_sel_hi:[1,1,1] neg_lo:[1,0,0] neg_hi:[1,0,0]
	v_pk_fma_f32 v[106:107], v[10:11], v[90:91], v[106:107] op_sel_hi:[1,0,1] neg_lo:[1,0,0] neg_hi:[1,0,0]
	v_pk_fma_f32 v[106:107], v[12:13], v[90:91], v[106:107] op_sel:[0,1,0] op_sel_hi:[1,1,1] neg_lo:[1,0,0] neg_hi:[1,0,0]
	v_pk_fma_f32 v[108:109], v[14:15], v[90:91], v[108:109] op_sel_hi:[1,0,1] neg_lo:[1,0,0] neg_hi:[1,0,0]
	v_pk_fma_f32 v[108:109], v[16:17], v[90:91], v[108:109] op_sel:[0,1,0] op_sel_hi:[1,1,1] neg_lo:[1,0,0] neg_hi:[1,0,0]
	v_pk_fma_f32 v[106:107], v[18:19], v[92:93], v[106:107] op_sel_hi:[1,0,1] neg_lo:[1,0,0] neg_hi:[1,0,0]
	v_pk_fma_f32 v[106:107], v[20:21], v[92:93], v[106:107] op_sel:[0,1,0] op_sel_hi:[1,1,1] neg_lo:[1,0,0] neg_hi:[1,0,0]
	v_pk_fma_f32 v[108:109], v[22:23], v[92:93], v[108:109] op_sel_hi:[1,0,1] neg_lo:[1,0,0] neg_hi:[1,0,0]
	v_pk_fma_f32 v[108:109], v[24:25], v[92:93], v[108:109] op_sel:[0,1,0] op_sel_hi:[1,1,1] neg_lo:[1,0,0] neg_hi:[1,0,0]
	ds_read_b128 v[2:5], v32 offset:15120
	s_waitcnt lgkmcnt(1)
	v_pk_fma_f32 v[106:107], v[120:121], v[94:95], v[106:107] op_sel_hi:[1,0,1] neg_lo:[1,0,0] neg_hi:[1,0,0]
	v_pk_fma_f32 v[106:107], v[122:123], v[94:95], v[106:107] op_sel:[0,1,0] op_sel_hi:[1,1,1] neg_lo:[1,0,0] neg_hi:[1,0,0]
	v_pk_fma_f32 v[108:109], v[124:125], v[94:95], v[108:109] op_sel_hi:[1,0,1] neg_lo:[1,0,0] neg_hi:[1,0,0]
	v_pk_fma_f32 v[108:109], v[126:127], v[94:95], v[108:109] op_sel:[0,1,0] op_sel_hi:[1,1,1] neg_lo:[1,0,0] neg_hi:[1,0,0]
	v_pk_fma_f32 v[106:107], v[128:129], v[96:97], v[106:107] op_sel_hi:[1,0,1] neg_lo:[1,0,0] neg_hi:[1,0,0]
	v_pk_fma_f32 v[106:107], v[130:131], v[96:97], v[106:107] op_sel:[0,1,0] op_sel_hi:[1,1,1] neg_lo:[1,0,0] neg_hi:[1,0,0]
	v_pk_fma_f32 v[108:109], v[132:133], v[96:97], v[108:109] op_sel_hi:[1,0,1] neg_lo:[1,0,0] neg_hi:[1,0,0]
	v_pk_fma_f32 v[108:109], v[134:135], v[96:97], v[108:109] op_sel:[0,1,0] op_sel_hi:[1,1,1] neg_lo:[1,0,0] neg_hi:[1,0,0]
	v_fma_f32 v107, -v145, v106, v107
	v_pk_fma_f32 v[108:109], v[148:149], v[106:107], v[108:109] op_sel_hi:[1,0,1] neg_lo:[1,0,0] neg_hi:[1,0,0]
	v_pk_fma_f32 v[108:109], v[150:151], v[106:107], v[108:109] op_sel:[0,1,0] op_sel_hi:[1,1,1] neg_lo:[1,0,0] neg_hi:[1,0,0]
	ds_read_u16 v152, v30 offset:15232
	ds_read_u16 v153, v30 offset:15504
	ds_read_b64 v[154:155], v31 offset:224
	ds_read_u16 v156, v30 offset:15776
	ds_read_u16 v157, v30 offset:16048
	ds_read_b64 v[158:159], v31 offset:232
	ds_read_b128 v[120:123], v32 offset:15232
	ds_read_b128 v[124:127], v32 offset:15776
	ds_read_b128 v[128:131], v32 offset:15248
	ds_read_b128 v[132:135], v32 offset:15792
	ds_read_b128 v[144:147], v32 offset:15264
	ds_read_b128 v[148:151], v32 offset:15808
	s_waitcnt lgkmcnt(12)
	v_fma_f32 v109, -v3, v108, v109
	ds_read_b128 v[2:5], v32 offset:15280
	ds_read_b128 v[6:9], v32 offset:15824
	ds_read_b128 v[10:13], v32 offset:15296
	ds_read_b128 v[14:17], v32 offset:15840
	ds_read_b128 v[18:21], v32 offset:15312
	ds_read_b128 v[22:25], v32 offset:15856
	s_waitcnt lgkmcnt(6)
	v_lshlrev_b32_e32 v152, 16, v152
	v_lshlrev_b32_e32 v153, 16, v153
	v_pk_mul_f32 v[110:111], v[152:153], v[154:155]
	v_lshlrev_b32_e32 v156, 16, v156
	v_lshlrev_b32_e32 v157, 16, v157
	v_pk_mul_f32 v[112:113], v[156:157], v[158:159]
	v_pk_fma_f32 v[110:111], v[120:121], v[46:47], v[110:111] op_sel_hi:[1,0,1] neg_lo:[1,0,0] neg_hi:[1,0,0]
	v_pk_fma_f32 v[110:111], v[122:123], v[46:47], v[110:111] op_sel:[0,1,0] op_sel_hi:[1,1,1] neg_lo:[1,0,0] neg_hi:[1,0,0]
	v_pk_fma_f32 v[112:113], v[124:125], v[46:47], v[112:113] op_sel_hi:[1,0,1] neg_lo:[1,0,0] neg_hi:[1,0,0]
	v_pk_fma_f32 v[112:113], v[126:127], v[46:47], v[112:113] op_sel:[0,1,0] op_sel_hi:[1,1,1] neg_lo:[1,0,0] neg_hi:[1,0,0]
	v_pk_fma_f32 v[110:111], v[128:129], v[48:49], v[110:111] op_sel_hi:[1,0,1] neg_lo:[1,0,0] neg_hi:[1,0,0]
	v_pk_fma_f32 v[110:111], v[130:131], v[48:49], v[110:111] op_sel:[0,1,0] op_sel_hi:[1,1,1] neg_lo:[1,0,0] neg_hi:[1,0,0]
	v_pk_fma_f32 v[112:113], v[132:133], v[48:49], v[112:113] op_sel_hi:[1,0,1] neg_lo:[1,0,0] neg_hi:[1,0,0]
	v_pk_fma_f32 v[112:113], v[134:135], v[48:49], v[112:113] op_sel:[0,1,0] op_sel_hi:[1,1,1] neg_lo:[1,0,0] neg_hi:[1,0,0]
	v_pk_fma_f32 v[110:111], v[144:145], v[50:51], v[110:111] op_sel_hi:[1,0,1] neg_lo:[1,0,0] neg_hi:[1,0,0]
	v_pk_fma_f32 v[110:111], v[146:147], v[50:51], v[110:111] op_sel:[0,1,0] op_sel_hi:[1,1,1] neg_lo:[1,0,0] neg_hi:[1,0,0]
	v_pk_fma_f32 v[112:113], v[148:149], v[50:51], v[112:113] op_sel_hi:[1,0,1] neg_lo:[1,0,0] neg_hi:[1,0,0]
	v_pk_fma_f32 v[112:113], v[150:151], v[50:51], v[112:113] op_sel:[0,1,0] op_sel_hi:[1,1,1] neg_lo:[1,0,0] neg_hi:[1,0,0]
	ds_read_b128 v[120:123], v32 offset:15328
	ds_read_b128 v[124:127], v32 offset:15872
	ds_read_b128 v[128:131], v32 offset:15344
	ds_read_b128 v[132:135], v32 offset:15888
	ds_read_b128 v[144:147], v32 offset:15360
	ds_read_b128 v[148:151], v32 offset:15904
	s_waitcnt lgkmcnt(6)
	v_pk_fma_f32 v[110:111], v[2:3], v[52:53], v[110:111] op_sel_hi:[1,0,1] neg_lo:[1,0,0] neg_hi:[1,0,0]
	v_pk_fma_f32 v[110:111], v[4:5], v[52:53], v[110:111] op_sel:[0,1,0] op_sel_hi:[1,1,1] neg_lo:[1,0,0] neg_hi:[1,0,0]
	v_pk_fma_f32 v[112:113], v[6:7], v[52:53], v[112:113] op_sel_hi:[1,0,1] neg_lo:[1,0,0] neg_hi:[1,0,0]
	v_pk_fma_f32 v[112:113], v[8:9], v[52:53], v[112:113] op_sel:[0,1,0] op_sel_hi:[1,1,1] neg_lo:[1,0,0] neg_hi:[1,0,0]
	v_pk_fma_f32 v[110:111], v[10:11], v[54:55], v[110:111] op_sel_hi:[1,0,1] neg_lo:[1,0,0] neg_hi:[1,0,0]
	v_pk_fma_f32 v[110:111], v[12:13], v[54:55], v[110:111] op_sel:[0,1,0] op_sel_hi:[1,1,1] neg_lo:[1,0,0] neg_hi:[1,0,0]
	v_pk_fma_f32 v[112:113], v[14:15], v[54:55], v[112:113] op_sel_hi:[1,0,1] neg_lo:[1,0,0] neg_hi:[1,0,0]
	v_pk_fma_f32 v[112:113], v[16:17], v[54:55], v[112:113] op_sel:[0,1,0] op_sel_hi:[1,1,1] neg_lo:[1,0,0] neg_hi:[1,0,0]
	v_pk_fma_f32 v[110:111], v[18:19], v[56:57], v[110:111] op_sel_hi:[1,0,1] neg_lo:[1,0,0] neg_hi:[1,0,0]
	v_pk_fma_f32 v[110:111], v[20:21], v[56:57], v[110:111] op_sel:[0,1,0] op_sel_hi:[1,1,1] neg_lo:[1,0,0] neg_hi:[1,0,0]
	v_pk_fma_f32 v[112:113], v[22:23], v[56:57], v[112:113] op_sel_hi:[1,0,1] neg_lo:[1,0,0] neg_hi:[1,0,0]
	v_pk_fma_f32 v[112:113], v[24:25], v[56:57], v[112:113] op_sel:[0,1,0] op_sel_hi:[1,1,1] neg_lo:[1,0,0] neg_hi:[1,0,0]
	ds_read_b128 v[2:5], v32 offset:15376
	ds_read_b128 v[6:9], v32 offset:15920
	ds_read_b128 v[10:13], v32 offset:15392
	ds_read_b128 v[14:17], v32 offset:15936
	ds_read_b128 v[18:21], v32 offset:15408
	ds_read_b128 v[22:25], v32 offset:15952
	s_waitcnt lgkmcnt(6)
	v_pk_fma_f32 v[110:111], v[120:121], v[58:59], v[110:111] op_sel_hi:[1,0,1] neg_lo:[1,0,0] neg_hi:[1,0,0]
	v_pk_fma_f32 v[110:111], v[122:123], v[58:59], v[110:111] op_sel:[0,1,0] op_sel_hi:[1,1,1] neg_lo:[1,0,0] neg_hi:[1,0,0]
	v_pk_fma_f32 v[112:113], v[124:125], v[58:59], v[112:113] op_sel_hi:[1,0,1] neg_lo:[1,0,0] neg_hi:[1,0,0]
	v_pk_fma_f32 v[112:113], v[126:127], v[58:59], v[112:113] op_sel:[0,1,0] op_sel_hi:[1,1,1] neg_lo:[1,0,0] neg_hi:[1,0,0]
	v_pk_fma_f32 v[110:111], v[128:129], v[60:61], v[110:111] op_sel_hi:[1,0,1] neg_lo:[1,0,0] neg_hi:[1,0,0]
	v_pk_fma_f32 v[110:111], v[130:131], v[60:61], v[110:111] op_sel:[0,1,0] op_sel_hi:[1,1,1] neg_lo:[1,0,0] neg_hi:[1,0,0]
	v_pk_fma_f32 v[112:113], v[132:133], v[60:61], v[112:113] op_sel_hi:[1,0,1] neg_lo:[1,0,0] neg_hi:[1,0,0]
	v_pk_fma_f32 v[112:113], v[134:135], v[60:61], v[112:113] op_sel:[0,1,0] op_sel_hi:[1,1,1] neg_lo:[1,0,0] neg_hi:[1,0,0]
	v_pk_fma_f32 v[110:111], v[144:145], v[62:63], v[110:111] op_sel_hi:[1,0,1] neg_lo:[1,0,0] neg_hi:[1,0,0]
	v_pk_fma_f32 v[110:111], v[146:147], v[62:63], v[110:111] op_sel:[0,1,0] op_sel_hi:[1,1,1] neg_lo:[1,0,0] neg_hi:[1,0,0]
	v_pk_fma_f32 v[112:113], v[148:149], v[62:63], v[112:113] op_sel_hi:[1,0,1] neg_lo:[1,0,0] neg_hi:[1,0,0]
	v_pk_fma_f32 v[112:113], v[150:151], v[62:63], v[112:113] op_sel:[0,1,0] op_sel_hi:[1,1,1] neg_lo:[1,0,0] neg_hi:[1,0,0]
	ds_read_b128 v[120:123], v32 offset:15424
	ds_read_b128 v[124:127], v32 offset:15968
	ds_read_b128 v[128:131], v32 offset:15440
	ds_read_b128 v[132:135], v32 offset:15984
	ds_read_b128 v[144:147], v32 offset:15456
	ds_read_b128 v[148:151], v32 offset:16000
	s_waitcnt lgkmcnt(6)
	v_pk_fma_f32 v[110:111], v[2:3], v[64:65], v[110:111] op_sel_hi:[1,0,1] neg_lo:[1,0,0] neg_hi:[1,0,0]
	v_pk_fma_f32 v[110:111], v[4:5], v[64:65], v[110:111] op_sel:[0,1,0] op_sel_hi:[1,1,1] neg_lo:[1,0,0] neg_hi:[1,0,0]
	v_pk_fma_f32 v[112:113], v[6:7], v[64:65], v[112:113] op_sel_hi:[1,0,1] neg_lo:[1,0,0] neg_hi:[1,0,0]
	v_pk_fma_f32 v[112:113], v[8:9], v[64:65], v[112:113] op_sel:[0,1,0] op_sel_hi:[1,1,1] neg_lo:[1,0,0] neg_hi:[1,0,0]
	v_pk_fma_f32 v[110:111], v[10:11], v[66:67], v[110:111] op_sel_hi:[1,0,1] neg_lo:[1,0,0] neg_hi:[1,0,0]
	v_pk_fma_f32 v[110:111], v[12:13], v[66:67], v[110:111] op_sel:[0,1,0] op_sel_hi:[1,1,1] neg_lo:[1,0,0] neg_hi:[1,0,0]
	v_pk_fma_f32 v[112:113], v[14:15], v[66:67], v[112:113] op_sel_hi:[1,0,1] neg_lo:[1,0,0] neg_hi:[1,0,0]
	v_pk_fma_f32 v[112:113], v[16:17], v[66:67], v[112:113] op_sel:[0,1,0] op_sel_hi:[1,1,1] neg_lo:[1,0,0] neg_hi:[1,0,0]
	v_pk_fma_f32 v[110:111], v[18:19], v[68:69], v[110:111] op_sel_hi:[1,0,1] neg_lo:[1,0,0] neg_hi:[1,0,0]
	v_pk_fma_f32 v[110:111], v[20:21], v[68:69], v[110:111] op_sel:[0,1,0] op_sel_hi:[1,1,1] neg_lo:[1,0,0] neg_hi:[1,0,0]
	v_pk_fma_f32 v[112:113], v[22:23], v[68:69], v[112:113] op_sel_hi:[1,0,1] neg_lo:[1,0,0] neg_hi:[1,0,0]
	v_pk_fma_f32 v[112:113], v[24:25], v[68:69], v[112:113] op_sel:[0,1,0] op_sel_hi:[1,1,1] neg_lo:[1,0,0] neg_hi:[1,0,0]
	ds_read_b128 v[2:5], v32 offset:15472
	ds_read_b128 v[6:9], v32 offset:16016
	ds_read_b128 v[10:13], v32 offset:15488
	ds_read_b128 v[14:17], v32 offset:16032
	ds_read_b128 v[18:21], v32 offset:15504
	ds_read_b128 v[22:25], v32 offset:16048
	s_waitcnt lgkmcnt(6)
	v_pk_fma_f32 v[110:111], v[120:121], v[70:71], v[110:111] op_sel_hi:[1,0,1] neg_lo:[1,0,0] neg_hi:[1,0,0]
	v_pk_fma_f32 v[110:111], v[122:123], v[70:71], v[110:111] op_sel:[0,1,0] op_sel_hi:[1,1,1] neg_lo:[1,0,0] neg_hi:[1,0,0]
	v_pk_fma_f32 v[112:113], v[124:125], v[70:71], v[112:113] op_sel_hi:[1,0,1] neg_lo:[1,0,0] neg_hi:[1,0,0]
	v_pk_fma_f32 v[112:113], v[126:127], v[70:71], v[112:113] op_sel:[0,1,0] op_sel_hi:[1,1,1] neg_lo:[1,0,0] neg_hi:[1,0,0]
	v_pk_fma_f32 v[110:111], v[128:129], v[72:73], v[110:111] op_sel_hi:[1,0,1] neg_lo:[1,0,0] neg_hi:[1,0,0]
	v_pk_fma_f32 v[110:111], v[130:131], v[72:73], v[110:111] op_sel:[0,1,0] op_sel_hi:[1,1,1] neg_lo:[1,0,0] neg_hi:[1,0,0]
	v_pk_fma_f32 v[112:113], v[132:133], v[72:73], v[112:113] op_sel_hi:[1,0,1] neg_lo:[1,0,0] neg_hi:[1,0,0]
	v_pk_fma_f32 v[112:113], v[134:135], v[72:73], v[112:113] op_sel:[0,1,0] op_sel_hi:[1,1,1] neg_lo:[1,0,0] neg_hi:[1,0,0]
	v_pk_fma_f32 v[110:111], v[144:145], v[74:75], v[110:111] op_sel_hi:[1,0,1] neg_lo:[1,0,0] neg_hi:[1,0,0]
	v_pk_fma_f32 v[110:111], v[146:147], v[74:75], v[110:111] op_sel:[0,1,0] op_sel_hi:[1,1,1] neg_lo:[1,0,0] neg_hi:[1,0,0]
	v_pk_fma_f32 v[112:113], v[148:149], v[74:75], v[112:113] op_sel_hi:[1,0,1] neg_lo:[1,0,0] neg_hi:[1,0,0]
	v_pk_fma_f32 v[112:113], v[150:151], v[74:75], v[112:113] op_sel:[0,1,0] op_sel_hi:[1,1,1] neg_lo:[1,0,0] neg_hi:[1,0,0]
	ds_read_b128 v[120:123], v32 offset:15520
	ds_read_b128 v[124:127], v32 offset:16064
	ds_read_b128 v[128:131], v32 offset:15536
	ds_read_b128 v[132:135], v32 offset:16080
	ds_read_b128 v[144:147], v32 offset:15552
	ds_read_b128 v[148:151], v32 offset:16096
	s_waitcnt lgkmcnt(6)
	v_pk_fma_f32 v[110:111], v[2:3], v[76:77], v[110:111] op_sel_hi:[1,0,1] neg_lo:[1,0,0] neg_hi:[1,0,0]
	v_pk_fma_f32 v[110:111], v[4:5], v[76:77], v[110:111] op_sel:[0,1,0] op_sel_hi:[1,1,1] neg_lo:[1,0,0] neg_hi:[1,0,0]
	v_pk_fma_f32 v[112:113], v[6:7], v[76:77], v[112:113] op_sel_hi:[1,0,1] neg_lo:[1,0,0] neg_hi:[1,0,0]
	v_pk_fma_f32 v[112:113], v[8:9], v[76:77], v[112:113] op_sel:[0,1,0] op_sel_hi:[1,1,1] neg_lo:[1,0,0] neg_hi:[1,0,0]
	v_pk_fma_f32 v[110:111], v[10:11], v[78:79], v[110:111] op_sel_hi:[1,0,1] neg_lo:[1,0,0] neg_hi:[1,0,0]
	v_pk_fma_f32 v[110:111], v[12:13], v[78:79], v[110:111] op_sel:[0,1,0] op_sel_hi:[1,1,1] neg_lo:[1,0,0] neg_hi:[1,0,0]
	v_pk_fma_f32 v[112:113], v[14:15], v[78:79], v[112:113] op_sel_hi:[1,0,1] neg_lo:[1,0,0] neg_hi:[1,0,0]
	v_pk_fma_f32 v[112:113], v[16:17], v[78:79], v[112:113] op_sel:[0,1,0] op_sel_hi:[1,1,1] neg_lo:[1,0,0] neg_hi:[1,0,0]
	v_pk_fma_f32 v[110:111], v[18:19], v[80:81], v[110:111] op_sel_hi:[1,0,1] neg_lo:[1,0,0] neg_hi:[1,0,0]
	v_pk_fma_f32 v[110:111], v[20:21], v[80:81], v[110:111] op_sel:[0,1,0] op_sel_hi:[1,1,1] neg_lo:[1,0,0] neg_hi:[1,0,0]
	v_pk_fma_f32 v[112:113], v[22:23], v[80:81], v[112:113] op_sel_hi:[1,0,1] neg_lo:[1,0,0] neg_hi:[1,0,0]
	v_pk_fma_f32 v[112:113], v[24:25], v[80:81], v[112:113] op_sel:[0,1,0] op_sel_hi:[1,1,1] neg_lo:[1,0,0] neg_hi:[1,0,0]
	ds_read_b128 v[2:5], v32 offset:15568
	ds_read_b128 v[6:9], v32 offset:16112
	ds_read_b128 v[10:13], v32 offset:15584
	ds_read_b128 v[14:17], v32 offset:16128
	ds_read_b128 v[18:21], v32 offset:15600
	ds_read_b128 v[22:25], v32 offset:16144
	s_waitcnt lgkmcnt(6)
	v_pk_fma_f32 v[110:111], v[120:121], v[82:83], v[110:111] op_sel_hi:[1,0,1] neg_lo:[1,0,0] neg_hi:[1,0,0]
	v_pk_fma_f32 v[110:111], v[122:123], v[82:83], v[110:111] op_sel:[0,1,0] op_sel_hi:[1,1,1] neg_lo:[1,0,0] neg_hi:[1,0,0]
	v_pk_fma_f32 v[112:113], v[124:125], v[82:83], v[112:113] op_sel_hi:[1,0,1] neg_lo:[1,0,0] neg_hi:[1,0,0]
	v_pk_fma_f32 v[112:113], v[126:127], v[82:83], v[112:113] op_sel:[0,1,0] op_sel_hi:[1,1,1] neg_lo:[1,0,0] neg_hi:[1,0,0]
	v_pk_fma_f32 v[110:111], v[128:129], v[84:85], v[110:111] op_sel_hi:[1,0,1] neg_lo:[1,0,0] neg_hi:[1,0,0]
	v_pk_fma_f32 v[110:111], v[130:131], v[84:85], v[110:111] op_sel:[0,1,0] op_sel_hi:[1,1,1] neg_lo:[1,0,0] neg_hi:[1,0,0]
	v_pk_fma_f32 v[112:113], v[132:133], v[84:85], v[112:113] op_sel_hi:[1,0,1] neg_lo:[1,0,0] neg_hi:[1,0,0]
	v_pk_fma_f32 v[112:113], v[134:135], v[84:85], v[112:113] op_sel:[0,1,0] op_sel_hi:[1,1,1] neg_lo:[1,0,0] neg_hi:[1,0,0]
	v_pk_fma_f32 v[110:111], v[144:145], v[86:87], v[110:111] op_sel_hi:[1,0,1] neg_lo:[1,0,0] neg_hi:[1,0,0]
	v_pk_fma_f32 v[110:111], v[146:147], v[86:87], v[110:111] op_sel:[0,1,0] op_sel_hi:[1,1,1] neg_lo:[1,0,0] neg_hi:[1,0,0]
	v_pk_fma_f32 v[112:113], v[148:149], v[86:87], v[112:113] op_sel_hi:[1,0,1] neg_lo:[1,0,0] neg_hi:[1,0,0]
	v_pk_fma_f32 v[112:113], v[150:151], v[86:87], v[112:113] op_sel:[0,1,0] op_sel_hi:[1,1,1] neg_lo:[1,0,0] neg_hi:[1,0,0]
	ds_read_b128 v[120:123], v32 offset:15616
	ds_read_b128 v[124:127], v32 offset:16160
	ds_read_b128 v[128:131], v32 offset:15632
	ds_read_b128 v[132:135], v32 offset:16176
	ds_read_b128 v[144:147], v32 offset:15648
	ds_read_b128 v[148:151], v32 offset:16192
	s_waitcnt lgkmcnt(6)
	v_pk_fma_f32 v[110:111], v[2:3], v[88:89], v[110:111] op_sel_hi:[1,0,1] neg_lo:[1,0,0] neg_hi:[1,0,0]
	v_pk_fma_f32 v[110:111], v[4:5], v[88:89], v[110:111] op_sel:[0,1,0] op_sel_hi:[1,1,1] neg_lo:[1,0,0] neg_hi:[1,0,0]
	v_pk_fma_f32 v[112:113], v[6:7], v[88:89], v[112:113] op_sel_hi:[1,0,1] neg_lo:[1,0,0] neg_hi:[1,0,0]
	v_pk_fma_f32 v[112:113], v[8:9], v[88:89], v[112:113] op_sel:[0,1,0] op_sel_hi:[1,1,1] neg_lo:[1,0,0] neg_hi:[1,0,0]
	v_pk_fma_f32 v[110:111], v[10:11], v[90:91], v[110:111] op_sel_hi:[1,0,1] neg_lo:[1,0,0] neg_hi:[1,0,0]
	v_pk_fma_f32 v[110:111], v[12:13], v[90:91], v[110:111] op_sel:[0,1,0] op_sel_hi:[1,1,1] neg_lo:[1,0,0] neg_hi:[1,0,0]
	v_pk_fma_f32 v[112:113], v[14:15], v[90:91], v[112:113] op_sel_hi:[1,0,1] neg_lo:[1,0,0] neg_hi:[1,0,0]
	v_pk_fma_f32 v[112:113], v[16:17], v[90:91], v[112:113] op_sel:[0,1,0] op_sel_hi:[1,1,1] neg_lo:[1,0,0] neg_hi:[1,0,0]
	v_pk_fma_f32 v[110:111], v[18:19], v[92:93], v[110:111] op_sel_hi:[1,0,1] neg_lo:[1,0,0] neg_hi:[1,0,0]
	v_pk_fma_f32 v[110:111], v[20:21], v[92:93], v[110:111] op_sel:[0,1,0] op_sel_hi:[1,1,1] neg_lo:[1,0,0] neg_hi:[1,0,0]
	v_pk_fma_f32 v[112:113], v[22:23], v[92:93], v[112:113] op_sel_hi:[1,0,1] neg_lo:[1,0,0] neg_hi:[1,0,0]
	v_pk_fma_f32 v[112:113], v[24:25], v[92:93], v[112:113] op_sel:[0,1,0] op_sel_hi:[1,1,1] neg_lo:[1,0,0] neg_hi:[1,0,0]
	ds_read_b128 v[2:5], v32 offset:15664
	ds_read_b128 v[6:9], v32 offset:16208
	ds_read_b128 v[10:13], v32 offset:15680
	ds_read_b128 v[14:17], v32 offset:16224
	ds_read_b128 v[18:21], v32 offset:16240
	s_waitcnt lgkmcnt(5)
	v_pk_fma_f32 v[110:111], v[120:121], v[94:95], v[110:111] op_sel_hi:[1,0,1] neg_lo:[1,0,0] neg_hi:[1,0,0]
	v_pk_fma_f32 v[110:111], v[122:123], v[94:95], v[110:111] op_sel:[0,1,0] op_sel_hi:[1,1,1] neg_lo:[1,0,0] neg_hi:[1,0,0]
	v_pk_fma_f32 v[112:113], v[124:125], v[94:95], v[112:113] op_sel_hi:[1,0,1] neg_lo:[1,0,0] neg_hi:[1,0,0]
	v_pk_fma_f32 v[112:113], v[126:127], v[94:95], v[112:113] op_sel:[0,1,0] op_sel_hi:[1,1,1] neg_lo:[1,0,0] neg_hi:[1,0,0]
	v_pk_fma_f32 v[110:111], v[128:129], v[96:97], v[110:111] op_sel_hi:[1,0,1] neg_lo:[1,0,0] neg_hi:[1,0,0]
	v_pk_fma_f32 v[110:111], v[130:131], v[96:97], v[110:111] op_sel:[0,1,0] op_sel_hi:[1,1,1] neg_lo:[1,0,0] neg_hi:[1,0,0]
	v_pk_fma_f32 v[112:113], v[132:133], v[96:97], v[112:113] op_sel_hi:[1,0,1] neg_lo:[1,0,0] neg_hi:[1,0,0]
	v_pk_fma_f32 v[112:113], v[134:135], v[96:97], v[112:113] op_sel:[0,1,0] op_sel_hi:[1,1,1] neg_lo:[1,0,0] neg_hi:[1,0,0]
	v_pk_fma_f32 v[110:111], v[144:145], v[106:107], v[110:111] op_sel_hi:[1,0,1] neg_lo:[1,0,0] neg_hi:[1,0,0]
	v_pk_fma_f32 v[110:111], v[146:147], v[106:107], v[110:111] op_sel:[0,1,0] op_sel_hi:[1,1,1] neg_lo:[1,0,0] neg_hi:[1,0,0]
	v_pk_fma_f32 v[112:113], v[148:149], v[106:107], v[112:113] op_sel_hi:[1,0,1] neg_lo:[1,0,0] neg_hi:[1,0,0]
	v_pk_fma_f32 v[112:113], v[150:151], v[106:107], v[112:113] op_sel:[0,1,0] op_sel_hi:[1,1,1] neg_lo:[1,0,0] neg_hi:[1,0,0]
	ds_read_u16 v152, v30 offset:16320
	ds_read_u16 v153, v30 offset:16592
	ds_read_b64 v[154:155], v31 offset:240
	ds_read_u16 v156, v30 offset:16864
	ds_read_u16 v157, v30 offset:17136
	ds_read_b64 v[158:159], v31 offset:248
	ds_read_b128 v[120:123], v32 offset:16320
	ds_read_b128 v[124:127], v32 offset:16864
	ds_read_b128 v[128:131], v32 offset:16336
	ds_read_b128 v[132:135], v32 offset:16880
	ds_read_b128 v[144:147], v32 offset:16352
	ds_read_b128 v[148:151], v32 offset:16896
	s_waitcnt lgkmcnt(12)
	v_pk_fma_f32 v[110:111], v[2:3], v[108:109], v[110:111] op_sel_hi:[1,0,1] neg_lo:[1,0,0] neg_hi:[1,0,0]
	v_pk_fma_f32 v[110:111], v[4:5], v[108:109], v[110:111] op_sel:[0,1,0] op_sel_hi:[1,1,1] neg_lo:[1,0,0] neg_hi:[1,0,0]
	v_pk_fma_f32 v[112:113], v[6:7], v[108:109], v[112:113] op_sel_hi:[1,0,1] neg_lo:[1,0,0] neg_hi:[1,0,0]
	v_pk_fma_f32 v[112:113], v[8:9], v[108:109], v[112:113] op_sel:[0,1,0] op_sel_hi:[1,1,1] neg_lo:[1,0,0] neg_hi:[1,0,0]
	v_fma_f32 v111, -v11, v110, v111
	v_pk_fma_f32 v[112:113], v[14:15], v[110:111], v[112:113] op_sel_hi:[1,0,1] neg_lo:[1,0,0] neg_hi:[1,0,0]
	v_pk_fma_f32 v[112:113], v[16:17], v[110:111], v[112:113] op_sel:[0,1,0] op_sel_hi:[1,1,1] neg_lo:[1,0,0] neg_hi:[1,0,0]
	v_fma_f32 v113, -v19, v112, v113
	ds_read_b128 v[2:5], v32 offset:16368
	ds_read_b128 v[6:9], v32 offset:16912
	ds_read_b128 v[10:13], v32 offset:16384
	ds_read_b128 v[14:17], v32 offset:16928
	ds_read_b128 v[18:21], v32 offset:16400
	ds_read_b128 v[22:25], v32 offset:16944
	s_waitcnt lgkmcnt(6)
	v_lshlrev_b32_e32 v152, 16, v152
	v_lshlrev_b32_e32 v153, 16, v153
	v_pk_mul_f32 v[114:115], v[152:153], v[154:155]
	v_lshlrev_b32_e32 v156, 16, v156
	v_lshlrev_b32_e32 v157, 16, v157
	v_pk_mul_f32 v[116:117], v[156:157], v[158:159]
	v_pk_fma_f32 v[114:115], v[120:121], v[46:47], v[114:115] op_sel_hi:[1,0,1] neg_lo:[1,0,0] neg_hi:[1,0,0]
	v_pk_fma_f32 v[114:115], v[122:123], v[46:47], v[114:115] op_sel:[0,1,0] op_sel_hi:[1,1,1] neg_lo:[1,0,0] neg_hi:[1,0,0]
	v_pk_fma_f32 v[116:117], v[124:125], v[46:47], v[116:117] op_sel_hi:[1,0,1] neg_lo:[1,0,0] neg_hi:[1,0,0]
	v_pk_fma_f32 v[116:117], v[126:127], v[46:47], v[116:117] op_sel:[0,1,0] op_sel_hi:[1,1,1] neg_lo:[1,0,0] neg_hi:[1,0,0]
	v_pk_fma_f32 v[114:115], v[128:129], v[48:49], v[114:115] op_sel_hi:[1,0,1] neg_lo:[1,0,0] neg_hi:[1,0,0]
	v_pk_fma_f32 v[114:115], v[130:131], v[48:49], v[114:115] op_sel:[0,1,0] op_sel_hi:[1,1,1] neg_lo:[1,0,0] neg_hi:[1,0,0]
	v_pk_fma_f32 v[116:117], v[132:133], v[48:49], v[116:117] op_sel_hi:[1,0,1] neg_lo:[1,0,0] neg_hi:[1,0,0]
	v_pk_fma_f32 v[116:117], v[134:135], v[48:49], v[116:117] op_sel:[0,1,0] op_sel_hi:[1,1,1] neg_lo:[1,0,0] neg_hi:[1,0,0]
	v_pk_fma_f32 v[114:115], v[144:145], v[50:51], v[114:115] op_sel_hi:[1,0,1] neg_lo:[1,0,0] neg_hi:[1,0,0]
	v_pk_fma_f32 v[114:115], v[146:147], v[50:51], v[114:115] op_sel:[0,1,0] op_sel_hi:[1,1,1] neg_lo:[1,0,0] neg_hi:[1,0,0]
	v_pk_fma_f32 v[116:117], v[148:149], v[50:51], v[116:117] op_sel_hi:[1,0,1] neg_lo:[1,0,0] neg_hi:[1,0,0]
	v_pk_fma_f32 v[116:117], v[150:151], v[50:51], v[116:117] op_sel:[0,1,0] op_sel_hi:[1,1,1] neg_lo:[1,0,0] neg_hi:[1,0,0]
	ds_read_b128 v[120:123], v32 offset:16416
	ds_read_b128 v[124:127], v32 offset:16960
	ds_read_b128 v[128:131], v32 offset:16432
	ds_read_b128 v[132:135], v32 offset:16976
	ds_read_b128 v[144:147], v32 offset:16448
	ds_read_b128 v[148:151], v32 offset:16992
	s_waitcnt lgkmcnt(6)
	v_pk_fma_f32 v[114:115], v[2:3], v[52:53], v[114:115] op_sel_hi:[1,0,1] neg_lo:[1,0,0] neg_hi:[1,0,0]
	v_pk_fma_f32 v[114:115], v[4:5], v[52:53], v[114:115] op_sel:[0,1,0] op_sel_hi:[1,1,1] neg_lo:[1,0,0] neg_hi:[1,0,0]
	v_pk_fma_f32 v[116:117], v[6:7], v[52:53], v[116:117] op_sel_hi:[1,0,1] neg_lo:[1,0,0] neg_hi:[1,0,0]
	v_pk_fma_f32 v[116:117], v[8:9], v[52:53], v[116:117] op_sel:[0,1,0] op_sel_hi:[1,1,1] neg_lo:[1,0,0] neg_hi:[1,0,0]
	v_pk_fma_f32 v[114:115], v[10:11], v[54:55], v[114:115] op_sel_hi:[1,0,1] neg_lo:[1,0,0] neg_hi:[1,0,0]
	v_pk_fma_f32 v[114:115], v[12:13], v[54:55], v[114:115] op_sel:[0,1,0] op_sel_hi:[1,1,1] neg_lo:[1,0,0] neg_hi:[1,0,0]
	v_pk_fma_f32 v[116:117], v[14:15], v[54:55], v[116:117] op_sel_hi:[1,0,1] neg_lo:[1,0,0] neg_hi:[1,0,0]
	v_pk_fma_f32 v[116:117], v[16:17], v[54:55], v[116:117] op_sel:[0,1,0] op_sel_hi:[1,1,1] neg_lo:[1,0,0] neg_hi:[1,0,0]
	v_pk_fma_f32 v[114:115], v[18:19], v[56:57], v[114:115] op_sel_hi:[1,0,1] neg_lo:[1,0,0] neg_hi:[1,0,0]
	v_pk_fma_f32 v[114:115], v[20:21], v[56:57], v[114:115] op_sel:[0,1,0] op_sel_hi:[1,1,1] neg_lo:[1,0,0] neg_hi:[1,0,0]
	v_pk_fma_f32 v[116:117], v[22:23], v[56:57], v[116:117] op_sel_hi:[1,0,1] neg_lo:[1,0,0] neg_hi:[1,0,0]
	v_pk_fma_f32 v[116:117], v[24:25], v[56:57], v[116:117] op_sel:[0,1,0] op_sel_hi:[1,1,1] neg_lo:[1,0,0] neg_hi:[1,0,0]
	ds_read_b128 v[2:5], v32 offset:16464
	ds_read_b128 v[6:9], v32 offset:17008
	ds_read_b128 v[10:13], v32 offset:16480
	ds_read_b128 v[14:17], v32 offset:17024
	ds_read_b128 v[18:21], v32 offset:16496
	ds_read_b128 v[22:25], v32 offset:17040
	s_waitcnt lgkmcnt(6)
	v_pk_fma_f32 v[114:115], v[120:121], v[58:59], v[114:115] op_sel_hi:[1,0,1] neg_lo:[1,0,0] neg_hi:[1,0,0]
	v_pk_fma_f32 v[114:115], v[122:123], v[58:59], v[114:115] op_sel:[0,1,0] op_sel_hi:[1,1,1] neg_lo:[1,0,0] neg_hi:[1,0,0]
	v_pk_fma_f32 v[116:117], v[124:125], v[58:59], v[116:117] op_sel_hi:[1,0,1] neg_lo:[1,0,0] neg_hi:[1,0,0]
	v_pk_fma_f32 v[116:117], v[126:127], v[58:59], v[116:117] op_sel:[0,1,0] op_sel_hi:[1,1,1] neg_lo:[1,0,0] neg_hi:[1,0,0]
	v_pk_fma_f32 v[114:115], v[128:129], v[60:61], v[114:115] op_sel_hi:[1,0,1] neg_lo:[1,0,0] neg_hi:[1,0,0]
	v_pk_fma_f32 v[114:115], v[130:131], v[60:61], v[114:115] op_sel:[0,1,0] op_sel_hi:[1,1,1] neg_lo:[1,0,0] neg_hi:[1,0,0]
	v_pk_fma_f32 v[116:117], v[132:133], v[60:61], v[116:117] op_sel_hi:[1,0,1] neg_lo:[1,0,0] neg_hi:[1,0,0]
	v_pk_fma_f32 v[116:117], v[134:135], v[60:61], v[116:117] op_sel:[0,1,0] op_sel_hi:[1,1,1] neg_lo:[1,0,0] neg_hi:[1,0,0]
	v_pk_fma_f32 v[114:115], v[144:145], v[62:63], v[114:115] op_sel_hi:[1,0,1] neg_lo:[1,0,0] neg_hi:[1,0,0]
	v_pk_fma_f32 v[114:115], v[146:147], v[62:63], v[114:115] op_sel:[0,1,0] op_sel_hi:[1,1,1] neg_lo:[1,0,0] neg_hi:[1,0,0]
	v_pk_fma_f32 v[116:117], v[148:149], v[62:63], v[116:117] op_sel_hi:[1,0,1] neg_lo:[1,0,0] neg_hi:[1,0,0]
	v_pk_fma_f32 v[116:117], v[150:151], v[62:63], v[116:117] op_sel:[0,1,0] op_sel_hi:[1,1,1] neg_lo:[1,0,0] neg_hi:[1,0,0]
	ds_read_b128 v[120:123], v32 offset:16512
	ds_read_b128 v[124:127], v32 offset:17056
	ds_read_b128 v[128:131], v32 offset:16528
	ds_read_b128 v[132:135], v32 offset:17072
	ds_read_b128 v[144:147], v32 offset:16544
	ds_read_b128 v[148:151], v32 offset:17088
	s_waitcnt lgkmcnt(6)
	v_pk_fma_f32 v[114:115], v[2:3], v[64:65], v[114:115] op_sel_hi:[1,0,1] neg_lo:[1,0,0] neg_hi:[1,0,0]
	v_pk_fma_f32 v[114:115], v[4:5], v[64:65], v[114:115] op_sel:[0,1,0] op_sel_hi:[1,1,1] neg_lo:[1,0,0] neg_hi:[1,0,0]
	v_pk_fma_f32 v[116:117], v[6:7], v[64:65], v[116:117] op_sel_hi:[1,0,1] neg_lo:[1,0,0] neg_hi:[1,0,0]
	v_pk_fma_f32 v[116:117], v[8:9], v[64:65], v[116:117] op_sel:[0,1,0] op_sel_hi:[1,1,1] neg_lo:[1,0,0] neg_hi:[1,0,0]
	v_pk_fma_f32 v[114:115], v[10:11], v[66:67], v[114:115] op_sel_hi:[1,0,1] neg_lo:[1,0,0] neg_hi:[1,0,0]
	v_pk_fma_f32 v[114:115], v[12:13], v[66:67], v[114:115] op_sel:[0,1,0] op_sel_hi:[1,1,1] neg_lo:[1,0,0] neg_hi:[1,0,0]
	v_pk_fma_f32 v[116:117], v[14:15], v[66:67], v[116:117] op_sel_hi:[1,0,1] neg_lo:[1,0,0] neg_hi:[1,0,0]
	v_pk_fma_f32 v[116:117], v[16:17], v[66:67], v[116:117] op_sel:[0,1,0] op_sel_hi:[1,1,1] neg_lo:[1,0,0] neg_hi:[1,0,0]
	v_pk_fma_f32 v[114:115], v[18:19], v[68:69], v[114:115] op_sel_hi:[1,0,1] neg_lo:[1,0,0] neg_hi:[1,0,0]
	v_pk_fma_f32 v[114:115], v[20:21], v[68:69], v[114:115] op_sel:[0,1,0] op_sel_hi:[1,1,1] neg_lo:[1,0,0] neg_hi:[1,0,0]
	v_pk_fma_f32 v[116:117], v[22:23], v[68:69], v[116:117] op_sel_hi:[1,0,1] neg_lo:[1,0,0] neg_hi:[1,0,0]
	v_pk_fma_f32 v[116:117], v[24:25], v[68:69], v[116:117] op_sel:[0,1,0] op_sel_hi:[1,1,1] neg_lo:[1,0,0] neg_hi:[1,0,0]
	ds_read_b128 v[2:5], v32 offset:16560
	ds_read_b128 v[6:9], v32 offset:17104
	ds_read_b128 v[10:13], v32 offset:16576
	ds_read_b128 v[14:17], v32 offset:17120
	ds_read_b128 v[18:21], v32 offset:16592
	ds_read_b128 v[22:25], v32 offset:17136
	s_waitcnt lgkmcnt(6)
	v_pk_fma_f32 v[114:115], v[120:121], v[70:71], v[114:115] op_sel_hi:[1,0,1] neg_lo:[1,0,0] neg_hi:[1,0,0]
	v_pk_fma_f32 v[114:115], v[122:123], v[70:71], v[114:115] op_sel:[0,1,0] op_sel_hi:[1,1,1] neg_lo:[1,0,0] neg_hi:[1,0,0]
	v_pk_fma_f32 v[116:117], v[124:125], v[70:71], v[116:117] op_sel_hi:[1,0,1] neg_lo:[1,0,0] neg_hi:[1,0,0]
	v_pk_fma_f32 v[116:117], v[126:127], v[70:71], v[116:117] op_sel:[0,1,0] op_sel_hi:[1,1,1] neg_lo:[1,0,0] neg_hi:[1,0,0]
	v_pk_fma_f32 v[114:115], v[128:129], v[72:73], v[114:115] op_sel_hi:[1,0,1] neg_lo:[1,0,0] neg_hi:[1,0,0]
	v_pk_fma_f32 v[114:115], v[130:131], v[72:73], v[114:115] op_sel:[0,1,0] op_sel_hi:[1,1,1] neg_lo:[1,0,0] neg_hi:[1,0,0]
	v_pk_fma_f32 v[116:117], v[132:133], v[72:73], v[116:117] op_sel_hi:[1,0,1] neg_lo:[1,0,0] neg_hi:[1,0,0]
	v_pk_fma_f32 v[116:117], v[134:135], v[72:73], v[116:117] op_sel:[0,1,0] op_sel_hi:[1,1,1] neg_lo:[1,0,0] neg_hi:[1,0,0]
	v_pk_fma_f32 v[114:115], v[144:145], v[74:75], v[114:115] op_sel_hi:[1,0,1] neg_lo:[1,0,0] neg_hi:[1,0,0]
	v_pk_fma_f32 v[114:115], v[146:147], v[74:75], v[114:115] op_sel:[0,1,0] op_sel_hi:[1,1,1] neg_lo:[1,0,0] neg_hi:[1,0,0]
	v_pk_fma_f32 v[116:117], v[148:149], v[74:75], v[116:117] op_sel_hi:[1,0,1] neg_lo:[1,0,0] neg_hi:[1,0,0]
	v_pk_fma_f32 v[116:117], v[150:151], v[74:75], v[116:117] op_sel:[0,1,0] op_sel_hi:[1,1,1] neg_lo:[1,0,0] neg_hi:[1,0,0]
	ds_read_b128 v[120:123], v32 offset:16608
	ds_read_b128 v[124:127], v32 offset:17152
	ds_read_b128 v[128:131], v32 offset:16624
	ds_read_b128 v[132:135], v32 offset:17168
	ds_read_b128 v[144:147], v32 offset:16640
	ds_read_b128 v[148:151], v32 offset:17184
	s_waitcnt lgkmcnt(6)
	v_pk_fma_f32 v[114:115], v[2:3], v[76:77], v[114:115] op_sel_hi:[1,0,1] neg_lo:[1,0,0] neg_hi:[1,0,0]
	v_pk_fma_f32 v[114:115], v[4:5], v[76:77], v[114:115] op_sel:[0,1,0] op_sel_hi:[1,1,1] neg_lo:[1,0,0] neg_hi:[1,0,0]
	v_pk_fma_f32 v[116:117], v[6:7], v[76:77], v[116:117] op_sel_hi:[1,0,1] neg_lo:[1,0,0] neg_hi:[1,0,0]
	v_pk_fma_f32 v[116:117], v[8:9], v[76:77], v[116:117] op_sel:[0,1,0] op_sel_hi:[1,1,1] neg_lo:[1,0,0] neg_hi:[1,0,0]
	v_pk_fma_f32 v[114:115], v[10:11], v[78:79], v[114:115] op_sel_hi:[1,0,1] neg_lo:[1,0,0] neg_hi:[1,0,0]
	v_pk_fma_f32 v[114:115], v[12:13], v[78:79], v[114:115] op_sel:[0,1,0] op_sel_hi:[1,1,1] neg_lo:[1,0,0] neg_hi:[1,0,0]
	v_pk_fma_f32 v[116:117], v[14:15], v[78:79], v[116:117] op_sel_hi:[1,0,1] neg_lo:[1,0,0] neg_hi:[1,0,0]
	v_pk_fma_f32 v[116:117], v[16:17], v[78:79], v[116:117] op_sel:[0,1,0] op_sel_hi:[1,1,1] neg_lo:[1,0,0] neg_hi:[1,0,0]
	v_pk_fma_f32 v[114:115], v[18:19], v[80:81], v[114:115] op_sel_hi:[1,0,1] neg_lo:[1,0,0] neg_hi:[1,0,0]
	v_pk_fma_f32 v[114:115], v[20:21], v[80:81], v[114:115] op_sel:[0,1,0] op_sel_hi:[1,1,1] neg_lo:[1,0,0] neg_hi:[1,0,0]
	v_pk_fma_f32 v[116:117], v[22:23], v[80:81], v[116:117] op_sel_hi:[1,0,1] neg_lo:[1,0,0] neg_hi:[1,0,0]
	v_pk_fma_f32 v[116:117], v[24:25], v[80:81], v[116:117] op_sel:[0,1,0] op_sel_hi:[1,1,1] neg_lo:[1,0,0] neg_hi:[1,0,0]
	ds_read_b128 v[2:5], v32 offset:16656
	ds_read_b128 v[6:9], v32 offset:17200
	ds_read_b128 v[10:13], v32 offset:16672
	ds_read_b128 v[14:17], v32 offset:17216
	ds_read_b128 v[18:21], v32 offset:16688
	ds_read_b128 v[22:25], v32 offset:17232
	s_waitcnt lgkmcnt(6)
	v_pk_fma_f32 v[114:115], v[120:121], v[82:83], v[114:115] op_sel_hi:[1,0,1] neg_lo:[1,0,0] neg_hi:[1,0,0]
	v_pk_fma_f32 v[114:115], v[122:123], v[82:83], v[114:115] op_sel:[0,1,0] op_sel_hi:[1,1,1] neg_lo:[1,0,0] neg_hi:[1,0,0]
	v_pk_fma_f32 v[116:117], v[124:125], v[82:83], v[116:117] op_sel_hi:[1,0,1] neg_lo:[1,0,0] neg_hi:[1,0,0]
	v_pk_fma_f32 v[116:117], v[126:127], v[82:83], v[116:117] op_sel:[0,1,0] op_sel_hi:[1,1,1] neg_lo:[1,0,0] neg_hi:[1,0,0]
	v_pk_fma_f32 v[114:115], v[128:129], v[84:85], v[114:115] op_sel_hi:[1,0,1] neg_lo:[1,0,0] neg_hi:[1,0,0]
	v_pk_fma_f32 v[114:115], v[130:131], v[84:85], v[114:115] op_sel:[0,1,0] op_sel_hi:[1,1,1] neg_lo:[1,0,0] neg_hi:[1,0,0]
	v_pk_fma_f32 v[116:117], v[132:133], v[84:85], v[116:117] op_sel_hi:[1,0,1] neg_lo:[1,0,0] neg_hi:[1,0,0]
	v_pk_fma_f32 v[116:117], v[134:135], v[84:85], v[116:117] op_sel:[0,1,0] op_sel_hi:[1,1,1] neg_lo:[1,0,0] neg_hi:[1,0,0]
	v_pk_fma_f32 v[114:115], v[144:145], v[86:87], v[114:115] op_sel_hi:[1,0,1] neg_lo:[1,0,0] neg_hi:[1,0,0]
	v_pk_fma_f32 v[114:115], v[146:147], v[86:87], v[114:115] op_sel:[0,1,0] op_sel_hi:[1,1,1] neg_lo:[1,0,0] neg_hi:[1,0,0]
	v_pk_fma_f32 v[116:117], v[148:149], v[86:87], v[116:117] op_sel_hi:[1,0,1] neg_lo:[1,0,0] neg_hi:[1,0,0]
	v_pk_fma_f32 v[116:117], v[150:151], v[86:87], v[116:117] op_sel:[0,1,0] op_sel_hi:[1,1,1] neg_lo:[1,0,0] neg_hi:[1,0,0]
	ds_read_b128 v[120:123], v32 offset:16704
	ds_read_b128 v[124:127], v32 offset:17248
	ds_read_b128 v[128:131], v32 offset:16720
	ds_read_b128 v[132:135], v32 offset:17264
	ds_read_b128 v[144:147], v32 offset:16736
	ds_read_b128 v[148:151], v32 offset:17280
	s_waitcnt lgkmcnt(6)
	v_pk_fma_f32 v[114:115], v[2:3], v[88:89], v[114:115] op_sel_hi:[1,0,1] neg_lo:[1,0,0] neg_hi:[1,0,0]
	v_pk_fma_f32 v[114:115], v[4:5], v[88:89], v[114:115] op_sel:[0,1,0] op_sel_hi:[1,1,1] neg_lo:[1,0,0] neg_hi:[1,0,0]
	v_pk_fma_f32 v[116:117], v[6:7], v[88:89], v[116:117] op_sel_hi:[1,0,1] neg_lo:[1,0,0] neg_hi:[1,0,0]
	v_pk_fma_f32 v[116:117], v[8:9], v[88:89], v[116:117] op_sel:[0,1,0] op_sel_hi:[1,1,1] neg_lo:[1,0,0] neg_hi:[1,0,0]
	v_pk_fma_f32 v[114:115], v[10:11], v[90:91], v[114:115] op_sel_hi:[1,0,1] neg_lo:[1,0,0] neg_hi:[1,0,0]
	v_pk_fma_f32 v[114:115], v[12:13], v[90:91], v[114:115] op_sel:[0,1,0] op_sel_hi:[1,1,1] neg_lo:[1,0,0] neg_hi:[1,0,0]
	v_pk_fma_f32 v[116:117], v[14:15], v[90:91], v[116:117] op_sel_hi:[1,0,1] neg_lo:[1,0,0] neg_hi:[1,0,0]
	v_pk_fma_f32 v[116:117], v[16:17], v[90:91], v[116:117] op_sel:[0,1,0] op_sel_hi:[1,1,1] neg_lo:[1,0,0] neg_hi:[1,0,0]
	v_pk_fma_f32 v[114:115], v[18:19], v[92:93], v[114:115] op_sel_hi:[1,0,1] neg_lo:[1,0,0] neg_hi:[1,0,0]
	v_pk_fma_f32 v[114:115], v[20:21], v[92:93], v[114:115] op_sel:[0,1,0] op_sel_hi:[1,1,1] neg_lo:[1,0,0] neg_hi:[1,0,0]
	v_pk_fma_f32 v[116:117], v[22:23], v[92:93], v[116:117] op_sel_hi:[1,0,1] neg_lo:[1,0,0] neg_hi:[1,0,0]
	v_pk_fma_f32 v[116:117], v[24:25], v[92:93], v[116:117] op_sel:[0,1,0] op_sel_hi:[1,1,1] neg_lo:[1,0,0] neg_hi:[1,0,0]
	ds_read_b128 v[2:5], v32 offset:16752
	ds_read_b128 v[6:9], v32 offset:17296
	ds_read_b128 v[10:13], v32 offset:16768
	ds_read_b128 v[14:17], v32 offset:17312
	ds_read_b128 v[18:21], v32 offset:16784
	ds_read_b128 v[22:25], v32 offset:17328
	s_waitcnt lgkmcnt(6)
	v_pk_fma_f32 v[114:115], v[120:121], v[94:95], v[114:115] op_sel_hi:[1,0,1] neg_lo:[1,0,0] neg_hi:[1,0,0]
	v_pk_fma_f32 v[114:115], v[122:123], v[94:95], v[114:115] op_sel:[0,1,0] op_sel_hi:[1,1,1] neg_lo:[1,0,0] neg_hi:[1,0,0]
	v_pk_fma_f32 v[116:117], v[124:125], v[94:95], v[116:117] op_sel_hi:[1,0,1] neg_lo:[1,0,0] neg_hi:[1,0,0]
	v_pk_fma_f32 v[116:117], v[126:127], v[94:95], v[116:117] op_sel:[0,1,0] op_sel_hi:[1,1,1] neg_lo:[1,0,0] neg_hi:[1,0,0]
	v_pk_fma_f32 v[114:115], v[128:129], v[96:97], v[114:115] op_sel_hi:[1,0,1] neg_lo:[1,0,0] neg_hi:[1,0,0]
	v_pk_fma_f32 v[114:115], v[130:131], v[96:97], v[114:115] op_sel:[0,1,0] op_sel_hi:[1,1,1] neg_lo:[1,0,0] neg_hi:[1,0,0]
	v_pk_fma_f32 v[116:117], v[132:133], v[96:97], v[116:117] op_sel_hi:[1,0,1] neg_lo:[1,0,0] neg_hi:[1,0,0]
	v_pk_fma_f32 v[116:117], v[134:135], v[96:97], v[116:117] op_sel:[0,1,0] op_sel_hi:[1,1,1] neg_lo:[1,0,0] neg_hi:[1,0,0]
	v_pk_fma_f32 v[114:115], v[144:145], v[106:107], v[114:115] op_sel_hi:[1,0,1] neg_lo:[1,0,0] neg_hi:[1,0,0]
	v_pk_fma_f32 v[114:115], v[146:147], v[106:107], v[114:115] op_sel:[0,1,0] op_sel_hi:[1,1,1] neg_lo:[1,0,0] neg_hi:[1,0,0]
	v_pk_fma_f32 v[116:117], v[148:149], v[106:107], v[116:117] op_sel_hi:[1,0,1] neg_lo:[1,0,0] neg_hi:[1,0,0]
	v_pk_fma_f32 v[116:117], v[150:151], v[106:107], v[116:117] op_sel:[0,1,0] op_sel_hi:[1,1,1] neg_lo:[1,0,0] neg_hi:[1,0,0]
	ds_read_b128 v[120:123], v32 offset:16800
	ds_read_b128 v[124:127], v32 offset:17344
	ds_read_b128 v[128:131], v32 offset:17360
	s_waitcnt lgkmcnt(3)
	v_pk_fma_f32 v[114:115], v[2:3], v[108:109], v[114:115] op_sel_hi:[1,0,1] neg_lo:[1,0,0] neg_hi:[1,0,0]
	v_pk_fma_f32 v[114:115], v[4:5], v[108:109], v[114:115] op_sel:[0,1,0] op_sel_hi:[1,1,1] neg_lo:[1,0,0] neg_hi:[1,0,0]
	v_pk_fma_f32 v[116:117], v[6:7], v[108:109], v[116:117] op_sel_hi:[1,0,1] neg_lo:[1,0,0] neg_hi:[1,0,0]
	v_pk_fma_f32 v[116:117], v[8:9], v[108:109], v[116:117] op_sel:[0,1,0] op_sel_hi:[1,1,1] neg_lo:[1,0,0] neg_hi:[1,0,0]
	v_pk_fma_f32 v[114:115], v[10:11], v[110:111], v[114:115] op_sel_hi:[1,0,1] neg_lo:[1,0,0] neg_hi:[1,0,0]
	v_pk_fma_f32 v[114:115], v[12:13], v[110:111], v[114:115] op_sel:[0,1,0] op_sel_hi:[1,1,1] neg_lo:[1,0,0] neg_hi:[1,0,0]
	v_pk_fma_f32 v[116:117], v[14:15], v[110:111], v[116:117] op_sel_hi:[1,0,1] neg_lo:[1,0,0] neg_hi:[1,0,0]
	v_pk_fma_f32 v[116:117], v[16:17], v[110:111], v[116:117] op_sel:[0,1,0] op_sel_hi:[1,1,1] neg_lo:[1,0,0] neg_hi:[1,0,0]
	v_pk_fma_f32 v[114:115], v[18:19], v[112:113], v[114:115] op_sel_hi:[1,0,1] neg_lo:[1,0,0] neg_hi:[1,0,0]
	v_pk_fma_f32 v[114:115], v[20:21], v[112:113], v[114:115] op_sel:[0,1,0] op_sel_hi:[1,1,1] neg_lo:[1,0,0] neg_hi:[1,0,0]
	v_pk_fma_f32 v[116:117], v[22:23], v[112:113], v[116:117] op_sel_hi:[1,0,1] neg_lo:[1,0,0] neg_hi:[1,0,0]
	v_pk_fma_f32 v[116:117], v[24:25], v[112:113], v[116:117] op_sel:[0,1,0] op_sel_hi:[1,1,1] neg_lo:[1,0,0] neg_hi:[1,0,0]
	s_waitcnt lgkmcnt(0)
	v_fma_f32 v115, -v121, v114, v115
	v_pk_fma_f32 v[116:117], v[124:125], v[114:115], v[116:117] op_sel_hi:[1,0,1] neg_lo:[1,0,0] neg_hi:[1,0,0]
	v_pk_fma_f32 v[116:117], v[126:127], v[114:115], v[116:117] op_sel:[0,1,0] op_sel_hi:[1,1,1] neg_lo:[1,0,0] neg_hi:[1,0,0]
	v_fma_f32 v117, -v129, v116, v117
	s_and_saveexec_b64 s[56:57], s[4:5]
	ds_add_u32 v169, v170 offset:36352
	s_or_b64 exec, exec, s[56:57]
	ds_read_b32 v2, v169 offset:36352
	s_add_i32 s7, s3, 16
	s_waitcnt lgkmcnt(0)
	v_cmp_gt_u32_e32 vcc, s7, v2
	s_and_saveexec_b64 s[56:57], vcc
	s_cbranch_execz .LBB0_519
	s_mov_b64 s[58:59], 0
